# nt hint on more last-use streams: phase-6 gate loads, phase-8 xpre loads, phase-11 x1 loads, f32 weight loads of the transposes
# speedup vs baseline: 1.0391x; 1.0084x over previous
.LBB0_56:
	s_lshl_b32 s4, s7, 6
	s_ashr_i32 s7, s6, 31
	v_or_b32_e32 v17, s4, v6
	s_waitcnt vmcnt(0)
	v_lshl_add_u64 v[18:19], s[6:7], 2, v[2:3]
	v_mad_i64_i32 v[20:21], s[6:7], v17, s12, v[18:19]
	v_or_b32_e32 v22, 2, v17
	v_or_b32_e32 v24, 4, v17
	v_or_b32_e32 v26, 6, v17
	v_or_b32_e32 v28, 8, v17
	v_or_b32_e32 v30, 10, v17
	v_or_b32_e32 v32, 12, v17
	v_or_b32_e32 v34, 14, v17
	v_mad_i64_i32 v[22:23], s[6:7], v22, s12, v[18:19]
	v_mad_i64_i32 v[24:25], s[6:7], v24, s12, v[18:19]
	v_mad_i64_i32 v[26:27], s[6:7], v26, s12, v[18:19]
	v_mad_i64_i32 v[28:29], s[6:7], v28, s12, v[18:19]
	v_mad_i64_i32 v[30:31], s[6:7], v30, s12, v[18:19]
	v_mad_i64_i32 v[32:33], s[6:7], v32, s12, v[18:19]
	v_mad_i64_i32 v[34:35], s[6:7], v34, s12, v[18:19]
	global_load_dword v36, v[20:21], off nt
	global_load_dword v37, v[22:23], off nt
	global_load_dword v38, v[24:25], off nt
	global_load_dword v39, v[26:27], off nt
	global_load_dword v40, v[28:29], off nt
	global_load_dword v41, v[30:31], off nt
	global_load_dword v42, v[32:33], off nt
	global_load_dword v43, v[34:35], off nt
	v_or_b32_e32 v20, 16, v17
	v_mad_i64_i32 v[20:21], s[6:7], v20, s12, v[18:19]
	v_or_b32_e32 v22, 18, v17
	v_or_b32_e32 v24, 20, v17
	v_or_b32_e32 v26, 22, v17
	v_or_b32_e32 v28, 24, v17
	v_or_b32_e32 v30, 26, v17
	v_or_b32_e32 v32, 28, v17
	v_or_b32_e32 v34, 30, v17
	v_mad_i64_i32 v[22:23], s[6:7], v22, s12, v[18:19]
	v_mad_i64_i32 v[24:25], s[6:7], v24, s12, v[18:19]
	v_mad_i64_i32 v[26:27], s[6:7], v26, s12, v[18:19]
	v_mad_i64_i32 v[28:29], s[6:7], v28, s12, v[18:19]
	v_mad_i64_i32 v[30:31], s[6:7], v30, s12, v[18:19]
	v_mad_i64_i32 v[32:33], s[6:7], v32, s12, v[18:19]
	v_mad_i64_i32 v[34:35], s[6:7], v34, s12, v[18:19]
	global_load_dword v44, v[20:21], off nt
	global_load_dword v45, v[22:23], off nt
	global_load_dword v46, v[24:25], off nt
	global_load_dword v47, v[26:27], off nt
	global_load_dword v48, v[28:29], off nt
	global_load_dword v49, v[30:31], off nt
	global_load_dword v50, v[32:33], off nt
	global_load_dword v51, v[34:35], off nt
	v_or_b32_e32 v20, 32, v17
	v_mad_i64_i32 v[20:21], s[6:7], v20, s12, v[18:19]
	v_or_b32_e32 v22, 34, v17
	v_or_b32_e32 v24, 36, v17
	v_or_b32_e32 v26, 38, v17
	v_or_b32_e32 v28, 40, v17
	v_or_b32_e32 v30, 42, v17
	v_or_b32_e32 v32, 44, v17
	v_or_b32_e32 v34, 46, v17
	v_mad_i64_i32 v[22:23], s[6:7], v22, s12, v[18:19]
	v_mad_i64_i32 v[24:25], s[6:7], v24, s12, v[18:19]
	v_mad_i64_i32 v[26:27], s[6:7], v26, s12, v[18:19]
	v_mad_i64_i32 v[28:29], s[6:7], v28, s12, v[18:19]
	v_mad_i64_i32 v[30:31], s[6:7], v30, s12, v[18:19]
	v_mad_i64_i32 v[32:33], s[6:7], v32, s12, v[18:19]
	v_mad_i64_i32 v[34:35], s[6:7], v34, s12, v[18:19]
	global_load_dword v52, v[20:21], off nt
	global_load_dword v53, v[22:23], off nt
	global_load_dword v54, v[24:25], off nt
	global_load_dword v55, v[26:27], off nt
	global_load_dword v56, v[28:29], off nt
	global_load_dword v57, v[30:31], off nt
	global_load_dword v58, v[32:33], off nt
	global_load_dword v59, v[34:35], off nt
	v_or_b32_e32 v20, 48, v17
	v_mad_i64_i32 v[20:21], s[6:7], v20, s12, v[18:19]
	v_or_b32_e32 v22, 50, v17
	v_or_b32_e32 v24, 52, v17
	v_or_b32_e32 v26, 54, v17
	v_or_b32_e32 v28, 56, v17
	v_or_b32_e32 v30, 58, v17
	v_or_b32_e32 v32, 60, v17
	v_or_b32_e32 v17, 62, v17
	v_mad_i64_i32 v[22:23], s[6:7], v22, s12, v[18:19]
	v_mad_i64_i32 v[24:25], s[6:7], v24, s12, v[18:19]
	v_mad_i64_i32 v[26:27], s[6:7], v26, s12, v[18:19]
	v_mad_i64_i32 v[28:29], s[6:7], v28, s12, v[18:19]
	v_mad_i64_i32 v[30:31], s[6:7], v30, s12, v[18:19]
	v_mad_i64_i32 v[32:33], s[6:7], v32, s12, v[18:19]
	v_mad_i64_i32 v[18:19], s[6:7], v17, s12, v[18:19]
	global_load_dword v17, v[20:21], off nt
	global_load_dword v34, v[22:23], off nt
	global_load_dword v35, v[24:25], off nt
	global_load_dword v60, v[26:27], off nt
	global_load_dword v61, v[28:29], off nt
	global_load_dword v62, v[30:31], off nt
	global_load_dword v63, v[32:33], off nt
	global_load_dword v64, v[18:19], off nt
	s_waitcnt vmcnt(30)
	ds_write2_b32 v7, v36, v37 offset1:66
	s_waitcnt vmcnt(28)
	ds_write2_b32 v7, v38, v39 offset0:132 offset1:198
	s_waitcnt vmcnt(26)
	ds_write2_b32 v10, v40, v41 offset0:8 offset1:74
	s_waitcnt vmcnt(24)
	ds_write2_b32 v10, v42, v43 offset0:140 offset1:206
	s_waitcnt vmcnt(22)
	ds_write2_b32 v11, v44, v45 offset0:16 offset1:82
	s_waitcnt vmcnt(20)
	ds_write2_b32 v11, v46, v47 offset0:148 offset1:214
	s_waitcnt vmcnt(18)
	ds_write2_b32 v12, v48, v49 offset0:24 offset1:90
	s_waitcnt vmcnt(16)
	ds_write2_b32 v12, v50, v51 offset0:156 offset1:222
	s_waitcnt vmcnt(14)
	ds_write2_b32 v13, v52, v53 offset0:32 offset1:98
	s_waitcnt vmcnt(12)
	ds_write2_b32 v13, v54, v55 offset0:164 offset1:230
	s_waitcnt vmcnt(10)
	ds_write2_b32 v14, v56, v57 offset0:40 offset1:106
	s_waitcnt vmcnt(8)
	ds_write2_b32 v14, v58, v59 offset0:172 offset1:238
	s_waitcnt vmcnt(6)
	ds_write2_b32 v15, v17, v34 offset0:48 offset1:114
	s_waitcnt vmcnt(4)
	ds_write2_b32 v15, v35, v60 offset0:180 offset1:246
	s_waitcnt vmcnt(2)
	ds_write2_b32 v16, v61, v62 offset0:56 offset1:122
	s_waitcnt vmcnt(0)
	ds_write2_b32 v16, v63, v64 offset0:188 offset1:254
	s_waitcnt lgkmcnt(0)
	ds_read2_b32 v[22:23], v9 offset0:33 offset1:41
	ds_read2_b32 v[24:25], v9 offset1:8
	ds_read2_b32 v[26:27], v9 offset0:66 offset1:74
	ds_read2_b32 v[28:29], v9 offset0:99 offset1:107
	ds_read2_b32 v[30:31], v9 offset0:132 offset1:140
	ds_read2_b32 v[32:33], v9 offset0:165 offset1:173
	ds_read2_b32 v[34:35], v9 offset0:198 offset1:206
	ds_read2_b32 v[36:37], v9 offset0:231 offset1:239
	s_add_i32 s13, s13, s10
	v_add_u32_e32 v40, s13, v8
	s_ashr_i32 s5, s4, 31
	v_ashrrev_i32_e32 v41, 31, v40
	v_lshl_add_u64 v[38:39], s[4:5], 1, v[4:5]
	v_lshlrev_b64 v[42:43], 11, v[40:41]
	s_waitcnt lgkmcnt(6)
	v_cvt_pk_bf16_f32 v18, v24, v22
	s_waitcnt lgkmcnt(4)
	v_cvt_pk_bf16_f32 v19, v26, v28
	s_waitcnt lgkmcnt(2)
	v_cvt_pk_bf16_f32 v20, v30, v32
	s_waitcnt lgkmcnt(0)
	v_cvt_pk_bf16_f32 v21, v34, v36
	v_lshl_add_u64 v[42:43], v[38:39], 0, v[42:43]
	v_add_u32_e32 v22, 8, v40
	global_store_dwordx4 v[42:43], v[18:21], off
	s_add_i32 s8, s8, s9
	s_add_i32 s10, s10, s11
	v_cvt_pk_bf16_f32 v18, v25, v23
	v_ashrrev_i32_e32 v23, 31, v22
	v_cvt_pk_bf16_f32 v19, v27, v29
	v_cvt_pk_bf16_f32 v20, v31, v33
	v_cvt_pk_bf16_f32 v21, v35, v37
	v_lshlrev_b64 v[22:23], 11, v[22:23]
	ds_read2_b32 v[24:25], v9 offset0:49 offset1:57
	ds_read2_b32 v[26:27], v9 offset0:16 offset1:24
	ds_read2_b32 v[28:29], v9 offset0:82 offset1:90
	ds_read2_b32 v[30:31], v9 offset0:115 offset1:123
	ds_read2_b32 v[32:33], v9 offset0:148 offset1:156
	ds_read2_b32 v[34:35], v9 offset0:181 offset1:189
	ds_read2_b32 v[36:37], v9 offset0:214 offset1:222
	ds_read2_b32 v[42:43], v9 offset0:247 offset1:255
	v_lshl_add_u64 v[22:23], v[38:39], 0, v[22:23]
	global_store_dwordx4 v[22:23], v[18:21], off
	v_add_u32_e32 v22, 16, v40
	v_ashrrev_i32_e32 v23, 31, v22
	v_lshlrev_b64 v[22:23], 11, v[22:23]
	s_waitcnt lgkmcnt(6)
	v_cvt_pk_bf16_f32 v18, v26, v24
	s_waitcnt lgkmcnt(4)
	v_cvt_pk_bf16_f32 v19, v28, v30
	s_waitcnt lgkmcnt(2)
	v_cvt_pk_bf16_f32 v20, v32, v34
	s_waitcnt lgkmcnt(0)
	v_cvt_pk_bf16_f32 v21, v36, v42
	v_lshl_add_u64 v[22:23], v[38:39], 0, v[22:23]
	global_store_dwordx4 v[22:23], v[18:21], off
	v_add_u32_e32 v22, 24, v40
	v_ashrrev_i32_e32 v23, 31, v22
	v_lshlrev_b64 v[22:23], 11, v[22:23]
	v_cvt_pk_bf16_f32 v18, v27, v25
	v_cvt_pk_bf16_f32 v19, v29, v31
	v_cvt_pk_bf16_f32 v20, v33, v35
	v_cvt_pk_bf16_f32 v21, v37, v43
	v_lshl_add_u64 v[22:23], v[38:39], 0, v[22:23]
	global_store_dwordx4 v[22:23], v[18:21], off
	s_waitcnt lgkmcnt(0)
	s_cmpk_lt_i32 s8, 0xd00
	s_cbranch_scc0 .LBB0_62

.LBB0_68:
	s_lshl_b32 s4, s7, 6
	s_ashr_i32 s7, s6, 31
	v_or_b32_e32 v17, s4, v6
	s_waitcnt vmcnt(0)
	v_lshl_add_u64 v[18:19], s[6:7], 2, v[2:3]
	v_mad_i64_i32 v[20:21], s[6:7], v17, s12, v[18:19]
	v_or_b32_e32 v22, 2, v17
	v_or_b32_e32 v24, 4, v17
	v_or_b32_e32 v26, 6, v17
	v_or_b32_e32 v28, 8, v17
	v_or_b32_e32 v30, 10, v17
	v_or_b32_e32 v32, 12, v17
	v_or_b32_e32 v34, 14, v17
	v_mad_i64_i32 v[22:23], s[6:7], v22, s12, v[18:19]
	v_mad_i64_i32 v[24:25], s[6:7], v24, s12, v[18:19]
	v_mad_i64_i32 v[26:27], s[6:7], v26, s12, v[18:19]
	v_mad_i64_i32 v[28:29], s[6:7], v28, s12, v[18:19]
	v_mad_i64_i32 v[30:31], s[6:7], v30, s12, v[18:19]
	v_mad_i64_i32 v[32:33], s[6:7], v32, s12, v[18:19]
	v_mad_i64_i32 v[34:35], s[6:7], v34, s12, v[18:19]
	global_load_dword v36, v[20:21], off nt
	global_load_dword v37, v[22:23], off nt
	global_load_dword v38, v[24:25], off nt
	global_load_dword v39, v[26:27], off nt
	global_load_dword v40, v[28:29], off nt
	global_load_dword v41, v[30:31], off nt
	global_load_dword v42, v[32:33], off nt
	global_load_dword v43, v[34:35], off nt
	v_or_b32_e32 v20, 16, v17
	v_mad_i64_i32 v[20:21], s[6:7], v20, s12, v[18:19]
	v_or_b32_e32 v22, 18, v17
	v_or_b32_e32 v24, 20, v17
	v_or_b32_e32 v26, 22, v17
	v_or_b32_e32 v28, 24, v17
	v_or_b32_e32 v30, 26, v17
	v_or_b32_e32 v32, 28, v17
	v_or_b32_e32 v34, 30, v17
	v_mad_i64_i32 v[22:23], s[6:7], v22, s12, v[18:19]
	v_mad_i64_i32 v[24:25], s[6:7], v24, s12, v[18:19]
	v_mad_i64_i32 v[26:27], s[6:7], v26, s12, v[18:19]
	v_mad_i64_i32 v[28:29], s[6:7], v28, s12, v[18:19]
	v_mad_i64_i32 v[30:31], s[6:7], v30, s12, v[18:19]
	v_mad_i64_i32 v[32:33], s[6:7], v32, s12, v[18:19]
	v_mad_i64_i32 v[34:35], s[6:7], v34, s12, v[18:19]
	global_load_dword v44, v[20:21], off nt
	global_load_dword v45, v[22:23], off nt
	global_load_dword v46, v[24:25], off nt
	global_load_dword v47, v[26:27], off nt
	global_load_dword v48, v[28:29], off nt
	global_load_dword v49, v[30:31], off nt
	global_load_dword v50, v[32:33], off nt
	global_load_dword v51, v[34:35], off nt
	v_or_b32_e32 v20, 32, v17
	v_mad_i64_i32 v[20:21], s[6:7], v20, s12, v[18:19]
	v_or_b32_e32 v22, 34, v17
	v_or_b32_e32 v24, 36, v17
	v_or_b32_e32 v26, 38, v17
	v_or_b32_e32 v28, 40, v17
	v_or_b32_e32 v30, 42, v17
	v_or_b32_e32 v32, 44, v17
	v_or_b32_e32 v34, 46, v17
	v_mad_i64_i32 v[22:23], s[6:7], v22, s12, v[18:19]
	v_mad_i64_i32 v[24:25], s[6:7], v24, s12, v[18:19]
	v_mad_i64_i32 v[26:27], s[6:7], v26, s12, v[18:19]
	v_mad_i64_i32 v[28:29], s[6:7], v28, s12, v[18:19]
	v_mad_i64_i32 v[30:31], s[6:7], v30, s12, v[18:19]
	v_mad_i64_i32 v[32:33], s[6:7], v32, s12, v[18:19]
	v_mad_i64_i32 v[34:35], s[6:7], v34, s12, v[18:19]
	global_load_dword v52, v[20:21], off nt
	global_load_dword v53, v[22:23], off nt
	global_load_dword v54, v[24:25], off nt
	global_load_dword v55, v[26:27], off nt
	global_load_dword v56, v[28:29], off nt
	global_load_dword v57, v[30:31], off nt
	global_load_dword v58, v[32:33], off nt
	global_load_dword v59, v[34:35], off nt
	v_or_b32_e32 v20, 48, v17
	v_mad_i64_i32 v[20:21], s[6:7], v20, s12, v[18:19]
	v_or_b32_e32 v22, 50, v17
	v_or_b32_e32 v24, 52, v17
	v_or_b32_e32 v26, 54, v17
	v_or_b32_e32 v28, 56, v17
	v_or_b32_e32 v30, 58, v17
	v_or_b32_e32 v32, 60, v17
	v_or_b32_e32 v17, 62, v17
	v_mad_i64_i32 v[22:23], s[6:7], v22, s12, v[18:19]
	v_mad_i64_i32 v[24:25], s[6:7], v24, s12, v[18:19]
	v_mad_i64_i32 v[26:27], s[6:7], v26, s12, v[18:19]
	v_mad_i64_i32 v[28:29], s[6:7], v28, s12, v[18:19]
	v_mad_i64_i32 v[30:31], s[6:7], v30, s12, v[18:19]
	v_mad_i64_i32 v[32:33], s[6:7], v32, s12, v[18:19]
	v_mad_i64_i32 v[18:19], s[6:7], v17, s12, v[18:19]
	global_load_dword v17, v[20:21], off nt
	global_load_dword v34, v[22:23], off nt
	global_load_dword v35, v[24:25], off nt
	global_load_dword v60, v[26:27], off nt
	global_load_dword v61, v[28:29], off nt
	global_load_dword v62, v[30:31], off nt
	global_load_dword v63, v[32:33], off nt
	global_load_dword v64, v[18:19], off nt
	s_waitcnt vmcnt(30)
	ds_write2_b32 v7, v36, v37 offset1:66
	s_waitcnt vmcnt(28)
	ds_write2_b32 v7, v38, v39 offset0:132 offset1:198
	s_waitcnt vmcnt(26)
	ds_write2_b32 v10, v40, v41 offset0:8 offset1:74
	s_waitcnt vmcnt(24)
	ds_write2_b32 v10, v42, v43 offset0:140 offset1:206
	s_waitcnt vmcnt(22)
	ds_write2_b32 v11, v44, v45 offset0:16 offset1:82
	s_waitcnt vmcnt(20)
	ds_write2_b32 v11, v46, v47 offset0:148 offset1:214
	s_waitcnt vmcnt(18)
	ds_write2_b32 v12, v48, v49 offset0:24 offset1:90
	s_waitcnt vmcnt(16)
	ds_write2_b32 v12, v50, v51 offset0:156 offset1:222
	s_waitcnt vmcnt(14)
	ds_write2_b32 v13, v52, v53 offset0:32 offset1:98
	s_waitcnt vmcnt(12)
	ds_write2_b32 v13, v54, v55 offset0:164 offset1:230
	s_waitcnt vmcnt(10)
	ds_write2_b32 v14, v56, v57 offset0:40 offset1:106
	s_waitcnt vmcnt(8)
	ds_write2_b32 v14, v58, v59 offset0:172 offset1:238
	s_waitcnt vmcnt(6)
	ds_write2_b32 v15, v17, v34 offset0:48 offset1:114
	s_waitcnt vmcnt(4)
	ds_write2_b32 v15, v35, v60 offset0:180 offset1:246
	s_waitcnt vmcnt(2)
	ds_write2_b32 v16, v61, v62 offset0:56 offset1:122
	s_waitcnt vmcnt(0)
	ds_write2_b32 v16, v63, v64 offset0:188 offset1:254
	s_waitcnt lgkmcnt(0)
	ds_read2_b32 v[22:23], v9 offset0:33 offset1:41
	ds_read2_b32 v[24:25], v9 offset1:8
	ds_read2_b32 v[26:27], v9 offset0:66 offset1:74
	ds_read2_b32 v[28:29], v9 offset0:99 offset1:107
	ds_read2_b32 v[30:31], v9 offset0:132 offset1:140
	ds_read2_b32 v[32:33], v9 offset0:165 offset1:173
	ds_read2_b32 v[34:35], v9 offset0:198 offset1:206
	ds_read2_b32 v[36:37], v9 offset0:231 offset1:239
	s_add_i32 s13, s13, s10
	v_add_u32_e32 v40, s13, v8
	s_ashr_i32 s5, s4, 31
	v_ashrrev_i32_e32 v41, 31, v40
	v_lshl_add_u64 v[38:39], s[4:5], 1, v[4:5]
	v_lshlrev_b64 v[42:43], 11, v[40:41]
	s_waitcnt lgkmcnt(6)
	v_cvt_pk_bf16_f32 v18, v24, v22
	s_waitcnt lgkmcnt(4)
	v_cvt_pk_bf16_f32 v19, v26, v28
	s_waitcnt lgkmcnt(2)
	v_cvt_pk_bf16_f32 v20, v30, v32
	s_waitcnt lgkmcnt(0)
	v_cvt_pk_bf16_f32 v21, v34, v36
	v_lshl_add_u64 v[42:43], v[38:39], 0, v[42:43]
	v_add_u32_e32 v22, 8, v40
	global_store_dwordx4 v[42:43], v[18:21], off
	s_add_i32 s8, s8, s9
	s_add_i32 s10, s10, s11
	v_cvt_pk_bf16_f32 v18, v25, v23
	v_ashrrev_i32_e32 v23, 31, v22
	v_cvt_pk_bf16_f32 v19, v27, v29
	v_cvt_pk_bf16_f32 v20, v31, v33
	v_cvt_pk_bf16_f32 v21, v35, v37
	v_lshlrev_b64 v[22:23], 11, v[22:23]
	ds_read2_b32 v[24:25], v9 offset0:49 offset1:57
	ds_read2_b32 v[26:27], v9 offset0:16 offset1:24
	ds_read2_b32 v[28:29], v9 offset0:82 offset1:90
	ds_read2_b32 v[30:31], v9 offset0:115 offset1:123
	ds_read2_b32 v[32:33], v9 offset0:148 offset1:156
	ds_read2_b32 v[34:35], v9 offset0:181 offset1:189
	ds_read2_b32 v[36:37], v9 offset0:214 offset1:222
	ds_read2_b32 v[42:43], v9 offset0:247 offset1:255
	v_lshl_add_u64 v[22:23], v[38:39], 0, v[22:23]
	global_store_dwordx4 v[22:23], v[18:21], off
	v_add_u32_e32 v22, 16, v40
	v_ashrrev_i32_e32 v23, 31, v22
	v_lshlrev_b64 v[22:23], 11, v[22:23]
	s_waitcnt lgkmcnt(6)
	v_cvt_pk_bf16_f32 v18, v26, v24
	s_waitcnt lgkmcnt(4)
	v_cvt_pk_bf16_f32 v19, v28, v30
	s_waitcnt lgkmcnt(2)
	v_cvt_pk_bf16_f32 v20, v32, v34
	s_waitcnt lgkmcnt(0)
	v_cvt_pk_bf16_f32 v21, v36, v42
	v_lshl_add_u64 v[22:23], v[38:39], 0, v[22:23]
	global_store_dwordx4 v[22:23], v[18:21], off
	v_add_u32_e32 v22, 24, v40
	v_ashrrev_i32_e32 v23, 31, v22
	v_lshlrev_b64 v[22:23], 11, v[22:23]
	v_cvt_pk_bf16_f32 v18, v27, v25
	v_cvt_pk_bf16_f32 v19, v29, v31
	v_cvt_pk_bf16_f32 v20, v33, v35
	v_cvt_pk_bf16_f32 v21, v37, v43
	v_lshl_add_u64 v[22:23], v[38:39], 0, v[22:23]
	global_store_dwordx4 v[22:23], v[18:21], off
	s_waitcnt lgkmcnt(0)
	s_cmpk_gt_i32 s8, 0xcff
	s_cbranch_scc1 .LBB0_74

.LBB0_288:
	s_ashr_i32 s4, s16, 31
	s_lshr_b32 s4, s4, 27
	s_add_i32 s4, s16, s4
	s_ashr_i32 s5, s4, 5
	s_lshl_b32 s4, s5, 6
	s_lshl_b32 s5, s5, 10
	v_or_b32_e32 v20, s4, v8
	s_sub_i32 s6, s15, s5
	v_or_b32_e32 v30, 10, v20
	v_or_b32_e32 v32, 12, v20
	v_or_b32_e32 v34, 14, v20
	v_or_b32_e32 v44, 24, v20
	v_or_b32_e32 v46, 26, v20
	v_or_b32_e32 v48, 28, v20
	v_or_b32_e32 v50, 30, v20
	s_ashr_i32 s7, s6, 31
	v_ashrrev_i32_e32 v21, 31, v20
	v_or_b32_e32 v22, 2, v20
	v_or_b32_e32 v24, 4, v20
	v_or_b32_e32 v26, 6, v20
	v_or_b32_e32 v28, 8, v20
	v_or_b32_e32 v36, 16, v20
	v_or_b32_e32 v38, 18, v20
	v_or_b32_e32 v40, 20, v20
	v_or_b32_e32 v42, 22, v20
	v_or_b32_e32 v52, 32, v20
	v_or_b32_e32 v54, 34, v20
	v_or_b32_e32 v56, 36, v20
	v_or_b32_e32 v58, 38, v20
	v_or_b32_e32 v60, 40, v20
	v_or_b32_e32 v62, 42, v20
	v_or_b32_e32 v64, 44, v20
	v_or_b32_e32 v66, 46, v20
	v_or_b32_e32 v68, 48, v20
	v_or_b32_e32 v70, 50, v20
	v_or_b32_e32 v72, 52, v20
	v_or_b32_e32 v74, 54, v20
	v_or_b32_e32 v76, 56, v20
	v_or_b32_e32 v78, 58, v20
	v_or_b32_e32 v80, 60, v20
	v_or_b32_e32 v82, 62, v20
	v_ashrrev_i32_e32 v31, 31, v30
	v_ashrrev_i32_e32 v33, 31, v32
	v_ashrrev_i32_e32 v35, 31, v34
	v_ashrrev_i32_e32 v45, 31, v44
	v_ashrrev_i32_e32 v47, 31, v46
	v_ashrrev_i32_e32 v49, 31, v48
	v_ashrrev_i32_e32 v51, 31, v50
	v_lshl_add_u64 v[84:85], s[6:7], 2, v[4:5]
	v_lshlrev_b64 v[20:21], 12, v[20:21]
	v_ashrrev_i32_e32 v23, 31, v22
	v_ashrrev_i32_e32 v25, 31, v24
	v_ashrrev_i32_e32 v27, 31, v26
	v_ashrrev_i32_e32 v29, 31, v28
	v_ashrrev_i32_e32 v37, 31, v36
	v_ashrrev_i32_e32 v39, 31, v38
	v_ashrrev_i32_e32 v41, 31, v40
	v_ashrrev_i32_e32 v43, 31, v42
	v_ashrrev_i32_e32 v53, 31, v52
	v_ashrrev_i32_e32 v55, 31, v54
	v_ashrrev_i32_e32 v57, 31, v56
	v_ashrrev_i32_e32 v59, 31, v58
	v_ashrrev_i32_e32 v61, 31, v60
	v_ashrrev_i32_e32 v63, 31, v62
	v_ashrrev_i32_e32 v65, 31, v64
	v_ashrrev_i32_e32 v67, 31, v66
	v_ashrrev_i32_e32 v69, 31, v68
	v_ashrrev_i32_e32 v71, 31, v70
	v_ashrrev_i32_e32 v73, 31, v72
	v_ashrrev_i32_e32 v75, 31, v74
	v_ashrrev_i32_e32 v77, 31, v76
	v_ashrrev_i32_e32 v79, 31, v78
	v_ashrrev_i32_e32 v81, 31, v80
	v_ashrrev_i32_e32 v83, 31, v82
	v_lshlrev_b64 v[30:31], 12, v[30:31]
	v_lshlrev_b64 v[32:33], 12, v[32:33]
	v_lshlrev_b64 v[34:35], 12, v[34:35]
	v_lshlrev_b64 v[44:45], 12, v[44:45]
	v_lshlrev_b64 v[46:47], 12, v[46:47]
	v_lshlrev_b64 v[48:49], 12, v[48:49]
	v_lshlrev_b64 v[50:51], 12, v[50:51]
	v_lshl_add_u64 v[20:21], v[84:85], 0, v[20:21]
	v_lshlrev_b64 v[22:23], 12, v[22:23]
	v_lshlrev_b64 v[24:25], 12, v[24:25]
	v_lshlrev_b64 v[26:27], 12, v[26:27]
	v_lshlrev_b64 v[28:29], 12, v[28:29]
	v_lshlrev_b64 v[36:37], 12, v[36:37]
	v_lshlrev_b64 v[38:39], 12, v[38:39]
	v_lshlrev_b64 v[40:41], 12, v[40:41]
	v_lshlrev_b64 v[42:43], 12, v[42:43]
	v_lshlrev_b64 v[52:53], 12, v[52:53]
	v_lshlrev_b64 v[54:55], 12, v[54:55]
	v_lshlrev_b64 v[56:57], 12, v[56:57]
	v_lshlrev_b64 v[58:59], 12, v[58:59]
	v_lshlrev_b64 v[60:61], 12, v[60:61]
	v_lshlrev_b64 v[62:63], 12, v[62:63]
	v_lshlrev_b64 v[64:65], 12, v[64:65]
	v_lshlrev_b64 v[66:67], 12, v[66:67]
	v_lshlrev_b64 v[68:69], 12, v[68:69]
	v_lshlrev_b64 v[70:71], 12, v[70:71]
	v_lshlrev_b64 v[72:73], 12, v[72:73]
	v_lshlrev_b64 v[74:75], 12, v[74:75]
	v_lshlrev_b64 v[76:77], 12, v[76:77]
	v_lshlrev_b64 v[78:79], 12, v[78:79]
	v_lshlrev_b64 v[80:81], 12, v[80:81]
	v_lshlrev_b64 v[82:83], 12, v[82:83]
	v_lshl_add_u64 v[30:31], v[84:85], 0, v[30:31]
	v_lshl_add_u64 v[32:33], v[84:85], 0, v[32:33]
	v_lshl_add_u64 v[34:35], v[84:85], 0, v[34:35]
	v_lshl_add_u64 v[44:45], v[84:85], 0, v[44:45]
	v_lshl_add_u64 v[46:47], v[84:85], 0, v[46:47]
	v_lshl_add_u64 v[48:49], v[84:85], 0, v[48:49]
	v_lshl_add_u64 v[50:51], v[84:85], 0, v[50:51]
	v_lshl_add_u64 v[22:23], v[84:85], 0, v[22:23]
	v_lshl_add_u64 v[24:25], v[84:85], 0, v[24:25]
	v_lshl_add_u64 v[26:27], v[84:85], 0, v[26:27]
	v_lshl_add_u64 v[28:29], v[84:85], 0, v[28:29]
	v_lshl_add_u64 v[36:37], v[84:85], 0, v[36:37]
	v_lshl_add_u64 v[38:39], v[84:85], 0, v[38:39]
	v_lshl_add_u64 v[40:41], v[84:85], 0, v[40:41]
	v_lshl_add_u64 v[42:43], v[84:85], 0, v[42:43]
	v_lshl_add_u64 v[52:53], v[84:85], 0, v[52:53]
	v_lshl_add_u64 v[54:55], v[84:85], 0, v[54:55]
	v_lshl_add_u64 v[56:57], v[84:85], 0, v[56:57]
	v_lshl_add_u64 v[58:59], v[84:85], 0, v[58:59]
	v_lshl_add_u64 v[60:61], v[84:85], 0, v[60:61]
	v_lshl_add_u64 v[62:63], v[84:85], 0, v[62:63]
	v_lshl_add_u64 v[64:65], v[84:85], 0, v[64:65]
	v_lshl_add_u64 v[66:67], v[84:85], 0, v[66:67]
	v_lshl_add_u64 v[68:69], v[84:85], 0, v[68:69]
	v_lshl_add_u64 v[70:71], v[84:85], 0, v[70:71]
	v_lshl_add_u64 v[72:73], v[84:85], 0, v[72:73]
	v_lshl_add_u64 v[74:75], v[84:85], 0, v[74:75]
	v_lshl_add_u64 v[76:77], v[84:85], 0, v[76:77]
	v_lshl_add_u64 v[78:79], v[84:85], 0, v[78:79]
	v_lshl_add_u64 v[80:81], v[84:85], 0, v[80:81]
	v_lshl_add_u64 v[82:83], v[84:85], 0, v[82:83]
	global_load_dword v19, v[20:21], off nt
	global_load_dword v84, v[22:23], off nt
	global_load_dword v85, v[24:25], off nt
	global_load_dword v86, v[26:27], off nt
	global_load_dword v87, v[28:29], off nt
	global_load_dword v88, v[30:31], off nt
	global_load_dword v89, v[32:33], off nt
	global_load_dword v90, v[34:35], off nt
	global_load_dword v91, v[36:37], off nt
	global_load_dword v92, v[38:39], off nt
	global_load_dword v93, v[40:41], off nt
	global_load_dword v94, v[42:43], off nt
	global_load_dword v95, v[44:45], off nt
	global_load_dword v96, v[46:47], off nt
	global_load_dword v97, v[48:49], off nt
	global_load_dword v30, v[50:51], off nt
	global_load_dword v31, v[52:53], off nt
	global_load_dword v32, v[54:55], off nt
	global_load_dword v33, v[56:57], off nt
	global_load_dword v34, v[58:59], off nt
	global_load_dword v35, v[60:61], off nt
	global_load_dword v44, v[62:63], off nt
	global_load_dword v45, v[64:65], off nt
	global_load_dword v46, v[66:67], off nt
	global_load_dword v47, v[68:69], off nt
	global_load_dword v48, v[70:71], off nt
	global_load_dword v49, v[72:73], off nt
	global_load_dword v98, v[74:75], off nt
	global_load_dword v99, v[76:77], off nt
	global_load_dword v100, v[78:79], off nt
	global_load_dword v50, v[80:81], off nt
	global_load_dword v51, v[82:83], off nt
	v_add_u32_e32 v22, s6, v9
	s_ashr_i32 s5, s4, 31
	v_ashrrev_i32_e32 v23, 31, v22
	v_add_u32_e32 v24, 8, v22
	v_add_u32_e32 v26, 16, v22
	v_add_u32_e32 v28, 24, v22
	v_lshl_add_u64 v[20:21], s[4:5], 1, v[6:7]
	v_lshlrev_b64 v[22:23], 12, v[22:23]
	v_ashrrev_i32_e32 v25, 31, v24
	v_ashrrev_i32_e32 v27, 31, v26
	v_ashrrev_i32_e32 v29, 31, v28
	v_lshl_add_u64 v[36:37], v[20:21], 0, v[22:23]
	v_lshlrev_b64 v[22:23], 12, v[24:25]
	v_lshlrev_b64 v[24:25], 12, v[26:27]
	v_lshlrev_b64 v[26:27], 12, v[28:29]
	s_waitcnt vmcnt(30)
	ds_write2_b32 v12, v19, v84 offset1:66
	s_waitcnt vmcnt(28)
	ds_write2_b32 v12, v85, v86 offset0:132 offset1:198
	s_waitcnt vmcnt(26)
	ds_write2_b32 v1, v87, v88 offset0:8 offset1:74
	s_waitcnt vmcnt(24)
	ds_write2_b32 v1, v89, v90 offset0:140 offset1:206
	s_waitcnt vmcnt(22)
	ds_write2_b32 v3, v91, v92 offset0:16 offset1:82
	s_waitcnt vmcnt(20)
	ds_write2_b32 v3, v93, v94 offset0:148 offset1:214
	s_waitcnt vmcnt(18)
	ds_write2_b32 v14, v95, v96 offset0:24 offset1:90
	s_waitcnt vmcnt(16)
	ds_write2_b32 v14, v97, v30 offset0:156 offset1:222
	s_waitcnt vmcnt(14)
	ds_write2_b32 v15, v31, v32 offset0:32 offset1:98
	s_waitcnt vmcnt(12)
	ds_write2_b32 v15, v33, v34 offset0:164 offset1:230
	s_waitcnt vmcnt(10)
	ds_write2_b32 v16, v35, v44 offset0:40 offset1:106
	s_waitcnt vmcnt(8)
	ds_write2_b32 v16, v45, v46 offset0:172 offset1:238
	s_waitcnt vmcnt(6)
	ds_write2_b32 v17, v47, v48 offset0:48 offset1:114
	s_waitcnt vmcnt(4)
	ds_write2_b32 v17, v49, v98 offset0:180 offset1:246
	s_waitcnt vmcnt(2)
	ds_write2_b32 v18, v99, v100 offset0:56 offset1:122
	s_waitcnt vmcnt(0)
	ds_write2_b32 v18, v50, v51 offset0:188 offset1:254
	s_waitcnt lgkmcnt(0)
	v_lshl_add_u64 v[40:41], v[20:21], 0, v[24:25]
	v_lshl_add_u64 v[42:43], v[20:21], 0, v[26:27]
	ds_read2_b32 v[24:25], v13 offset0:33 offset1:41
	ds_read2_b32 v[26:27], v13 offset1:8
	ds_read2_b32 v[28:29], v13 offset0:66 offset1:74
	ds_read2_b32 v[30:31], v13 offset0:99 offset1:107
	ds_read2_b32 v[32:33], v13 offset0:132 offset1:140
	ds_read2_b32 v[34:35], v13 offset0:165 offset1:173
	ds_read2_b32 v[44:45], v13 offset0:198 offset1:206
	ds_read2_b32 v[46:47], v13 offset0:231 offset1:239
	ds_read2_b32 v[48:49], v13 offset0:49 offset1:57
	ds_read2_b32 v[50:51], v13 offset0:16 offset1:24
	ds_read2_b32 v[52:53], v13 offset0:82 offset1:90
	ds_read2_b32 v[54:55], v13 offset0:115 offset1:123
	ds_read2_b32 v[56:57], v13 offset0:148 offset1:156
	ds_read2_b32 v[58:59], v13 offset0:181 offset1:189
	ds_read2_b32 v[60:61], v13 offset0:214 offset1:222
	ds_read2_b32 v[62:63], v13 offset0:247 offset1:255
	v_lshl_add_u64 v[38:39], v[20:21], 0, v[22:23]
	s_waitcnt lgkmcnt(14)
	v_cvt_pk_bf16_f32 v20, v26, v24
	s_waitcnt lgkmcnt(12)
	v_cvt_pk_bf16_f32 v21, v28, v30
	s_waitcnt lgkmcnt(10)
	v_cvt_pk_bf16_f32 v22, v32, v34
	s_waitcnt lgkmcnt(8)
	v_cvt_pk_bf16_f32 v23, v44, v46
	v_cvt_pk_bf16_f32 v24, v27, v25
	v_cvt_pk_bf16_f32 v25, v29, v31
	v_cvt_pk_bf16_f32 v26, v33, v35
	v_cvt_pk_bf16_f32 v27, v45, v47
	s_waitcnt lgkmcnt(6)
	v_cvt_pk_bf16_f32 v28, v50, v48
	s_waitcnt lgkmcnt(4)
	v_cvt_pk_bf16_f32 v29, v52, v54
	s_waitcnt lgkmcnt(2)
	v_cvt_pk_bf16_f32 v30, v56, v58
	s_waitcnt lgkmcnt(0)
	v_cvt_pk_bf16_f32 v31, v60, v62
	v_cvt_pk_bf16_f32 v32, v51, v49
	v_cvt_pk_bf16_f32 v33, v53, v55
	v_cvt_pk_bf16_f32 v34, v57, v59
	v_cvt_pk_bf16_f32 v35, v61, v63
	global_store_dwordx4 v[36:37], v[20:23], off
	global_store_dwordx4 v[38:39], v[24:27], off
	global_store_dwordx4 v[40:41], v[28:31], off
	global_store_dwordx4 v[42:43], v[32:35], off
	s_waitcnt lgkmcnt(0)
	s_add_i32 s16, s16, s9
	s_add_i32 s15, s15, s14
	s_cmpk_gt_i32 s16, 0x1ff
	s_cbranch_scc0 .LBB0_288
	s_load_dwordx2 s[4:5], s[0:1], 0x88
	v_mov_b32_e32 v1, 0
	v_lshlrev_b32_e32 v0, 2, v0
	v_lshlrev_b32_e32 v2, 1, v2
	v_mov_b32_e32 v3, v1
	s_waitcnt lgkmcnt(0)
	v_lshl_add_u64 v[4:5], s[4:5], 0, v[0:1]
	v_lshl_add_u64 v[6:7], s[10:11], 0, v[2:3]
	s_mov_b64 s[4:5], 0xd00800
	v_lshl_add_u64 v[6:7], v[6:7], 0, s[4:5]
	s_mov_b32 s15, s13
	s_mov_b32 s16, s8
.LBB0_290:
	s_ashr_i32 s4, s16, 31
	s_lshr_b32 s4, s4, 27
	s_add_i32 s4, s16, s4
	s_ashr_i32 s5, s4, 5
	s_lshl_b32 s4, s5, 6
	s_lshl_b32 s5, s5, 10
	v_or_b32_e32 v14, s4, v8
	s_sub_i32 s6, s15, s5
	v_or_b32_e32 v24, 10, v14
	v_or_b32_e32 v26, 12, v14
	v_or_b32_e32 v28, 14, v14
	v_or_b32_e32 v38, 24, v14
	v_or_b32_e32 v40, 26, v14
	v_or_b32_e32 v42, 28, v14
	v_or_b32_e32 v44, 30, v14
	s_ashr_i32 s7, s6, 31
	v_ashrrev_i32_e32 v15, 31, v14
	v_or_b32_e32 v16, 2, v14
	v_or_b32_e32 v18, 4, v14
	v_or_b32_e32 v20, 6, v14
	v_or_b32_e32 v22, 8, v14
	v_or_b32_e32 v30, 16, v14
	v_or_b32_e32 v32, 18, v14
	v_or_b32_e32 v34, 20, v14
	v_or_b32_e32 v36, 22, v14
	v_or_b32_e32 v46, 32, v14
	v_or_b32_e32 v48, 34, v14
	v_or_b32_e32 v50, 36, v14
	v_or_b32_e32 v52, 38, v14
	v_or_b32_e32 v54, 40, v14
	v_or_b32_e32 v56, 42, v14
	v_or_b32_e32 v58, 44, v14
	v_or_b32_e32 v60, 46, v14
	v_or_b32_e32 v62, 48, v14
	v_or_b32_e32 v64, 50, v14
	v_or_b32_e32 v66, 52, v14
	v_or_b32_e32 v68, 54, v14
	v_or_b32_e32 v70, 56, v14
	v_or_b32_e32 v72, 58, v14
	v_or_b32_e32 v74, 60, v14
	v_or_b32_e32 v76, 62, v14
	v_ashrrev_i32_e32 v25, 31, v24
	v_ashrrev_i32_e32 v27, 31, v26
	v_ashrrev_i32_e32 v29, 31, v28
	v_ashrrev_i32_e32 v39, 31, v38
	v_ashrrev_i32_e32 v41, 31, v40
	v_ashrrev_i32_e32 v43, 31, v42
	v_ashrrev_i32_e32 v45, 31, v44
	v_lshl_add_u64 v[78:79], s[6:7], 2, v[4:5]
	v_lshlrev_b64 v[14:15], 12, v[14:15]
	v_ashrrev_i32_e32 v17, 31, v16
	v_ashrrev_i32_e32 v19, 31, v18
	v_ashrrev_i32_e32 v21, 31, v20
	v_ashrrev_i32_e32 v23, 31, v22
	v_ashrrev_i32_e32 v31, 31, v30
	v_ashrrev_i32_e32 v33, 31, v32
	v_ashrrev_i32_e32 v35, 31, v34
	v_ashrrev_i32_e32 v37, 31, v36
	v_ashrrev_i32_e32 v47, 31, v46
	v_ashrrev_i32_e32 v49, 31, v48
	v_ashrrev_i32_e32 v51, 31, v50
	v_ashrrev_i32_e32 v53, 31, v52
	v_ashrrev_i32_e32 v55, 31, v54
	v_ashrrev_i32_e32 v57, 31, v56
	v_ashrrev_i32_e32 v59, 31, v58
	v_ashrrev_i32_e32 v61, 31, v60
	v_ashrrev_i32_e32 v63, 31, v62
	v_ashrrev_i32_e32 v65, 31, v64
	v_ashrrev_i32_e32 v67, 31, v66
	v_ashrrev_i32_e32 v69, 31, v68
	v_ashrrev_i32_e32 v71, 31, v70
	v_ashrrev_i32_e32 v73, 31, v72
	v_ashrrev_i32_e32 v75, 31, v74
	v_ashrrev_i32_e32 v77, 31, v76
	v_lshlrev_b64 v[24:25], 12, v[24:25]
	v_lshlrev_b64 v[26:27], 12, v[26:27]
	v_lshlrev_b64 v[28:29], 12, v[28:29]
	v_lshlrev_b64 v[38:39], 12, v[38:39]
	v_lshlrev_b64 v[40:41], 12, v[40:41]
	v_lshlrev_b64 v[42:43], 12, v[42:43]
	v_lshlrev_b64 v[44:45], 12, v[44:45]
	v_lshl_add_u64 v[14:15], v[78:79], 0, v[14:15]
	v_lshlrev_b64 v[16:17], 12, v[16:17]
	v_lshlrev_b64 v[18:19], 12, v[18:19]
	v_lshlrev_b64 v[20:21], 12, v[20:21]
	v_lshlrev_b64 v[22:23], 12, v[22:23]
	v_lshlrev_b64 v[30:31], 12, v[30:31]
	v_lshlrev_b64 v[32:33], 12, v[32:33]
	v_lshlrev_b64 v[34:35], 12, v[34:35]
	v_lshlrev_b64 v[36:37], 12, v[36:37]
	v_lshlrev_b64 v[46:47], 12, v[46:47]
	v_lshlrev_b64 v[48:49], 12, v[48:49]
	v_lshlrev_b64 v[50:51], 12, v[50:51]
	v_lshlrev_b64 v[52:53], 12, v[52:53]
	v_lshlrev_b64 v[54:55], 12, v[54:55]
	v_lshlrev_b64 v[56:57], 12, v[56:57]
	v_lshlrev_b64 v[58:59], 12, v[58:59]
	v_lshlrev_b64 v[60:61], 12, v[60:61]
	v_lshlrev_b64 v[62:63], 12, v[62:63]
	v_lshlrev_b64 v[64:65], 12, v[64:65]
	v_lshlrev_b64 v[66:67], 12, v[66:67]
	v_lshlrev_b64 v[68:69], 12, v[68:69]
	v_lshlrev_b64 v[70:71], 12, v[70:71]
	v_lshlrev_b64 v[72:73], 12, v[72:73]
	v_lshlrev_b64 v[74:75], 12, v[74:75]
	v_lshlrev_b64 v[76:77], 12, v[76:77]
	v_lshl_add_u64 v[24:25], v[78:79], 0, v[24:25]
	v_lshl_add_u64 v[26:27], v[78:79], 0, v[26:27]
	v_lshl_add_u64 v[28:29], v[78:79], 0, v[28:29]
	v_lshl_add_u64 v[38:39], v[78:79], 0, v[38:39]
	v_lshl_add_u64 v[40:41], v[78:79], 0, v[40:41]
	v_lshl_add_u64 v[42:43], v[78:79], 0, v[42:43]
	v_lshl_add_u64 v[44:45], v[78:79], 0, v[44:45]
	v_lshl_add_u64 v[16:17], v[78:79], 0, v[16:17]
	v_lshl_add_u64 v[18:19], v[78:79], 0, v[18:19]
	v_lshl_add_u64 v[20:21], v[78:79], 0, v[20:21]
	v_lshl_add_u64 v[22:23], v[78:79], 0, v[22:23]
	v_lshl_add_u64 v[30:31], v[78:79], 0, v[30:31]
	v_lshl_add_u64 v[32:33], v[78:79], 0, v[32:33]
	v_lshl_add_u64 v[34:35], v[78:79], 0, v[34:35]
	v_lshl_add_u64 v[36:37], v[78:79], 0, v[36:37]
	v_lshl_add_u64 v[46:47], v[78:79], 0, v[46:47]
	v_lshl_add_u64 v[48:49], v[78:79], 0, v[48:49]
	v_lshl_add_u64 v[50:51], v[78:79], 0, v[50:51]
	v_lshl_add_u64 v[52:53], v[78:79], 0, v[52:53]
	v_lshl_add_u64 v[54:55], v[78:79], 0, v[54:55]
	v_lshl_add_u64 v[56:57], v[78:79], 0, v[56:57]
	v_lshl_add_u64 v[58:59], v[78:79], 0, v[58:59]
	v_lshl_add_u64 v[60:61], v[78:79], 0, v[60:61]
	v_lshl_add_u64 v[62:63], v[78:79], 0, v[62:63]
	v_lshl_add_u64 v[64:65], v[78:79], 0, v[64:65]
	v_lshl_add_u64 v[66:67], v[78:79], 0, v[66:67]
	v_lshl_add_u64 v[68:69], v[78:79], 0, v[68:69]
	v_lshl_add_u64 v[70:71], v[78:79], 0, v[70:71]
	v_lshl_add_u64 v[72:73], v[78:79], 0, v[72:73]
	v_lshl_add_u64 v[74:75], v[78:79], 0, v[74:75]
	v_lshl_add_u64 v[76:77], v[78:79], 0, v[76:77]
	global_load_dword v1, v[14:15], off nt
	global_load_dword v3, v[16:17], off nt
	global_load_dword v78, v[18:19], off nt
	global_load_dword v79, v[20:21], off nt
	global_load_dword v80, v[22:23], off nt
	global_load_dword v81, v[24:25], off nt
	global_load_dword v82, v[26:27], off nt
	global_load_dword v83, v[28:29], off nt
	global_load_dword v84, v[30:31], off nt
	global_load_dword v85, v[32:33], off nt
	global_load_dword v86, v[34:35], off nt
	global_load_dword v87, v[36:37], off nt
	global_load_dword v88, v[38:39], off nt
	global_load_dword v89, v[40:41], off nt
	global_load_dword v90, v[42:43], off nt
	global_load_dword v24, v[44:45], off nt
	global_load_dword v25, v[46:47], off nt
	global_load_dword v26, v[48:49], off nt
	global_load_dword v27, v[50:51], off nt
	global_load_dword v28, v[52:53], off nt
	global_load_dword v29, v[54:55], off nt
	global_load_dword v38, v[56:57], off nt
	global_load_dword v39, v[58:59], off nt
	global_load_dword v40, v[60:61], off nt
	global_load_dword v41, v[62:63], off nt
	global_load_dword v42, v[64:65], off nt
	global_load_dword v43, v[66:67], off nt
	global_load_dword v91, v[68:69], off nt
	global_load_dword v92, v[70:71], off nt
	global_load_dword v93, v[72:73], off nt
	global_load_dword v44, v[74:75], off nt
	global_load_dword v45, v[76:77], off nt
	v_add_u32_e32 v16, s6, v9
	s_ashr_i32 s5, s4, 31
	v_ashrrev_i32_e32 v17, 31, v16
	v_add_u32_e32 v18, 8, v16
	v_add_u32_e32 v20, 16, v16
	v_add_u32_e32 v22, 24, v16
	v_lshl_add_u64 v[14:15], s[4:5], 1, v[6:7]
	v_lshlrev_b64 v[16:17], 12, v[16:17]
	v_ashrrev_i32_e32 v19, 31, v18
	v_ashrrev_i32_e32 v21, 31, v20
	v_ashrrev_i32_e32 v23, 31, v22
	v_add_u32_e32 v46, 0x400, v12
	v_add_u32_e32 v47, 0x800, v12
	v_add_u32_e32 v48, 0xc00, v12
	v_add_u32_e32 v49, 0x1000, v12
	v_add_u32_e32 v50, 0x1400, v12
	v_add_u32_e32 v51, 0x1800, v12
	v_add_u32_e32 v52, 0x1c00, v12
	v_lshl_add_u64 v[30:31], v[14:15], 0, v[16:17]
	v_lshlrev_b64 v[16:17], 12, v[18:19]
	v_lshlrev_b64 v[18:19], 12, v[20:21]
	v_lshlrev_b64 v[20:21], 12, v[22:23]
	s_waitcnt vmcnt(30)
	ds_write2_b32 v12, v1, v3 offset1:66
	s_waitcnt vmcnt(28)
	ds_write2_b32 v12, v78, v79 offset0:132 offset1:198
	s_waitcnt vmcnt(26)
	ds_write2_b32 v46, v80, v81 offset0:8 offset1:74
	s_waitcnt vmcnt(24)
	ds_write2_b32 v46, v82, v83 offset0:140 offset1:206
	s_waitcnt vmcnt(22)
	ds_write2_b32 v47, v84, v85 offset0:16 offset1:82
	s_waitcnt vmcnt(20)
	ds_write2_b32 v47, v86, v87 offset0:148 offset1:214
	s_waitcnt vmcnt(18)
	ds_write2_b32 v48, v88, v89 offset0:24 offset1:90
	s_waitcnt vmcnt(16)
	ds_write2_b32 v48, v90, v24 offset0:156 offset1:222
	s_waitcnt vmcnt(14)
	ds_write2_b32 v49, v25, v26 offset0:32 offset1:98
	s_waitcnt vmcnt(12)
	ds_write2_b32 v49, v27, v28 offset0:164 offset1:230
	s_waitcnt vmcnt(10)
	ds_write2_b32 v50, v29, v38 offset0:40 offset1:106
	s_waitcnt vmcnt(8)
	ds_write2_b32 v50, v39, v40 offset0:172 offset1:238
	s_waitcnt vmcnt(6)
	ds_write2_b32 v51, v41, v42 offset0:48 offset1:114
	s_waitcnt vmcnt(4)
	ds_write2_b32 v51, v43, v91 offset0:180 offset1:246
	s_waitcnt vmcnt(2)
	ds_write2_b32 v52, v92, v93 offset0:56 offset1:122
	s_waitcnt vmcnt(0)
	ds_write2_b32 v52, v44, v45 offset0:188 offset1:254
	s_waitcnt lgkmcnt(0)
	v_lshl_add_u64 v[34:35], v[14:15], 0, v[18:19]
	v_lshl_add_u64 v[36:37], v[14:15], 0, v[20:21]
	ds_read2_b32 v[18:19], v13 offset0:33 offset1:41
	ds_read2_b32 v[20:21], v13 offset1:8
	ds_read2_b32 v[22:23], v13 offset0:66 offset1:74
	ds_read2_b32 v[24:25], v13 offset0:99 offset1:107
	ds_read2_b32 v[26:27], v13 offset0:132 offset1:140
	ds_read2_b32 v[28:29], v13 offset0:165 offset1:173
	ds_read2_b32 v[38:39], v13 offset0:198 offset1:206
	ds_read2_b32 v[40:41], v13 offset0:231 offset1:239
	ds_read2_b32 v[42:43], v13 offset0:49 offset1:57
	ds_read2_b32 v[44:45], v13 offset0:16 offset1:24
	ds_read2_b32 v[46:47], v13 offset0:82 offset1:90
	ds_read2_b32 v[48:49], v13 offset0:115 offset1:123
	ds_read2_b32 v[50:51], v13 offset0:148 offset1:156
	ds_read2_b32 v[52:53], v13 offset0:181 offset1:189
	ds_read2_b32 v[54:55], v13 offset0:214 offset1:222
	ds_read2_b32 v[56:57], v13 offset0:247 offset1:255
	v_lshl_add_u64 v[32:33], v[14:15], 0, v[16:17]
	s_waitcnt lgkmcnt(14)
	v_cvt_pk_bf16_f32 v14, v20, v18
	s_waitcnt lgkmcnt(12)
	v_cvt_pk_bf16_f32 v15, v22, v24
	s_waitcnt lgkmcnt(10)
	v_cvt_pk_bf16_f32 v16, v26, v28
	s_waitcnt lgkmcnt(8)
	v_cvt_pk_bf16_f32 v17, v38, v40
	v_cvt_pk_bf16_f32 v18, v21, v19
	v_cvt_pk_bf16_f32 v19, v23, v25
	v_cvt_pk_bf16_f32 v20, v27, v29
	v_cvt_pk_bf16_f32 v21, v39, v41
	s_waitcnt lgkmcnt(6)
	v_cvt_pk_bf16_f32 v22, v44, v42
	s_waitcnt lgkmcnt(4)
	v_cvt_pk_bf16_f32 v23, v46, v48
	s_waitcnt lgkmcnt(2)
	v_cvt_pk_bf16_f32 v24, v50, v52
	s_waitcnt lgkmcnt(0)
	v_cvt_pk_bf16_f32 v25, v54, v56
	v_cvt_pk_bf16_f32 v26, v45, v43
	v_cvt_pk_bf16_f32 v27, v47, v49
	v_cvt_pk_bf16_f32 v28, v51, v53
	v_cvt_pk_bf16_f32 v29, v55, v57
	global_store_dwordx4 v[30:31], v[14:17], off
	global_store_dwordx4 v[32:33], v[18:21], off
	global_store_dwordx4 v[34:35], v[22:25], off
	global_store_dwordx4 v[36:37], v[26:29], off
	s_waitcnt lgkmcnt(0)
	s_add_i32 s16, s16, s9
	s_add_i32 s15, s15, s14
	s_cmpk_gt_i32 s16, 0x1ff
	s_cbranch_scc0 .LBB0_290
	s_load_dwordx2 s[4:5], s[0:1], 0x90
	v_mov_b32_e32 v1, 0
	v_mov_b32_e32 v3, v1
	v_lshl_add_u64 v[2:3], s[10:11], 0, v[2:3]
	s_mov_b32 s15, s8
	s_waitcnt lgkmcnt(0)
	v_lshl_add_u64 v[0:1], s[4:5], 0, v[0:1]
	s_mov_b64 s[4:5], 0x1100000
	v_lshl_add_u64 v[2:3], v[2:3], 0, s[4:5]
.LBB0_292:
	s_ashr_i32 s4, s15, 31
	s_lshr_b32 s4, s4, 27
	s_add_i32 s4, s15, s4
	s_ashr_i32 s5, s4, 5
	s_lshl_b32 s4, s5, 6
	s_lshl_b32 s5, s5, 10
	v_or_b32_e32 v4, s4, v8
	s_sub_i32 s6, s13, s5
	v_or_b32_e32 v20, 10, v4
	v_or_b32_e32 v22, 12, v4
	v_or_b32_e32 v24, 14, v4
	v_or_b32_e32 v34, 24, v4
	v_or_b32_e32 v36, 26, v4
	v_or_b32_e32 v38, 28, v4
	v_or_b32_e32 v40, 30, v4
	s_ashr_i32 s7, s6, 31
	v_ashrrev_i32_e32 v5, 31, v4
	v_or_b32_e32 v6, 2, v4
	v_or_b32_e32 v14, 4, v4
	v_or_b32_e32 v16, 6, v4
	v_or_b32_e32 v18, 8, v4
	v_or_b32_e32 v26, 16, v4
	v_or_b32_e32 v28, 18, v4
	v_or_b32_e32 v30, 20, v4
	v_or_b32_e32 v32, 22, v4
	v_or_b32_e32 v42, 32, v4
	v_or_b32_e32 v44, 34, v4
	v_or_b32_e32 v46, 36, v4
	v_or_b32_e32 v48, 38, v4
	v_or_b32_e32 v50, 40, v4
	v_or_b32_e32 v52, 42, v4
	v_or_b32_e32 v54, 44, v4
	v_or_b32_e32 v56, 46, v4
	v_or_b32_e32 v58, 48, v4
	v_or_b32_e32 v60, 50, v4
	v_or_b32_e32 v62, 52, v4
	v_or_b32_e32 v64, 54, v4
	v_or_b32_e32 v66, 56, v4
	v_or_b32_e32 v68, 58, v4
	v_or_b32_e32 v70, 60, v4
	v_or_b32_e32 v72, 62, v4
	v_ashrrev_i32_e32 v21, 31, v20
	v_ashrrev_i32_e32 v23, 31, v22
	v_ashrrev_i32_e32 v25, 31, v24
	v_ashrrev_i32_e32 v35, 31, v34
	v_ashrrev_i32_e32 v37, 31, v36
	v_ashrrev_i32_e32 v39, 31, v38
	v_ashrrev_i32_e32 v41, 31, v40
	v_lshl_add_u64 v[74:75], s[6:7], 2, v[0:1]
	v_lshlrev_b64 v[4:5], 12, v[4:5]
	v_ashrrev_i32_e32 v7, 31, v6
	v_ashrrev_i32_e32 v15, 31, v14
	v_ashrrev_i32_e32 v17, 31, v16
	v_ashrrev_i32_e32 v19, 31, v18
	v_ashrrev_i32_e32 v27, 31, v26
	v_ashrrev_i32_e32 v29, 31, v28
	v_ashrrev_i32_e32 v31, 31, v30
	v_ashrrev_i32_e32 v33, 31, v32
	v_ashrrev_i32_e32 v43, 31, v42
	v_ashrrev_i32_e32 v45, 31, v44
	v_ashrrev_i32_e32 v47, 31, v46
	v_ashrrev_i32_e32 v49, 31, v48
	v_ashrrev_i32_e32 v51, 31, v50
	v_ashrrev_i32_e32 v53, 31, v52
	v_ashrrev_i32_e32 v55, 31, v54
	v_ashrrev_i32_e32 v57, 31, v56
	v_ashrrev_i32_e32 v59, 31, v58
	v_ashrrev_i32_e32 v61, 31, v60
	v_ashrrev_i32_e32 v63, 31, v62
	v_ashrrev_i32_e32 v65, 31, v64
	v_ashrrev_i32_e32 v67, 31, v66
	v_ashrrev_i32_e32 v69, 31, v68
	v_ashrrev_i32_e32 v71, 31, v70
	v_ashrrev_i32_e32 v73, 31, v72
	v_lshlrev_b64 v[20:21], 12, v[20:21]
	v_lshlrev_b64 v[22:23], 12, v[22:23]
	v_lshlrev_b64 v[24:25], 12, v[24:25]
	v_lshlrev_b64 v[34:35], 12, v[34:35]
	v_lshlrev_b64 v[36:37], 12, v[36:37]
	v_lshlrev_b64 v[38:39], 12, v[38:39]
	v_lshlrev_b64 v[40:41], 12, v[40:41]
	v_lshl_add_u64 v[4:5], v[74:75], 0, v[4:5]
	v_lshlrev_b64 v[6:7], 12, v[6:7]
	v_lshlrev_b64 v[14:15], 12, v[14:15]
	v_lshlrev_b64 v[16:17], 12, v[16:17]
	v_lshlrev_b64 v[18:19], 12, v[18:19]
	v_lshlrev_b64 v[26:27], 12, v[26:27]
	v_lshlrev_b64 v[28:29], 12, v[28:29]
	v_lshlrev_b64 v[30:31], 12, v[30:31]
	v_lshlrev_b64 v[32:33], 12, v[32:33]
	v_lshlrev_b64 v[42:43], 12, v[42:43]
	v_lshlrev_b64 v[44:45], 12, v[44:45]
	v_lshlrev_b64 v[46:47], 12, v[46:47]
	v_lshlrev_b64 v[48:49], 12, v[48:49]
	v_lshlrev_b64 v[50:51], 12, v[50:51]
	v_lshlrev_b64 v[52:53], 12, v[52:53]
	v_lshlrev_b64 v[54:55], 12, v[54:55]
	v_lshlrev_b64 v[56:57], 12, v[56:57]
	v_lshlrev_b64 v[58:59], 12, v[58:59]
	v_lshlrev_b64 v[60:61], 12, v[60:61]
	v_lshlrev_b64 v[62:63], 12, v[62:63]
	v_lshlrev_b64 v[64:65], 12, v[64:65]
	v_lshlrev_b64 v[66:67], 12, v[66:67]
	v_lshlrev_b64 v[68:69], 12, v[68:69]
	v_lshlrev_b64 v[70:71], 12, v[70:71]
	v_lshlrev_b64 v[72:73], 12, v[72:73]
	v_lshl_add_u64 v[20:21], v[74:75], 0, v[20:21]
	v_lshl_add_u64 v[22:23], v[74:75], 0, v[22:23]
	v_lshl_add_u64 v[24:25], v[74:75], 0, v[24:25]
	v_lshl_add_u64 v[34:35], v[74:75], 0, v[34:35]
	v_lshl_add_u64 v[36:37], v[74:75], 0, v[36:37]
	v_lshl_add_u64 v[38:39], v[74:75], 0, v[38:39]
	v_lshl_add_u64 v[40:41], v[74:75], 0, v[40:41]
	v_lshl_add_u64 v[6:7], v[74:75], 0, v[6:7]
	v_lshl_add_u64 v[14:15], v[74:75], 0, v[14:15]
	v_lshl_add_u64 v[16:17], v[74:75], 0, v[16:17]
	v_lshl_add_u64 v[18:19], v[74:75], 0, v[18:19]
	v_lshl_add_u64 v[26:27], v[74:75], 0, v[26:27]
	v_lshl_add_u64 v[28:29], v[74:75], 0, v[28:29]
	v_lshl_add_u64 v[30:31], v[74:75], 0, v[30:31]
	v_lshl_add_u64 v[32:33], v[74:75], 0, v[32:33]
	v_lshl_add_u64 v[42:43], v[74:75], 0, v[42:43]
	v_lshl_add_u64 v[44:45], v[74:75], 0, v[44:45]
	v_lshl_add_u64 v[46:47], v[74:75], 0, v[46:47]
	v_lshl_add_u64 v[48:49], v[74:75], 0, v[48:49]
	v_lshl_add_u64 v[50:51], v[74:75], 0, v[50:51]
	v_lshl_add_u64 v[52:53], v[74:75], 0, v[52:53]
	v_lshl_add_u64 v[54:55], v[74:75], 0, v[54:55]
	v_lshl_add_u64 v[56:57], v[74:75], 0, v[56:57]
	v_lshl_add_u64 v[58:59], v[74:75], 0, v[58:59]
	v_lshl_add_u64 v[60:61], v[74:75], 0, v[60:61]
	v_lshl_add_u64 v[62:63], v[74:75], 0, v[62:63]
	v_lshl_add_u64 v[64:65], v[74:75], 0, v[64:65]
	v_lshl_add_u64 v[66:67], v[74:75], 0, v[66:67]
	v_lshl_add_u64 v[68:69], v[74:75], 0, v[68:69]
	v_lshl_add_u64 v[70:71], v[74:75], 0, v[70:71]
	v_lshl_add_u64 v[72:73], v[74:75], 0, v[72:73]
	global_load_dword v74, v[4:5], off nt
	global_load_dword v75, v[6:7], off nt
	global_load_dword v76, v[14:15], off nt
	global_load_dword v77, v[16:17], off nt
	global_load_dword v78, v[18:19], off nt
	global_load_dword v79, v[20:21], off nt
	global_load_dword v80, v[22:23], off nt
	global_load_dword v81, v[24:25], off nt
	global_load_dword v82, v[26:27], off nt
	global_load_dword v83, v[28:29], off nt
	global_load_dword v84, v[30:31], off nt
	global_load_dword v85, v[32:33], off nt
	global_load_dword v86, v[34:35], off nt
	global_load_dword v87, v[36:37], off nt
	global_load_dword v88, v[38:39], off nt
	global_load_dword v20, v[40:41], off nt
	global_load_dword v21, v[42:43], off nt
	global_load_dword v22, v[44:45], off nt
	global_load_dword v23, v[46:47], off nt
	global_load_dword v24, v[48:49], off nt
	global_load_dword v25, v[50:51], off nt
	global_load_dword v34, v[52:53], off nt
	global_load_dword v35, v[54:55], off nt
	global_load_dword v36, v[56:57], off nt
	global_load_dword v37, v[58:59], off nt
	global_load_dword v38, v[60:61], off nt
	global_load_dword v39, v[62:63], off nt
	global_load_dword v89, v[64:65], off nt
	global_load_dword v90, v[66:67], off nt
	global_load_dword v91, v[68:69], off nt
	global_load_dword v40, v[70:71], off nt
	global_load_dword v41, v[72:73], off nt
	v_add_u32_e32 v6, s6, v9
	s_ashr_i32 s5, s4, 31
	v_ashrrev_i32_e32 v7, 31, v6
	v_add_u32_e32 v14, 8, v6
	v_add_u32_e32 v16, 16, v6
	v_add_u32_e32 v18, 24, v6
	v_lshl_add_u64 v[4:5], s[4:5], 1, v[2:3]
	v_lshlrev_b64 v[6:7], 11, v[6:7]
	v_ashrrev_i32_e32 v15, 31, v14
	v_ashrrev_i32_e32 v17, 31, v16
	v_ashrrev_i32_e32 v19, 31, v18
	v_add_u32_e32 v42, 0x400, v12
	v_add_u32_e32 v43, 0x800, v12
	v_add_u32_e32 v44, 0xc00, v12
	v_add_u32_e32 v45, 0x1000, v12
	v_add_u32_e32 v46, 0x1400, v12
	v_add_u32_e32 v47, 0x1800, v12
	v_add_u32_e32 v48, 0x1c00, v12
	v_lshl_add_u64 v[26:27], v[4:5], 0, v[6:7]
	v_lshlrev_b64 v[6:7], 11, v[14:15]
	v_lshlrev_b64 v[14:15], 11, v[16:17]
	v_lshlrev_b64 v[16:17], 11, v[18:19]
	s_waitcnt vmcnt(30)
	ds_write2_b32 v12, v74, v75 offset1:66
	s_waitcnt vmcnt(28)
	ds_write2_b32 v12, v76, v77 offset0:132 offset1:198
	s_waitcnt vmcnt(26)
	ds_write2_b32 v42, v78, v79 offset0:8 offset1:74
	s_waitcnt vmcnt(24)
	ds_write2_b32 v42, v80, v81 offset0:140 offset1:206
	s_waitcnt vmcnt(22)
	ds_write2_b32 v43, v82, v83 offset0:16 offset1:82
	s_waitcnt vmcnt(20)
	ds_write2_b32 v43, v84, v85 offset0:148 offset1:214
	s_waitcnt vmcnt(18)
	ds_write2_b32 v44, v86, v87 offset0:24 offset1:90
	s_waitcnt vmcnt(16)
	ds_write2_b32 v44, v88, v20 offset0:156 offset1:222
	s_waitcnt vmcnt(14)
	ds_write2_b32 v45, v21, v22 offset0:32 offset1:98
	s_waitcnt vmcnt(12)
	ds_write2_b32 v45, v23, v24 offset0:164 offset1:230
	s_waitcnt vmcnt(10)
	ds_write2_b32 v46, v25, v34 offset0:40 offset1:106
	s_waitcnt vmcnt(8)
	ds_write2_b32 v46, v35, v36 offset0:172 offset1:238
	s_waitcnt vmcnt(6)
	ds_write2_b32 v47, v37, v38 offset0:48 offset1:114
	s_waitcnt vmcnt(4)
	ds_write2_b32 v47, v39, v89 offset0:180 offset1:246
	s_waitcnt vmcnt(2)
	ds_write2_b32 v48, v90, v91 offset0:56 offset1:122
	s_waitcnt vmcnt(0)
	ds_write2_b32 v48, v40, v41 offset0:188 offset1:254
	s_waitcnt lgkmcnt(0)
	v_lshl_add_u64 v[30:31], v[4:5], 0, v[14:15]
	v_lshl_add_u64 v[32:33], v[4:5], 0, v[16:17]
	ds_read2_b32 v[14:15], v13 offset0:33 offset1:41
	ds_read2_b32 v[16:17], v13 offset1:8
	ds_read2_b32 v[18:19], v13 offset0:66 offset1:74
	ds_read2_b32 v[20:21], v13 offset0:99 offset1:107
	ds_read2_b32 v[22:23], v13 offset0:132 offset1:140
	ds_read2_b32 v[24:25], v13 offset0:165 offset1:173
	ds_read2_b32 v[34:35], v13 offset0:198 offset1:206
	ds_read2_b32 v[36:37], v13 offset0:231 offset1:239
	ds_read2_b32 v[38:39], v13 offset0:49 offset1:57
	ds_read2_b32 v[40:41], v13 offset0:16 offset1:24
	ds_read2_b32 v[42:43], v13 offset0:82 offset1:90
	ds_read2_b32 v[44:45], v13 offset0:115 offset1:123
	ds_read2_b32 v[46:47], v13 offset0:148 offset1:156
	ds_read2_b32 v[48:49], v13 offset0:181 offset1:189
	ds_read2_b32 v[50:51], v13 offset0:214 offset1:222
	ds_read2_b32 v[52:53], v13 offset0:247 offset1:255
	v_lshl_add_u64 v[28:29], v[4:5], 0, v[6:7]
	s_waitcnt lgkmcnt(14)
	v_cvt_pk_bf16_f32 v4, v16, v14
	s_waitcnt lgkmcnt(12)
	v_cvt_pk_bf16_f32 v5, v18, v20
	s_waitcnt lgkmcnt(10)
	v_cvt_pk_bf16_f32 v6, v22, v24
	s_waitcnt lgkmcnt(8)
	v_cvt_pk_bf16_f32 v7, v34, v36
	v_cvt_pk_bf16_f32 v14, v17, v15
	v_cvt_pk_bf16_f32 v15, v19, v21
	v_cvt_pk_bf16_f32 v16, v23, v25
	v_cvt_pk_bf16_f32 v17, v35, v37
	s_waitcnt lgkmcnt(6)
	v_cvt_pk_bf16_f32 v18, v40, v38
	s_waitcnt lgkmcnt(4)
	v_cvt_pk_bf16_f32 v19, v42, v44
	s_waitcnt lgkmcnt(2)
	v_cvt_pk_bf16_f32 v20, v46, v48
	s_waitcnt lgkmcnt(0)
	v_cvt_pk_bf16_f32 v21, v50, v52
	v_cvt_pk_bf16_f32 v22, v41, v39
	v_cvt_pk_bf16_f32 v23, v43, v45
	v_cvt_pk_bf16_f32 v24, v47, v49
	v_cvt_pk_bf16_f32 v25, v51, v53
	global_store_dwordx4 v[26:27], v[4:7], off
	global_store_dwordx4 v[28:29], v[14:17], off
	global_store_dwordx4 v[30:31], v[18:21], off
	global_store_dwordx4 v[32:33], v[22:25], off
	s_waitcnt lgkmcnt(0)
	s_add_i32 s15, s15, s9
	s_add_i32 s13, s13, s14
	s_cmpk_gt_i32 s15, 0x1ff
	s_cbranch_scc0 .LBB0_292

.LBB0_295:
	s_mul_hi_i32 s4, s8, 0x2e8ba2e9
	s_lshr_b32 s5, s4, 31
	s_ashr_i32 s4, s4, 5
	s_add_i32 s4, s4, s5
	s_mul_i32 s13, s4, 0xffffea00
	s_mul_i32 s5, s4, 0xffffff50
	s_add_i32 s14, s6, s13
	s_add_i32 s5, s8, s5
	s_add_i32 s13, s14, 0xfffff500
	s_cmpk_lt_i32 s5, 0x58
	s_cselect_b32 s5, s14, s13
	s_cselect_b32 s13, 0, 0x80
	s_lshl_b32 s4, s4, 6
	s_ashr_i32 s15, s14, 31
	v_or_b32_e32 v22, s4, v8
	v_lshl_add_u64 v[18:19], s[14:15], 2, v[0:1]
	v_or_b32_e32 v28, 8, v22
	v_or_b32_e32 v30, 10, v22
	v_or_b32_e32 v32, 12, v22
	v_or_b32_e32 v42, 22, v22
	v_or_b32_e32 v44, 24, v22
	v_or_b32_e32 v46, 26, v22
	v_or_b32_e32 v48, 28, v22
	v_or_b32_e32 v50, 30, v22
	v_mad_i64_i32 v[20:21], s[14:15], v22, s12, v[18:19]
	v_or_b32_e32 v23, 2, v22
	v_or_b32_e32 v24, 4, v22
	v_or_b32_e32 v26, 6, v22
	v_or_b32_e32 v34, 14, v22
	v_or_b32_e32 v36, 16, v22
	v_or_b32_e32 v38, 18, v22
	v_or_b32_e32 v40, 20, v22
	v_or_b32_e32 v52, 32, v22
	v_or_b32_e32 v54, 34, v22
	v_or_b32_e32 v56, 36, v22
	v_or_b32_e32 v58, 38, v22
	v_or_b32_e32 v60, 40, v22
	v_or_b32_e32 v62, 42, v22
	v_or_b32_e32 v64, 44, v22
	v_or_b32_e32 v66, 46, v22
	v_or_b32_e32 v68, 48, v22
	v_or_b32_e32 v70, 50, v22
	v_or_b32_e32 v72, 52, v22
	v_or_b32_e32 v74, 54, v22
	v_or_b32_e32 v76, 56, v22
	v_or_b32_e32 v78, 58, v22
	v_or_b32_e32 v80, 60, v22
	v_or_b32_e32 v82, 62, v22
	v_mad_i64_i32 v[28:29], s[14:15], v28, s12, v[18:19]
	v_mad_i64_i32 v[30:31], s[14:15], v30, s12, v[18:19]
	v_mad_i64_i32 v[32:33], s[14:15], v32, s12, v[18:19]
	v_mad_i64_i32 v[42:43], s[14:15], v42, s12, v[18:19]
	v_mad_i64_i32 v[44:45], s[14:15], v44, s12, v[18:19]
	v_mad_i64_i32 v[46:47], s[14:15], v46, s12, v[18:19]
	v_mad_i64_i32 v[48:49], s[14:15], v48, s12, v[18:19]
	v_mad_i64_i32 v[50:51], s[14:15], v50, s12, v[18:19]
	v_mad_i64_i32 v[22:23], s[14:15], v23, s12, v[18:19]
	v_mad_i64_i32 v[24:25], s[14:15], v24, s12, v[18:19]
	v_mad_i64_i32 v[26:27], s[14:15], v26, s12, v[18:19]
	v_mad_i64_i32 v[34:35], s[14:15], v34, s12, v[18:19]
	v_mad_i64_i32 v[36:37], s[14:15], v36, s12, v[18:19]
	v_mad_i64_i32 v[38:39], s[14:15], v38, s12, v[18:19]
	v_mad_i64_i32 v[40:41], s[14:15], v40, s12, v[18:19]
	v_mad_i64_i32 v[52:53], s[14:15], v52, s12, v[18:19]
	v_mad_i64_i32 v[54:55], s[14:15], v54, s12, v[18:19]
	v_mad_i64_i32 v[56:57], s[14:15], v56, s12, v[18:19]
	v_mad_i64_i32 v[58:59], s[14:15], v58, s12, v[18:19]
	v_mad_i64_i32 v[60:61], s[14:15], v60, s12, v[18:19]
	v_mad_i64_i32 v[62:63], s[14:15], v62, s12, v[18:19]
	v_mad_i64_i32 v[64:65], s[14:15], v64, s12, v[18:19]
	v_mad_i64_i32 v[66:67], s[14:15], v66, s12, v[18:19]
	v_mad_i64_i32 v[68:69], s[14:15], v68, s12, v[18:19]
	v_mad_i64_i32 v[70:71], s[14:15], v70, s12, v[18:19]
	v_mad_i64_i32 v[72:73], s[14:15], v72, s12, v[18:19]
	v_mad_i64_i32 v[74:75], s[14:15], v74, s12, v[18:19]
	v_mad_i64_i32 v[76:77], s[14:15], v76, s12, v[18:19]
	v_mad_i64_i32 v[78:79], s[14:15], v78, s12, v[18:19]
	v_mad_i64_i32 v[80:81], s[14:15], v80, s12, v[18:19]
	v_mad_i64_i32 v[18:19], s[14:15], v82, s12, v[18:19]
	global_load_dword v82, v[20:21], off nt
	global_load_dword v83, v[22:23], off nt
	global_load_dword v84, v[24:25], off nt
	global_load_dword v85, v[26:27], off nt
	global_load_dword v86, v[28:29], off nt
	global_load_dword v87, v[30:31], off nt
	global_load_dword v88, v[32:33], off nt
	global_load_dword v89, v[34:35], off nt
	global_load_dword v90, v[36:37], off nt
	global_load_dword v91, v[38:39], off nt
	global_load_dword v92, v[40:41], off nt
	global_load_dword v93, v[42:43], off nt
	global_load_dword v94, v[44:45], off nt
	global_load_dword v95, v[46:47], off nt
	global_load_dword v96, v[48:49], off nt
	global_load_dword v28, v[50:51], off nt
	global_load_dword v29, v[52:53], off nt
	global_load_dword v30, v[54:55], off nt
	global_load_dword v31, v[56:57], off nt
	global_load_dword v32, v[58:59], off nt
	global_load_dword v33, v[60:61], off nt
	global_load_dword v42, v[62:63], off nt
	global_load_dword v43, v[64:65], off nt
	global_load_dword v44, v[66:67], off nt
	global_load_dword v45, v[68:69], off nt
	global_load_dword v46, v[70:71], off nt
	global_load_dword v47, v[72:73], off nt
	global_load_dword v48, v[74:75], off nt
	global_load_dword v49, v[76:77], off nt
	global_load_dword v97, v[78:79], off nt
	global_load_dword v50, v[80:81], off nt
	global_load_dword v51, v[18:19], off nt
	s_lshl_b32 s14, s5, 1
	s_and_b32 s15, s5, 0x60
	s_ashr_i32 s5, s4, 31
	s_and_b32 s14, s14, 0xffffff00
	s_or_b32 s13, s15, s13
	v_lshl_add_u64 v[18:19], s[4:5], 1, v[2:3]
	s_or_b32 s4, s13, s14
	v_or_b32_e32 v22, s4, v6
	v_or_b32_e32 v24, s4, v7
	v_or_b32_e32 v26, s4, v10
	v_ashrrev_i32_e32 v23, 31, v22
	v_ashrrev_i32_e32 v25, 31, v24
	v_ashrrev_i32_e32 v27, 31, v26
	v_lshlrev_b64 v[22:23], 11, v[22:23]
	v_lshlrev_b64 v[24:25], 11, v[24:25]
	v_lshlrev_b64 v[26:27], 11, v[26:27]
	s_waitcnt vmcnt(30)
	ds_write2_b32 v4, v82, v83 offset1:66
	s_waitcnt vmcnt(28)
	ds_write2_b32 v4, v84, v85 offset0:132 offset1:198
	s_waitcnt vmcnt(26)
	ds_write2_b32 v11, v86, v87 offset0:8 offset1:74
	s_waitcnt vmcnt(24)
	ds_write2_b32 v11, v88, v89 offset0:140 offset1:206
	s_waitcnt vmcnt(22)
	ds_write2_b32 v12, v90, v91 offset0:16 offset1:82
	s_waitcnt vmcnt(20)
	ds_write2_b32 v12, v92, v93 offset0:148 offset1:214
	s_waitcnt vmcnt(18)
	ds_write2_b32 v13, v94, v95 offset0:24 offset1:90
	s_waitcnt vmcnt(16)
	ds_write2_b32 v13, v96, v28 offset0:156 offset1:222
	s_waitcnt vmcnt(14)
	ds_write2_b32 v14, v29, v30 offset0:32 offset1:98
	s_waitcnt vmcnt(12)
	ds_write2_b32 v14, v31, v32 offset0:164 offset1:230
	s_waitcnt vmcnt(10)
	ds_write2_b32 v15, v33, v42 offset0:40 offset1:106
	s_waitcnt vmcnt(8)
	ds_write2_b32 v15, v43, v44 offset0:172 offset1:238
	s_waitcnt vmcnt(6)
	ds_write2_b32 v16, v45, v46 offset0:48 offset1:114
	s_waitcnt vmcnt(4)
	ds_write2_b32 v16, v47, v48 offset0:180 offset1:246
	s_waitcnt vmcnt(2)
	ds_write2_b32 v17, v49, v97 offset0:56 offset1:122
	s_waitcnt vmcnt(0)
	ds_write2_b32 v17, v50, v51 offset0:188 offset1:254
	s_waitcnt lgkmcnt(0)
	v_lshl_add_u64 v[36:37], v[18:19], 0, v[22:23]
	v_lshl_add_u64 v[38:39], v[18:19], 0, v[24:25]
	v_lshl_add_u64 v[40:41], v[18:19], 0, v[26:27]
	ds_read2_b32 v[22:23], v5 offset0:33 offset1:41
	ds_read2_b32 v[24:25], v5 offset1:8
	ds_read2_b32 v[26:27], v5 offset0:66 offset1:74
	ds_read2_b32 v[28:29], v5 offset0:99 offset1:107
	ds_read2_b32 v[30:31], v5 offset0:132 offset1:140
	ds_read2_b32 v[32:33], v5 offset0:165 offset1:173
	ds_read2_b32 v[42:43], v5 offset0:198 offset1:206
	ds_read2_b32 v[44:45], v5 offset0:231 offset1:239
	ds_read2_b32 v[46:47], v5 offset0:49 offset1:57
	ds_read2_b32 v[48:49], v5 offset0:16 offset1:24
	ds_read2_b32 v[50:51], v5 offset0:82 offset1:90
	ds_read2_b32 v[52:53], v5 offset0:115 offset1:123
	ds_read2_b32 v[54:55], v5 offset0:148 offset1:156
	ds_read2_b32 v[56:57], v5 offset0:181 offset1:189
	ds_read2_b32 v[58:59], v5 offset0:214 offset1:222
	ds_read2_b32 v[60:61], v5 offset0:247 offset1:255
	v_or_b32_e32 v20, s4, v9
	v_ashrrev_i32_e32 v21, 31, v20
	v_lshlrev_b64 v[20:21], 11, v[20:21]
	v_lshl_add_u64 v[34:35], v[18:19], 0, v[20:21]
	s_waitcnt lgkmcnt(14)
	v_cvt_pk_bf16_f32 v18, v24, v22
	s_waitcnt lgkmcnt(12)
	v_cvt_pk_bf16_f32 v19, v26, v28
	s_waitcnt lgkmcnt(10)
	v_cvt_pk_bf16_f32 v20, v30, v32
	s_waitcnt lgkmcnt(8)
	v_cvt_pk_bf16_f32 v21, v42, v44
	v_cvt_pk_bf16_f32 v22, v25, v23
	v_cvt_pk_bf16_f32 v23, v27, v29
	v_cvt_pk_bf16_f32 v24, v31, v33
	v_cvt_pk_bf16_f32 v25, v43, v45
	s_waitcnt lgkmcnt(6)
	v_cvt_pk_bf16_f32 v26, v48, v46
	s_waitcnt lgkmcnt(4)
	v_cvt_pk_bf16_f32 v27, v50, v52
	s_waitcnt lgkmcnt(2)
	v_cvt_pk_bf16_f32 v28, v54, v56
	s_waitcnt lgkmcnt(0)
	v_cvt_pk_bf16_f32 v29, v58, v60
	v_cvt_pk_bf16_f32 v30, v49, v47
	v_cvt_pk_bf16_f32 v31, v51, v53
	v_cvt_pk_bf16_f32 v32, v55, v57
	v_cvt_pk_bf16_f32 v33, v59, v61
	global_store_dwordx4 v[34:35], v[18:21], off
	global_store_dwordx4 v[36:37], v[22:25], off
	global_store_dwordx4 v[38:39], v[26:29], off
	global_store_dwordx4 v[40:41], v[30:33], off
	s_waitcnt lgkmcnt(0)
	s_add_i32 s8, s8, s9
	s_add_i32 s6, s6, s7
	s_cmpk_gt_i32 s8, 0xaff
	s_cbranch_scc0 .LBB0_295

.LBB0_301:
	s_ashr_i32 s2, s13, 31
	s_lshr_b32 s2, s2, 27
	s_add_i32 s2, s13, s2
	s_ashr_i32 s3, s2, 5
	s_lshl_b32 s2, s3, 6
	s_lshl_b32 s3, s3, 10
	v_or_b32_e32 v20, s2, v8
	s_sub_i32 s4, s12, s3
	v_or_b32_e32 v30, 10, v20
	v_or_b32_e32 v32, 12, v20
	v_or_b32_e32 v34, 14, v20
	v_or_b32_e32 v44, 24, v20
	v_or_b32_e32 v46, 26, v20
	v_or_b32_e32 v48, 28, v20
	v_or_b32_e32 v50, 30, v20
	s_ashr_i32 s5, s4, 31
	v_ashrrev_i32_e32 v21, 31, v20
	v_or_b32_e32 v22, 2, v20
	v_or_b32_e32 v24, 4, v20
	v_or_b32_e32 v26, 6, v20
	v_or_b32_e32 v28, 8, v20
	v_or_b32_e32 v36, 16, v20
	v_or_b32_e32 v38, 18, v20
	v_or_b32_e32 v40, 20, v20
	v_or_b32_e32 v42, 22, v20
	v_or_b32_e32 v52, 32, v20
	v_or_b32_e32 v54, 34, v20
	v_or_b32_e32 v56, 36, v20
	v_or_b32_e32 v58, 38, v20
	v_or_b32_e32 v60, 40, v20
	v_or_b32_e32 v62, 42, v20
	v_or_b32_e32 v64, 44, v20
	v_or_b32_e32 v66, 46, v20
	v_or_b32_e32 v68, 48, v20
	v_or_b32_e32 v70, 50, v20
	v_or_b32_e32 v72, 52, v20
	v_or_b32_e32 v74, 54, v20
	v_or_b32_e32 v76, 56, v20
	v_or_b32_e32 v78, 58, v20
	v_or_b32_e32 v80, 60, v20
	v_or_b32_e32 v82, 62, v20
	v_ashrrev_i32_e32 v31, 31, v30
	v_ashrrev_i32_e32 v33, 31, v32
	v_ashrrev_i32_e32 v35, 31, v34
	v_ashrrev_i32_e32 v45, 31, v44
	v_ashrrev_i32_e32 v47, 31, v46
	v_ashrrev_i32_e32 v49, 31, v48
	v_ashrrev_i32_e32 v51, 31, v50
	v_lshl_add_u64 v[84:85], s[4:5], 2, v[4:5]
	v_lshlrev_b64 v[20:21], 12, v[20:21]
	v_ashrrev_i32_e32 v23, 31, v22
	v_ashrrev_i32_e32 v25, 31, v24
	v_ashrrev_i32_e32 v27, 31, v26
	v_ashrrev_i32_e32 v29, 31, v28
	v_ashrrev_i32_e32 v37, 31, v36
	v_ashrrev_i32_e32 v39, 31, v38
	v_ashrrev_i32_e32 v41, 31, v40
	v_ashrrev_i32_e32 v43, 31, v42
	v_ashrrev_i32_e32 v53, 31, v52
	v_ashrrev_i32_e32 v55, 31, v54
	v_ashrrev_i32_e32 v57, 31, v56
	v_ashrrev_i32_e32 v59, 31, v58
	v_ashrrev_i32_e32 v61, 31, v60
	v_ashrrev_i32_e32 v63, 31, v62
	v_ashrrev_i32_e32 v65, 31, v64
	v_ashrrev_i32_e32 v67, 31, v66
	v_ashrrev_i32_e32 v69, 31, v68
	v_ashrrev_i32_e32 v71, 31, v70
	v_ashrrev_i32_e32 v73, 31, v72
	v_ashrrev_i32_e32 v75, 31, v74
	v_ashrrev_i32_e32 v77, 31, v76
	v_ashrrev_i32_e32 v79, 31, v78
	v_ashrrev_i32_e32 v81, 31, v80
	v_ashrrev_i32_e32 v83, 31, v82
	v_lshlrev_b64 v[30:31], 12, v[30:31]
	v_lshlrev_b64 v[32:33], 12, v[32:33]
	v_lshlrev_b64 v[34:35], 12, v[34:35]
	v_lshlrev_b64 v[44:45], 12, v[44:45]
	v_lshlrev_b64 v[46:47], 12, v[46:47]
	v_lshlrev_b64 v[48:49], 12, v[48:49]
	v_lshlrev_b64 v[50:51], 12, v[50:51]
	v_lshl_add_u64 v[20:21], v[84:85], 0, v[20:21]
	v_lshlrev_b64 v[22:23], 12, v[22:23]
	v_lshlrev_b64 v[24:25], 12, v[24:25]
	v_lshlrev_b64 v[26:27], 12, v[26:27]
	v_lshlrev_b64 v[28:29], 12, v[28:29]
	v_lshlrev_b64 v[36:37], 12, v[36:37]
	v_lshlrev_b64 v[38:39], 12, v[38:39]
	v_lshlrev_b64 v[40:41], 12, v[40:41]
	v_lshlrev_b64 v[42:43], 12, v[42:43]
	v_lshlrev_b64 v[52:53], 12, v[52:53]
	v_lshlrev_b64 v[54:55], 12, v[54:55]
	v_lshlrev_b64 v[56:57], 12, v[56:57]
	v_lshlrev_b64 v[58:59], 12, v[58:59]
	v_lshlrev_b64 v[60:61], 12, v[60:61]
	v_lshlrev_b64 v[62:63], 12, v[62:63]
	v_lshlrev_b64 v[64:65], 12, v[64:65]
	v_lshlrev_b64 v[66:67], 12, v[66:67]
	v_lshlrev_b64 v[68:69], 12, v[68:69]
	v_lshlrev_b64 v[70:71], 12, v[70:71]
	v_lshlrev_b64 v[72:73], 12, v[72:73]
	v_lshlrev_b64 v[74:75], 12, v[74:75]
	v_lshlrev_b64 v[76:77], 12, v[76:77]
	v_lshlrev_b64 v[78:79], 12, v[78:79]
	v_lshlrev_b64 v[80:81], 12, v[80:81]
	v_lshlrev_b64 v[82:83], 12, v[82:83]
	v_lshl_add_u64 v[30:31], v[84:85], 0, v[30:31]
	v_lshl_add_u64 v[32:33], v[84:85], 0, v[32:33]
	v_lshl_add_u64 v[34:35], v[84:85], 0, v[34:35]
	v_lshl_add_u64 v[44:45], v[84:85], 0, v[44:45]
	v_lshl_add_u64 v[46:47], v[84:85], 0, v[46:47]
	v_lshl_add_u64 v[48:49], v[84:85], 0, v[48:49]
	v_lshl_add_u64 v[50:51], v[84:85], 0, v[50:51]
	v_lshl_add_u64 v[22:23], v[84:85], 0, v[22:23]
	v_lshl_add_u64 v[24:25], v[84:85], 0, v[24:25]
	v_lshl_add_u64 v[26:27], v[84:85], 0, v[26:27]
	v_lshl_add_u64 v[28:29], v[84:85], 0, v[28:29]
	v_lshl_add_u64 v[36:37], v[84:85], 0, v[36:37]
	v_lshl_add_u64 v[38:39], v[84:85], 0, v[38:39]
	v_lshl_add_u64 v[40:41], v[84:85], 0, v[40:41]
	v_lshl_add_u64 v[42:43], v[84:85], 0, v[42:43]
	v_lshl_add_u64 v[52:53], v[84:85], 0, v[52:53]
	v_lshl_add_u64 v[54:55], v[84:85], 0, v[54:55]
	v_lshl_add_u64 v[56:57], v[84:85], 0, v[56:57]
	v_lshl_add_u64 v[58:59], v[84:85], 0, v[58:59]
	v_lshl_add_u64 v[60:61], v[84:85], 0, v[60:61]
	v_lshl_add_u64 v[62:63], v[84:85], 0, v[62:63]
	v_lshl_add_u64 v[64:65], v[84:85], 0, v[64:65]
	v_lshl_add_u64 v[66:67], v[84:85], 0, v[66:67]
	v_lshl_add_u64 v[68:69], v[84:85], 0, v[68:69]
	v_lshl_add_u64 v[70:71], v[84:85], 0, v[70:71]
	v_lshl_add_u64 v[72:73], v[84:85], 0, v[72:73]
	v_lshl_add_u64 v[74:75], v[84:85], 0, v[74:75]
	v_lshl_add_u64 v[76:77], v[84:85], 0, v[76:77]
	v_lshl_add_u64 v[78:79], v[84:85], 0, v[78:79]
	v_lshl_add_u64 v[80:81], v[84:85], 0, v[80:81]
	v_lshl_add_u64 v[82:83], v[84:85], 0, v[82:83]
	global_load_dword v19, v[20:21], off nt
	global_load_dword v84, v[22:23], off nt
	global_load_dword v85, v[24:25], off nt
	global_load_dword v86, v[26:27], off nt
	global_load_dword v87, v[28:29], off nt
	global_load_dword v88, v[30:31], off nt
	global_load_dword v89, v[32:33], off nt
	global_load_dword v90, v[34:35], off nt
	global_load_dword v91, v[36:37], off nt
	global_load_dword v92, v[38:39], off nt
	global_load_dword v93, v[40:41], off nt
	global_load_dword v94, v[42:43], off nt
	global_load_dword v95, v[44:45], off nt
	global_load_dword v96, v[46:47], off nt
	global_load_dword v97, v[48:49], off nt
	global_load_dword v30, v[50:51], off nt
	global_load_dword v31, v[52:53], off nt
	global_load_dword v32, v[54:55], off nt
	global_load_dword v33, v[56:57], off nt
	global_load_dword v34, v[58:59], off nt
	global_load_dword v35, v[60:61], off nt
	global_load_dword v44, v[62:63], off nt
	global_load_dword v45, v[64:65], off nt
	global_load_dword v46, v[66:67], off nt
	global_load_dword v47, v[68:69], off nt
	global_load_dword v48, v[70:71], off nt
	global_load_dword v49, v[72:73], off nt
	global_load_dword v98, v[74:75], off nt
	global_load_dword v99, v[76:77], off nt
	global_load_dword v100, v[78:79], off nt
	global_load_dword v50, v[80:81], off nt
	global_load_dword v51, v[82:83], off nt
	v_add_u32_e32 v22, s4, v9
	s_ashr_i32 s3, s2, 31
	v_ashrrev_i32_e32 v23, 31, v22
	v_add_u32_e32 v24, 8, v22
	v_add_u32_e32 v26, 16, v22
	v_add_u32_e32 v28, 24, v22
	v_lshl_add_u64 v[20:21], s[2:3], 1, v[6:7]
	v_lshlrev_b64 v[22:23], 12, v[22:23]
	v_ashrrev_i32_e32 v25, 31, v24
	v_ashrrev_i32_e32 v27, 31, v26
	v_ashrrev_i32_e32 v29, 31, v28
	v_lshl_add_u64 v[36:37], v[20:21], 0, v[22:23]
	v_lshlrev_b64 v[22:23], 12, v[24:25]
	v_lshlrev_b64 v[24:25], 12, v[26:27]
	v_lshlrev_b64 v[26:27], 12, v[28:29]
	s_waitcnt vmcnt(30)
	ds_write2_b32 v12, v19, v84 offset1:66
	s_waitcnt vmcnt(28)
	ds_write2_b32 v12, v85, v86 offset0:132 offset1:198
	s_waitcnt vmcnt(26)
	ds_write2_b32 v1, v87, v88 offset0:8 offset1:74
	s_waitcnt vmcnt(24)
	ds_write2_b32 v1, v89, v90 offset0:140 offset1:206
	s_waitcnt vmcnt(22)
	ds_write2_b32 v3, v91, v92 offset0:16 offset1:82
	s_waitcnt vmcnt(20)
	ds_write2_b32 v3, v93, v94 offset0:148 offset1:214
	s_waitcnt vmcnt(18)
	ds_write2_b32 v14, v95, v96 offset0:24 offset1:90
	s_waitcnt vmcnt(16)
	ds_write2_b32 v14, v97, v30 offset0:156 offset1:222
	s_waitcnt vmcnt(14)
	ds_write2_b32 v15, v31, v32 offset0:32 offset1:98
	s_waitcnt vmcnt(12)
	ds_write2_b32 v15, v33, v34 offset0:164 offset1:230
	s_waitcnt vmcnt(10)
	ds_write2_b32 v16, v35, v44 offset0:40 offset1:106
	s_waitcnt vmcnt(8)
	ds_write2_b32 v16, v45, v46 offset0:172 offset1:238
	s_waitcnt vmcnt(6)
	ds_write2_b32 v17, v47, v48 offset0:48 offset1:114
	s_waitcnt vmcnt(4)
	ds_write2_b32 v17, v49, v98 offset0:180 offset1:246
	s_waitcnt vmcnt(2)
	ds_write2_b32 v18, v99, v100 offset0:56 offset1:122
	s_waitcnt vmcnt(0)
	ds_write2_b32 v18, v50, v51 offset0:188 offset1:254
	s_waitcnt lgkmcnt(0)
	v_lshl_add_u64 v[40:41], v[20:21], 0, v[24:25]
	v_lshl_add_u64 v[42:43], v[20:21], 0, v[26:27]
	ds_read2_b32 v[24:25], v13 offset0:33 offset1:41
	ds_read2_b32 v[26:27], v13 offset1:8
	ds_read2_b32 v[28:29], v13 offset0:66 offset1:74
	ds_read2_b32 v[30:31], v13 offset0:99 offset1:107
	ds_read2_b32 v[32:33], v13 offset0:132 offset1:140
	ds_read2_b32 v[34:35], v13 offset0:165 offset1:173
	ds_read2_b32 v[44:45], v13 offset0:198 offset1:206
	ds_read2_b32 v[46:47], v13 offset0:231 offset1:239
	ds_read2_b32 v[48:49], v13 offset0:49 offset1:57
	ds_read2_b32 v[50:51], v13 offset0:16 offset1:24
	ds_read2_b32 v[52:53], v13 offset0:82 offset1:90
	ds_read2_b32 v[54:55], v13 offset0:115 offset1:123
	ds_read2_b32 v[56:57], v13 offset0:148 offset1:156
	ds_read2_b32 v[58:59], v13 offset0:181 offset1:189
	ds_read2_b32 v[60:61], v13 offset0:214 offset1:222
	ds_read2_b32 v[62:63], v13 offset0:247 offset1:255
	v_lshl_add_u64 v[38:39], v[20:21], 0, v[22:23]
	s_waitcnt lgkmcnt(14)
	v_cvt_pk_bf16_f32 v20, v26, v24
	s_waitcnt lgkmcnt(12)
	v_cvt_pk_bf16_f32 v21, v28, v30
	s_waitcnt lgkmcnt(10)
	v_cvt_pk_bf16_f32 v22, v32, v34
	s_waitcnt lgkmcnt(8)
	v_cvt_pk_bf16_f32 v23, v44, v46
	v_cvt_pk_bf16_f32 v24, v27, v25
	v_cvt_pk_bf16_f32 v25, v29, v31
	v_cvt_pk_bf16_f32 v26, v33, v35
	v_cvt_pk_bf16_f32 v27, v45, v47
	s_waitcnt lgkmcnt(6)
	v_cvt_pk_bf16_f32 v28, v50, v48
	s_waitcnt lgkmcnt(4)
	v_cvt_pk_bf16_f32 v29, v52, v54
	s_waitcnt lgkmcnt(2)
	v_cvt_pk_bf16_f32 v30, v56, v58
	s_waitcnt lgkmcnt(0)
	v_cvt_pk_bf16_f32 v31, v60, v62
	v_cvt_pk_bf16_f32 v32, v51, v49
	v_cvt_pk_bf16_f32 v33, v53, v55
	v_cvt_pk_bf16_f32 v34, v57, v59
	v_cvt_pk_bf16_f32 v35, v61, v63
	global_store_dwordx4 v[36:37], v[20:23], off
	global_store_dwordx4 v[38:39], v[24:27], off
	global_store_dwordx4 v[40:41], v[28:31], off
	global_store_dwordx4 v[42:43], v[32:35], off
	s_waitcnt lgkmcnt(0)
	s_add_i32 s13, s13, s14
	s_add_i32 s12, s12, s9
	s_cmpk_gt_i32 s13, 0x1ff
	s_cbranch_scc0 .LBB0_301
	s_load_dwordx2 s[2:3], s[0:1], 0x88
	v_mov_b32_e32 v1, 0
	v_lshlrev_b32_e32 v0, 2, v0
	v_lshlrev_b32_e32 v2, 1, v2
	v_mov_b32_e32 v3, v1
	s_waitcnt lgkmcnt(0)
	v_lshl_add_u64 v[4:5], s[2:3], 0, v[0:1]
	v_lshl_add_u64 v[6:7], s[10:11], 0, v[2:3]
	s_mov_b64 s[2:3], 0xd00800
	v_lshl_add_u64 v[6:7], v[6:7], 0, s[2:3]
	s_mov_b32 s12, s8
	s_mov_b32 s13, s6
.LBB0_303:
	s_ashr_i32 s2, s13, 31
	s_lshr_b32 s2, s2, 27
	s_add_i32 s2, s13, s2
	s_ashr_i32 s3, s2, 5
	s_lshl_b32 s2, s3, 6
	s_lshl_b32 s3, s3, 10
	v_or_b32_e32 v14, s2, v8
	s_sub_i32 s4, s12, s3
	v_or_b32_e32 v24, 10, v14
	v_or_b32_e32 v26, 12, v14
	v_or_b32_e32 v28, 14, v14
	v_or_b32_e32 v38, 24, v14
	v_or_b32_e32 v40, 26, v14
	v_or_b32_e32 v42, 28, v14
	v_or_b32_e32 v44, 30, v14
	s_ashr_i32 s5, s4, 31
	v_ashrrev_i32_e32 v15, 31, v14
	v_or_b32_e32 v16, 2, v14
	v_or_b32_e32 v18, 4, v14
	v_or_b32_e32 v20, 6, v14
	v_or_b32_e32 v22, 8, v14
	v_or_b32_e32 v30, 16, v14
	v_or_b32_e32 v32, 18, v14
	v_or_b32_e32 v34, 20, v14
	v_or_b32_e32 v36, 22, v14
	v_or_b32_e32 v46, 32, v14
	v_or_b32_e32 v48, 34, v14
	v_or_b32_e32 v50, 36, v14
	v_or_b32_e32 v52, 38, v14
	v_or_b32_e32 v54, 40, v14
	v_or_b32_e32 v56, 42, v14
	v_or_b32_e32 v58, 44, v14
	v_or_b32_e32 v60, 46, v14
	v_or_b32_e32 v62, 48, v14
	v_or_b32_e32 v64, 50, v14
	v_or_b32_e32 v66, 52, v14
	v_or_b32_e32 v68, 54, v14
	v_or_b32_e32 v70, 56, v14
	v_or_b32_e32 v72, 58, v14
	v_or_b32_e32 v74, 60, v14
	v_or_b32_e32 v76, 62, v14
	v_ashrrev_i32_e32 v25, 31, v24
	v_ashrrev_i32_e32 v27, 31, v26
	v_ashrrev_i32_e32 v29, 31, v28
	v_ashrrev_i32_e32 v39, 31, v38
	v_ashrrev_i32_e32 v41, 31, v40
	v_ashrrev_i32_e32 v43, 31, v42
	v_ashrrev_i32_e32 v45, 31, v44
	v_lshl_add_u64 v[78:79], s[4:5], 2, v[4:5]
	v_lshlrev_b64 v[14:15], 12, v[14:15]
	v_ashrrev_i32_e32 v17, 31, v16
	v_ashrrev_i32_e32 v19, 31, v18
	v_ashrrev_i32_e32 v21, 31, v20
	v_ashrrev_i32_e32 v23, 31, v22
	v_ashrrev_i32_e32 v31, 31, v30
	v_ashrrev_i32_e32 v33, 31, v32
	v_ashrrev_i32_e32 v35, 31, v34
	v_ashrrev_i32_e32 v37, 31, v36
	v_ashrrev_i32_e32 v47, 31, v46
	v_ashrrev_i32_e32 v49, 31, v48
	v_ashrrev_i32_e32 v51, 31, v50
	v_ashrrev_i32_e32 v53, 31, v52
	v_ashrrev_i32_e32 v55, 31, v54
	v_ashrrev_i32_e32 v57, 31, v56
	v_ashrrev_i32_e32 v59, 31, v58
	v_ashrrev_i32_e32 v61, 31, v60
	v_ashrrev_i32_e32 v63, 31, v62
	v_ashrrev_i32_e32 v65, 31, v64
	v_ashrrev_i32_e32 v67, 31, v66
	v_ashrrev_i32_e32 v69, 31, v68
	v_ashrrev_i32_e32 v71, 31, v70
	v_ashrrev_i32_e32 v73, 31, v72
	v_ashrrev_i32_e32 v75, 31, v74
	v_ashrrev_i32_e32 v77, 31, v76
	v_lshlrev_b64 v[24:25], 12, v[24:25]
	v_lshlrev_b64 v[26:27], 12, v[26:27]
	v_lshlrev_b64 v[28:29], 12, v[28:29]
	v_lshlrev_b64 v[38:39], 12, v[38:39]
	v_lshlrev_b64 v[40:41], 12, v[40:41]
	v_lshlrev_b64 v[42:43], 12, v[42:43]
	v_lshlrev_b64 v[44:45], 12, v[44:45]
	v_lshl_add_u64 v[14:15], v[78:79], 0, v[14:15]
	v_lshlrev_b64 v[16:17], 12, v[16:17]
	v_lshlrev_b64 v[18:19], 12, v[18:19]
	v_lshlrev_b64 v[20:21], 12, v[20:21]
	v_lshlrev_b64 v[22:23], 12, v[22:23]
	v_lshlrev_b64 v[30:31], 12, v[30:31]
	v_lshlrev_b64 v[32:33], 12, v[32:33]
	v_lshlrev_b64 v[34:35], 12, v[34:35]
	v_lshlrev_b64 v[36:37], 12, v[36:37]
	v_lshlrev_b64 v[46:47], 12, v[46:47]
	v_lshlrev_b64 v[48:49], 12, v[48:49]
	v_lshlrev_b64 v[50:51], 12, v[50:51]
	v_lshlrev_b64 v[52:53], 12, v[52:53]
	v_lshlrev_b64 v[54:55], 12, v[54:55]
	v_lshlrev_b64 v[56:57], 12, v[56:57]
	v_lshlrev_b64 v[58:59], 12, v[58:59]
	v_lshlrev_b64 v[60:61], 12, v[60:61]
	v_lshlrev_b64 v[62:63], 12, v[62:63]
	v_lshlrev_b64 v[64:65], 12, v[64:65]
	v_lshlrev_b64 v[66:67], 12, v[66:67]
	v_lshlrev_b64 v[68:69], 12, v[68:69]
	v_lshlrev_b64 v[70:71], 12, v[70:71]
	v_lshlrev_b64 v[72:73], 12, v[72:73]
	v_lshlrev_b64 v[74:75], 12, v[74:75]
	v_lshlrev_b64 v[76:77], 12, v[76:77]
	v_lshl_add_u64 v[24:25], v[78:79], 0, v[24:25]
	v_lshl_add_u64 v[26:27], v[78:79], 0, v[26:27]
	v_lshl_add_u64 v[28:29], v[78:79], 0, v[28:29]
	v_lshl_add_u64 v[38:39], v[78:79], 0, v[38:39]
	v_lshl_add_u64 v[40:41], v[78:79], 0, v[40:41]
	v_lshl_add_u64 v[42:43], v[78:79], 0, v[42:43]
	v_lshl_add_u64 v[44:45], v[78:79], 0, v[44:45]
	v_lshl_add_u64 v[16:17], v[78:79], 0, v[16:17]
	v_lshl_add_u64 v[18:19], v[78:79], 0, v[18:19]
	v_lshl_add_u64 v[20:21], v[78:79], 0, v[20:21]
	v_lshl_add_u64 v[22:23], v[78:79], 0, v[22:23]
	v_lshl_add_u64 v[30:31], v[78:79], 0, v[30:31]
	v_lshl_add_u64 v[32:33], v[78:79], 0, v[32:33]
	v_lshl_add_u64 v[34:35], v[78:79], 0, v[34:35]
	v_lshl_add_u64 v[36:37], v[78:79], 0, v[36:37]
	v_lshl_add_u64 v[46:47], v[78:79], 0, v[46:47]
	v_lshl_add_u64 v[48:49], v[78:79], 0, v[48:49]
	v_lshl_add_u64 v[50:51], v[78:79], 0, v[50:51]
	v_lshl_add_u64 v[52:53], v[78:79], 0, v[52:53]
	v_lshl_add_u64 v[54:55], v[78:79], 0, v[54:55]
	v_lshl_add_u64 v[56:57], v[78:79], 0, v[56:57]
	v_lshl_add_u64 v[58:59], v[78:79], 0, v[58:59]
	v_lshl_add_u64 v[60:61], v[78:79], 0, v[60:61]
	v_lshl_add_u64 v[62:63], v[78:79], 0, v[62:63]
	v_lshl_add_u64 v[64:65], v[78:79], 0, v[64:65]
	v_lshl_add_u64 v[66:67], v[78:79], 0, v[66:67]
	v_lshl_add_u64 v[68:69], v[78:79], 0, v[68:69]
	v_lshl_add_u64 v[70:71], v[78:79], 0, v[70:71]
	v_lshl_add_u64 v[72:73], v[78:79], 0, v[72:73]
	v_lshl_add_u64 v[74:75], v[78:79], 0, v[74:75]
	v_lshl_add_u64 v[76:77], v[78:79], 0, v[76:77]
	global_load_dword v1, v[14:15], off nt
	global_load_dword v3, v[16:17], off nt
	global_load_dword v78, v[18:19], off nt
	global_load_dword v79, v[20:21], off nt
	global_load_dword v80, v[22:23], off nt
	global_load_dword v81, v[24:25], off nt
	global_load_dword v82, v[26:27], off nt
	global_load_dword v83, v[28:29], off nt
	global_load_dword v84, v[30:31], off nt
	global_load_dword v85, v[32:33], off nt
	global_load_dword v86, v[34:35], off nt
	global_load_dword v87, v[36:37], off nt
	global_load_dword v88, v[38:39], off nt
	global_load_dword v89, v[40:41], off nt
	global_load_dword v90, v[42:43], off nt
	global_load_dword v24, v[44:45], off nt
	global_load_dword v25, v[46:47], off nt
	global_load_dword v26, v[48:49], off nt
	global_load_dword v27, v[50:51], off nt
	global_load_dword v28, v[52:53], off nt
	global_load_dword v29, v[54:55], off nt
	global_load_dword v38, v[56:57], off nt
	global_load_dword v39, v[58:59], off nt
	global_load_dword v40, v[60:61], off nt
	global_load_dword v41, v[62:63], off nt
	global_load_dword v42, v[64:65], off nt
	global_load_dword v43, v[66:67], off nt
	global_load_dword v91, v[68:69], off nt
	global_load_dword v92, v[70:71], off nt
	global_load_dword v93, v[72:73], off nt
	global_load_dword v44, v[74:75], off nt
	global_load_dword v45, v[76:77], off nt
	v_add_u32_e32 v16, s4, v9
	s_ashr_i32 s3, s2, 31
	v_ashrrev_i32_e32 v17, 31, v16
	v_add_u32_e32 v18, 8, v16
	v_add_u32_e32 v20, 16, v16
	v_add_u32_e32 v22, 24, v16
	v_lshl_add_u64 v[14:15], s[2:3], 1, v[6:7]
	v_lshlrev_b64 v[16:17], 12, v[16:17]
	v_ashrrev_i32_e32 v19, 31, v18
	v_ashrrev_i32_e32 v21, 31, v20
	v_ashrrev_i32_e32 v23, 31, v22
	v_add_u32_e32 v46, 0x400, v12
	v_add_u32_e32 v47, 0x800, v12
	v_add_u32_e32 v48, 0xc00, v12
	v_add_u32_e32 v49, 0x1000, v12
	v_add_u32_e32 v50, 0x1400, v12
	v_add_u32_e32 v51, 0x1800, v12
	v_add_u32_e32 v52, 0x1c00, v12
	v_lshl_add_u64 v[30:31], v[14:15], 0, v[16:17]
	v_lshlrev_b64 v[16:17], 12, v[18:19]
	v_lshlrev_b64 v[18:19], 12, v[20:21]
	v_lshlrev_b64 v[20:21], 12, v[22:23]
	s_waitcnt vmcnt(30)
	ds_write2_b32 v12, v1, v3 offset1:66
	s_waitcnt vmcnt(28)
	ds_write2_b32 v12, v78, v79 offset0:132 offset1:198
	s_waitcnt vmcnt(26)
	ds_write2_b32 v46, v80, v81 offset0:8 offset1:74
	s_waitcnt vmcnt(24)
	ds_write2_b32 v46, v82, v83 offset0:140 offset1:206
	s_waitcnt vmcnt(22)
	ds_write2_b32 v47, v84, v85 offset0:16 offset1:82
	s_waitcnt vmcnt(20)
	ds_write2_b32 v47, v86, v87 offset0:148 offset1:214
	s_waitcnt vmcnt(18)
	ds_write2_b32 v48, v88, v89 offset0:24 offset1:90
	s_waitcnt vmcnt(16)
	ds_write2_b32 v48, v90, v24 offset0:156 offset1:222
	s_waitcnt vmcnt(14)
	ds_write2_b32 v49, v25, v26 offset0:32 offset1:98
	s_waitcnt vmcnt(12)
	ds_write2_b32 v49, v27, v28 offset0:164 offset1:230
	s_waitcnt vmcnt(10)
	ds_write2_b32 v50, v29, v38 offset0:40 offset1:106
	s_waitcnt vmcnt(8)
	ds_write2_b32 v50, v39, v40 offset0:172 offset1:238
	s_waitcnt vmcnt(6)
	ds_write2_b32 v51, v41, v42 offset0:48 offset1:114
	s_waitcnt vmcnt(4)
	ds_write2_b32 v51, v43, v91 offset0:180 offset1:246
	s_waitcnt vmcnt(2)
	ds_write2_b32 v52, v92, v93 offset0:56 offset1:122
	s_waitcnt vmcnt(0)
	ds_write2_b32 v52, v44, v45 offset0:188 offset1:254
	s_waitcnt lgkmcnt(0)
	v_lshl_add_u64 v[34:35], v[14:15], 0, v[18:19]
	v_lshl_add_u64 v[36:37], v[14:15], 0, v[20:21]
	ds_read2_b32 v[18:19], v13 offset0:33 offset1:41
	ds_read2_b32 v[20:21], v13 offset1:8
	ds_read2_b32 v[22:23], v13 offset0:66 offset1:74
	ds_read2_b32 v[24:25], v13 offset0:99 offset1:107
	ds_read2_b32 v[26:27], v13 offset0:132 offset1:140
	ds_read2_b32 v[28:29], v13 offset0:165 offset1:173
	ds_read2_b32 v[38:39], v13 offset0:198 offset1:206
	ds_read2_b32 v[40:41], v13 offset0:231 offset1:239
	ds_read2_b32 v[42:43], v13 offset0:49 offset1:57
	ds_read2_b32 v[44:45], v13 offset0:16 offset1:24
	ds_read2_b32 v[46:47], v13 offset0:82 offset1:90
	ds_read2_b32 v[48:49], v13 offset0:115 offset1:123
	ds_read2_b32 v[50:51], v13 offset0:148 offset1:156
	ds_read2_b32 v[52:53], v13 offset0:181 offset1:189
	ds_read2_b32 v[54:55], v13 offset0:214 offset1:222
	ds_read2_b32 v[56:57], v13 offset0:247 offset1:255
	v_lshl_add_u64 v[32:33], v[14:15], 0, v[16:17]
	s_waitcnt lgkmcnt(14)
	v_cvt_pk_bf16_f32 v14, v20, v18
	s_waitcnt lgkmcnt(12)
	v_cvt_pk_bf16_f32 v15, v22, v24
	s_waitcnt lgkmcnt(10)
	v_cvt_pk_bf16_f32 v16, v26, v28
	s_waitcnt lgkmcnt(8)
	v_cvt_pk_bf16_f32 v17, v38, v40
	v_cvt_pk_bf16_f32 v18, v21, v19
	v_cvt_pk_bf16_f32 v19, v23, v25
	v_cvt_pk_bf16_f32 v20, v27, v29
	v_cvt_pk_bf16_f32 v21, v39, v41
	s_waitcnt lgkmcnt(6)
	v_cvt_pk_bf16_f32 v22, v44, v42
	s_waitcnt lgkmcnt(4)
	v_cvt_pk_bf16_f32 v23, v46, v48
	s_waitcnt lgkmcnt(2)
	v_cvt_pk_bf16_f32 v24, v50, v52
	s_waitcnt lgkmcnt(0)
	v_cvt_pk_bf16_f32 v25, v54, v56
	v_cvt_pk_bf16_f32 v26, v45, v43
	v_cvt_pk_bf16_f32 v27, v47, v49
	v_cvt_pk_bf16_f32 v28, v51, v53
	v_cvt_pk_bf16_f32 v29, v55, v57
	global_store_dwordx4 v[30:31], v[14:17], off
	global_store_dwordx4 v[32:33], v[18:21], off
	global_store_dwordx4 v[34:35], v[22:25], off
	global_store_dwordx4 v[36:37], v[26:29], off
	s_waitcnt lgkmcnt(0)
	s_add_i32 s13, s13, s14
	s_add_i32 s12, s12, s9
	s_cmpk_gt_i32 s13, 0x1ff
	s_cbranch_scc0 .LBB0_303
	s_load_dwordx2 s[2:3], s[0:1], 0x90
	v_mov_b32_e32 v1, 0
	v_mov_b32_e32 v3, v1
	v_lshl_add_u64 v[2:3], s[10:11], 0, v[2:3]
	s_mov_b32 s12, s6
	s_waitcnt lgkmcnt(0)
	v_lshl_add_u64 v[0:1], s[2:3], 0, v[0:1]
	s_mov_b64 s[2:3], 0x1100000
	v_lshl_add_u64 v[2:3], v[2:3], 0, s[2:3]
.LBB0_305:
	s_ashr_i32 s2, s12, 31
	s_lshr_b32 s2, s2, 27
	s_add_i32 s2, s12, s2
	s_ashr_i32 s3, s2, 5
	s_lshl_b32 s2, s3, 6
	s_lshl_b32 s3, s3, 10
	v_or_b32_e32 v4, s2, v8
	s_sub_i32 s4, s8, s3
	v_or_b32_e32 v20, 10, v4
	v_or_b32_e32 v22, 12, v4
	v_or_b32_e32 v24, 14, v4
	v_or_b32_e32 v34, 24, v4
	v_or_b32_e32 v36, 26, v4
	v_or_b32_e32 v38, 28, v4
	v_or_b32_e32 v40, 30, v4
	s_ashr_i32 s5, s4, 31
	v_ashrrev_i32_e32 v5, 31, v4
	v_or_b32_e32 v6, 2, v4
	v_or_b32_e32 v14, 4, v4
	v_or_b32_e32 v16, 6, v4
	v_or_b32_e32 v18, 8, v4
	v_or_b32_e32 v26, 16, v4
	v_or_b32_e32 v28, 18, v4
	v_or_b32_e32 v30, 20, v4
	v_or_b32_e32 v32, 22, v4
	v_or_b32_e32 v42, 32, v4
	v_or_b32_e32 v44, 34, v4
	v_or_b32_e32 v46, 36, v4
	v_or_b32_e32 v48, 38, v4
	v_or_b32_e32 v50, 40, v4
	v_or_b32_e32 v52, 42, v4
	v_or_b32_e32 v54, 44, v4
	v_or_b32_e32 v56, 46, v4
	v_or_b32_e32 v58, 48, v4
	v_or_b32_e32 v60, 50, v4
	v_or_b32_e32 v62, 52, v4
	v_or_b32_e32 v64, 54, v4
	v_or_b32_e32 v66, 56, v4
	v_or_b32_e32 v68, 58, v4
	v_or_b32_e32 v70, 60, v4
	v_or_b32_e32 v72, 62, v4
	v_ashrrev_i32_e32 v21, 31, v20
	v_ashrrev_i32_e32 v23, 31, v22
	v_ashrrev_i32_e32 v25, 31, v24
	v_ashrrev_i32_e32 v35, 31, v34
	v_ashrrev_i32_e32 v37, 31, v36
	v_ashrrev_i32_e32 v39, 31, v38
	v_ashrrev_i32_e32 v41, 31, v40
	v_lshl_add_u64 v[74:75], s[4:5], 2, v[0:1]
	v_lshlrev_b64 v[4:5], 12, v[4:5]
	v_ashrrev_i32_e32 v7, 31, v6
	v_ashrrev_i32_e32 v15, 31, v14
	v_ashrrev_i32_e32 v17, 31, v16
	v_ashrrev_i32_e32 v19, 31, v18
	v_ashrrev_i32_e32 v27, 31, v26
	v_ashrrev_i32_e32 v29, 31, v28
	v_ashrrev_i32_e32 v31, 31, v30
	v_ashrrev_i32_e32 v33, 31, v32
	v_ashrrev_i32_e32 v43, 31, v42
	v_ashrrev_i32_e32 v45, 31, v44
	v_ashrrev_i32_e32 v47, 31, v46
	v_ashrrev_i32_e32 v49, 31, v48
	v_ashrrev_i32_e32 v51, 31, v50
	v_ashrrev_i32_e32 v53, 31, v52
	v_ashrrev_i32_e32 v55, 31, v54
	v_ashrrev_i32_e32 v57, 31, v56
	v_ashrrev_i32_e32 v59, 31, v58
	v_ashrrev_i32_e32 v61, 31, v60
	v_ashrrev_i32_e32 v63, 31, v62
	v_ashrrev_i32_e32 v65, 31, v64
	v_ashrrev_i32_e32 v67, 31, v66
	v_ashrrev_i32_e32 v69, 31, v68
	v_ashrrev_i32_e32 v71, 31, v70
	v_ashrrev_i32_e32 v73, 31, v72
	v_lshlrev_b64 v[20:21], 12, v[20:21]
	v_lshlrev_b64 v[22:23], 12, v[22:23]
	v_lshlrev_b64 v[24:25], 12, v[24:25]
	v_lshlrev_b64 v[34:35], 12, v[34:35]
	v_lshlrev_b64 v[36:37], 12, v[36:37]
	v_lshlrev_b64 v[38:39], 12, v[38:39]
	v_lshlrev_b64 v[40:41], 12, v[40:41]
	v_lshl_add_u64 v[4:5], v[74:75], 0, v[4:5]
	v_lshlrev_b64 v[6:7], 12, v[6:7]
	v_lshlrev_b64 v[14:15], 12, v[14:15]
	v_lshlrev_b64 v[16:17], 12, v[16:17]
	v_lshlrev_b64 v[18:19], 12, v[18:19]
	v_lshlrev_b64 v[26:27], 12, v[26:27]
	v_lshlrev_b64 v[28:29], 12, v[28:29]
	v_lshlrev_b64 v[30:31], 12, v[30:31]
	v_lshlrev_b64 v[32:33], 12, v[32:33]
	v_lshlrev_b64 v[42:43], 12, v[42:43]
	v_lshlrev_b64 v[44:45], 12, v[44:45]
	v_lshlrev_b64 v[46:47], 12, v[46:47]
	v_lshlrev_b64 v[48:49], 12, v[48:49]
	v_lshlrev_b64 v[50:51], 12, v[50:51]
	v_lshlrev_b64 v[52:53], 12, v[52:53]
	v_lshlrev_b64 v[54:55], 12, v[54:55]
	v_lshlrev_b64 v[56:57], 12, v[56:57]
	v_lshlrev_b64 v[58:59], 12, v[58:59]
	v_lshlrev_b64 v[60:61], 12, v[60:61]
	v_lshlrev_b64 v[62:63], 12, v[62:63]
	v_lshlrev_b64 v[64:65], 12, v[64:65]
	v_lshlrev_b64 v[66:67], 12, v[66:67]
	v_lshlrev_b64 v[68:69], 12, v[68:69]
	v_lshlrev_b64 v[70:71], 12, v[70:71]
	v_lshlrev_b64 v[72:73], 12, v[72:73]
	v_lshl_add_u64 v[20:21], v[74:75], 0, v[20:21]
	v_lshl_add_u64 v[22:23], v[74:75], 0, v[22:23]
	v_lshl_add_u64 v[24:25], v[74:75], 0, v[24:25]
	v_lshl_add_u64 v[34:35], v[74:75], 0, v[34:35]
	v_lshl_add_u64 v[36:37], v[74:75], 0, v[36:37]
	v_lshl_add_u64 v[38:39], v[74:75], 0, v[38:39]
	v_lshl_add_u64 v[40:41], v[74:75], 0, v[40:41]
	v_lshl_add_u64 v[6:7], v[74:75], 0, v[6:7]
	v_lshl_add_u64 v[14:15], v[74:75], 0, v[14:15]
	v_lshl_add_u64 v[16:17], v[74:75], 0, v[16:17]
	v_lshl_add_u64 v[18:19], v[74:75], 0, v[18:19]
	v_lshl_add_u64 v[26:27], v[74:75], 0, v[26:27]
	v_lshl_add_u64 v[28:29], v[74:75], 0, v[28:29]
	v_lshl_add_u64 v[30:31], v[74:75], 0, v[30:31]
	v_lshl_add_u64 v[32:33], v[74:75], 0, v[32:33]
	v_lshl_add_u64 v[42:43], v[74:75], 0, v[42:43]
	v_lshl_add_u64 v[44:45], v[74:75], 0, v[44:45]
	v_lshl_add_u64 v[46:47], v[74:75], 0, v[46:47]
	v_lshl_add_u64 v[48:49], v[74:75], 0, v[48:49]
	v_lshl_add_u64 v[50:51], v[74:75], 0, v[50:51]
	v_lshl_add_u64 v[52:53], v[74:75], 0, v[52:53]
	v_lshl_add_u64 v[54:55], v[74:75], 0, v[54:55]
	v_lshl_add_u64 v[56:57], v[74:75], 0, v[56:57]
	v_lshl_add_u64 v[58:59], v[74:75], 0, v[58:59]
	v_lshl_add_u64 v[60:61], v[74:75], 0, v[60:61]
	v_lshl_add_u64 v[62:63], v[74:75], 0, v[62:63]
	v_lshl_add_u64 v[64:65], v[74:75], 0, v[64:65]
	v_lshl_add_u64 v[66:67], v[74:75], 0, v[66:67]
	v_lshl_add_u64 v[68:69], v[74:75], 0, v[68:69]
	v_lshl_add_u64 v[70:71], v[74:75], 0, v[70:71]
	v_lshl_add_u64 v[72:73], v[74:75], 0, v[72:73]
	global_load_dword v74, v[4:5], off nt
	global_load_dword v75, v[6:7], off nt
	global_load_dword v76, v[14:15], off nt
	global_load_dword v77, v[16:17], off nt
	global_load_dword v78, v[18:19], off nt
	global_load_dword v79, v[20:21], off nt
	global_load_dword v80, v[22:23], off nt
	global_load_dword v81, v[24:25], off nt
	global_load_dword v82, v[26:27], off nt
	global_load_dword v83, v[28:29], off nt
	global_load_dword v84, v[30:31], off nt
	global_load_dword v85, v[32:33], off nt
	global_load_dword v86, v[34:35], off nt
	global_load_dword v87, v[36:37], off nt
	global_load_dword v88, v[38:39], off nt
	global_load_dword v20, v[40:41], off nt
	global_load_dword v21, v[42:43], off nt
	global_load_dword v22, v[44:45], off nt
	global_load_dword v23, v[46:47], off nt
	global_load_dword v24, v[48:49], off nt
	global_load_dword v25, v[50:51], off nt
	global_load_dword v34, v[52:53], off nt
	global_load_dword v35, v[54:55], off nt
	global_load_dword v36, v[56:57], off nt
	global_load_dword v37, v[58:59], off nt
	global_load_dword v38, v[60:61], off nt
	global_load_dword v39, v[62:63], off nt
	global_load_dword v89, v[64:65], off nt
	global_load_dword v90, v[66:67], off nt
	global_load_dword v91, v[68:69], off nt
	global_load_dword v40, v[70:71], off nt
	global_load_dword v41, v[72:73], off nt
	v_add_u32_e32 v6, s4, v9
	s_ashr_i32 s3, s2, 31
	v_ashrrev_i32_e32 v7, 31, v6
	v_add_u32_e32 v14, 8, v6
	v_add_u32_e32 v16, 16, v6
	v_add_u32_e32 v18, 24, v6
	v_lshl_add_u64 v[4:5], s[2:3], 1, v[2:3]
	v_lshlrev_b64 v[6:7], 11, v[6:7]
	v_ashrrev_i32_e32 v15, 31, v14
	v_ashrrev_i32_e32 v17, 31, v16
	v_ashrrev_i32_e32 v19, 31, v18
	v_add_u32_e32 v42, 0x400, v12
	v_add_u32_e32 v43, 0x800, v12
	v_add_u32_e32 v44, 0xc00, v12
	v_add_u32_e32 v45, 0x1000, v12
	v_add_u32_e32 v46, 0x1400, v12
	v_add_u32_e32 v47, 0x1800, v12
	v_add_u32_e32 v48, 0x1c00, v12
	v_lshl_add_u64 v[26:27], v[4:5], 0, v[6:7]
	v_lshlrev_b64 v[6:7], 11, v[14:15]
	v_lshlrev_b64 v[14:15], 11, v[16:17]
	v_lshlrev_b64 v[16:17], 11, v[18:19]
	s_waitcnt vmcnt(30)
	ds_write2_b32 v12, v74, v75 offset1:66
	s_waitcnt vmcnt(28)
	ds_write2_b32 v12, v76, v77 offset0:132 offset1:198
	s_waitcnt vmcnt(26)
	ds_write2_b32 v42, v78, v79 offset0:8 offset1:74
	s_waitcnt vmcnt(24)
	ds_write2_b32 v42, v80, v81 offset0:140 offset1:206
	s_waitcnt vmcnt(22)
	ds_write2_b32 v43, v82, v83 offset0:16 offset1:82
	s_waitcnt vmcnt(20)
	ds_write2_b32 v43, v84, v85 offset0:148 offset1:214
	s_waitcnt vmcnt(18)
	ds_write2_b32 v44, v86, v87 offset0:24 offset1:90
	s_waitcnt vmcnt(16)
	ds_write2_b32 v44, v88, v20 offset0:156 offset1:222
	s_waitcnt vmcnt(14)
	ds_write2_b32 v45, v21, v22 offset0:32 offset1:98
	s_waitcnt vmcnt(12)
	ds_write2_b32 v45, v23, v24 offset0:164 offset1:230
	s_waitcnt vmcnt(10)
	ds_write2_b32 v46, v25, v34 offset0:40 offset1:106
	s_waitcnt vmcnt(8)
	ds_write2_b32 v46, v35, v36 offset0:172 offset1:238
	s_waitcnt vmcnt(6)
	ds_write2_b32 v47, v37, v38 offset0:48 offset1:114
	s_waitcnt vmcnt(4)
	ds_write2_b32 v47, v39, v89 offset0:180 offset1:246
	s_waitcnt vmcnt(2)
	ds_write2_b32 v48, v90, v91 offset0:56 offset1:122
	s_waitcnt vmcnt(0)
	ds_write2_b32 v48, v40, v41 offset0:188 offset1:254
	s_waitcnt lgkmcnt(0)
	v_lshl_add_u64 v[30:31], v[4:5], 0, v[14:15]
	v_lshl_add_u64 v[32:33], v[4:5], 0, v[16:17]
	ds_read2_b32 v[14:15], v13 offset0:33 offset1:41
	ds_read2_b32 v[16:17], v13 offset1:8
	ds_read2_b32 v[18:19], v13 offset0:66 offset1:74
	ds_read2_b32 v[20:21], v13 offset0:99 offset1:107
	ds_read2_b32 v[22:23], v13 offset0:132 offset1:140
	ds_read2_b32 v[24:25], v13 offset0:165 offset1:173
	ds_read2_b32 v[34:35], v13 offset0:198 offset1:206
	ds_read2_b32 v[36:37], v13 offset0:231 offset1:239
	ds_read2_b32 v[38:39], v13 offset0:49 offset1:57
	ds_read2_b32 v[40:41], v13 offset0:16 offset1:24
	ds_read2_b32 v[42:43], v13 offset0:82 offset1:90
	ds_read2_b32 v[44:45], v13 offset0:115 offset1:123
	ds_read2_b32 v[46:47], v13 offset0:148 offset1:156
	ds_read2_b32 v[48:49], v13 offset0:181 offset1:189
	ds_read2_b32 v[50:51], v13 offset0:214 offset1:222
	ds_read2_b32 v[52:53], v13 offset0:247 offset1:255
	v_lshl_add_u64 v[28:29], v[4:5], 0, v[6:7]
	s_waitcnt lgkmcnt(14)
	v_cvt_pk_bf16_f32 v4, v16, v14
	s_waitcnt lgkmcnt(12)
	v_cvt_pk_bf16_f32 v5, v18, v20
	s_waitcnt lgkmcnt(10)
	v_cvt_pk_bf16_f32 v6, v22, v24
	s_waitcnt lgkmcnt(8)
	v_cvt_pk_bf16_f32 v7, v34, v36
	v_cvt_pk_bf16_f32 v14, v17, v15
	v_cvt_pk_bf16_f32 v15, v19, v21
	v_cvt_pk_bf16_f32 v16, v23, v25
	v_cvt_pk_bf16_f32 v17, v35, v37
	s_waitcnt lgkmcnt(6)
	v_cvt_pk_bf16_f32 v18, v40, v38
	s_waitcnt lgkmcnt(4)
	v_cvt_pk_bf16_f32 v19, v42, v44
	s_waitcnt lgkmcnt(2)
	v_cvt_pk_bf16_f32 v20, v46, v48
	s_waitcnt lgkmcnt(0)
	v_cvt_pk_bf16_f32 v21, v50, v52
	v_cvt_pk_bf16_f32 v22, v41, v39
	v_cvt_pk_bf16_f32 v23, v43, v45
	v_cvt_pk_bf16_f32 v24, v47, v49
	v_cvt_pk_bf16_f32 v25, v51, v53
	global_store_dwordx4 v[26:27], v[4:7], off
	global_store_dwordx4 v[28:29], v[14:17], off
	global_store_dwordx4 v[30:31], v[18:21], off
	global_store_dwordx4 v[32:33], v[22:25], off
	s_waitcnt lgkmcnt(0)
	s_add_i32 s12, s12, s14
	s_add_i32 s8, s8, s9
	s_cmpk_gt_i32 s12, 0x1ff
	s_cbranch_scc0 .LBB0_305

.LBB0_308:
	s_mul_hi_i32 s2, s6, 0x2e8ba2e9
	s_lshr_b32 s3, s2, 31
	s_ashr_i32 s2, s2, 5
	s_add_i32 s2, s2, s3
	s_mul_i32 s8, s2, 0xffffea00
	s_mul_i32 s3, s2, 0xffffff50
	s_add_i32 s10, s4, s8
	s_add_i32 s3, s6, s3
	s_add_i32 s8, s10, 0xfffff500
	s_cmpk_lt_i32 s3, 0x58
	s_cselect_b32 s3, s10, s8
	s_cselect_b32 s8, 0, 0x80
	s_lshl_b32 s2, s2, 6
	s_ashr_i32 s11, s10, 31
	v_or_b32_e32 v22, s2, v8
	v_lshl_add_u64 v[18:19], s[10:11], 2, v[0:1]
	v_or_b32_e32 v28, 8, v22
	v_or_b32_e32 v30, 10, v22
	v_or_b32_e32 v32, 12, v22
	v_or_b32_e32 v42, 22, v22
	v_or_b32_e32 v44, 24, v22
	v_or_b32_e32 v46, 26, v22
	v_or_b32_e32 v48, 28, v22
	v_or_b32_e32 v50, 30, v22
	v_mad_i64_i32 v[20:21], s[10:11], v22, s7, v[18:19]
	v_or_b32_e32 v23, 2, v22
	v_or_b32_e32 v24, 4, v22
	v_or_b32_e32 v26, 6, v22
	v_or_b32_e32 v34, 14, v22
	v_or_b32_e32 v36, 16, v22
	v_or_b32_e32 v38, 18, v22
	v_or_b32_e32 v40, 20, v22
	v_or_b32_e32 v52, 32, v22
	v_or_b32_e32 v54, 34, v22
	v_or_b32_e32 v56, 36, v22
	v_or_b32_e32 v58, 38, v22
	v_or_b32_e32 v60, 40, v22
	v_or_b32_e32 v62, 42, v22
	v_or_b32_e32 v64, 44, v22
	v_or_b32_e32 v66, 46, v22
	v_or_b32_e32 v68, 48, v22
	v_or_b32_e32 v70, 50, v22
	v_or_b32_e32 v72, 52, v22
	v_or_b32_e32 v74, 54, v22
	v_or_b32_e32 v76, 56, v22
	v_or_b32_e32 v78, 58, v22
	v_or_b32_e32 v80, 60, v22
	v_or_b32_e32 v82, 62, v22
	v_mad_i64_i32 v[28:29], s[10:11], v28, s7, v[18:19]
	v_mad_i64_i32 v[30:31], s[10:11], v30, s7, v[18:19]
	v_mad_i64_i32 v[32:33], s[10:11], v32, s7, v[18:19]
	v_mad_i64_i32 v[42:43], s[10:11], v42, s7, v[18:19]
	v_mad_i64_i32 v[44:45], s[10:11], v44, s7, v[18:19]
	v_mad_i64_i32 v[46:47], s[10:11], v46, s7, v[18:19]
	v_mad_i64_i32 v[48:49], s[10:11], v48, s7, v[18:19]
	v_mad_i64_i32 v[50:51], s[10:11], v50, s7, v[18:19]
	v_mad_i64_i32 v[22:23], s[10:11], v23, s7, v[18:19]
	v_mad_i64_i32 v[24:25], s[10:11], v24, s7, v[18:19]
	v_mad_i64_i32 v[26:27], s[10:11], v26, s7, v[18:19]
	v_mad_i64_i32 v[34:35], s[10:11], v34, s7, v[18:19]
	v_mad_i64_i32 v[36:37], s[10:11], v36, s7, v[18:19]
	v_mad_i64_i32 v[38:39], s[10:11], v38, s7, v[18:19]
	v_mad_i64_i32 v[40:41], s[10:11], v40, s7, v[18:19]
	v_mad_i64_i32 v[52:53], s[10:11], v52, s7, v[18:19]
	v_mad_i64_i32 v[54:55], s[10:11], v54, s7, v[18:19]
	v_mad_i64_i32 v[56:57], s[10:11], v56, s7, v[18:19]
	v_mad_i64_i32 v[58:59], s[10:11], v58, s7, v[18:19]
	v_mad_i64_i32 v[60:61], s[10:11], v60, s7, v[18:19]
	v_mad_i64_i32 v[62:63], s[10:11], v62, s7, v[18:19]
	v_mad_i64_i32 v[64:65], s[10:11], v64, s7, v[18:19]
	v_mad_i64_i32 v[66:67], s[10:11], v66, s7, v[18:19]
	v_mad_i64_i32 v[68:69], s[10:11], v68, s7, v[18:19]
	v_mad_i64_i32 v[70:71], s[10:11], v70, s7, v[18:19]
	v_mad_i64_i32 v[72:73], s[10:11], v72, s7, v[18:19]
	v_mad_i64_i32 v[74:75], s[10:11], v74, s7, v[18:19]
	v_mad_i64_i32 v[76:77], s[10:11], v76, s7, v[18:19]
	v_mad_i64_i32 v[78:79], s[10:11], v78, s7, v[18:19]
	v_mad_i64_i32 v[80:81], s[10:11], v80, s7, v[18:19]
	v_mad_i64_i32 v[18:19], s[10:11], v82, s7, v[18:19]
	global_load_dword v82, v[20:21], off nt
	global_load_dword v83, v[22:23], off nt
	global_load_dword v84, v[24:25], off nt
	global_load_dword v85, v[26:27], off nt
	global_load_dword v86, v[28:29], off nt
	global_load_dword v87, v[30:31], off nt
	global_load_dword v88, v[32:33], off nt
	global_load_dword v89, v[34:35], off nt
	global_load_dword v90, v[36:37], off nt
	global_load_dword v91, v[38:39], off nt
	global_load_dword v92, v[40:41], off nt
	global_load_dword v93, v[42:43], off nt
	global_load_dword v94, v[44:45], off nt
	global_load_dword v95, v[46:47], off nt
	global_load_dword v96, v[48:49], off nt
	global_load_dword v28, v[50:51], off nt
	global_load_dword v29, v[52:53], off nt
	global_load_dword v30, v[54:55], off nt
	global_load_dword v31, v[56:57], off nt
	global_load_dword v32, v[58:59], off nt
	global_load_dword v33, v[60:61], off nt
	global_load_dword v42, v[62:63], off nt
	global_load_dword v43, v[64:65], off nt
	global_load_dword v44, v[66:67], off nt
	global_load_dword v45, v[68:69], off nt
	global_load_dword v46, v[70:71], off nt
	global_load_dword v47, v[72:73], off nt
	global_load_dword v48, v[74:75], off nt
	global_load_dword v49, v[76:77], off nt
	global_load_dword v97, v[78:79], off nt
	global_load_dword v50, v[80:81], off nt
	global_load_dword v51, v[18:19], off nt
	s_lshl_b32 s9, s3, 1
	s_and_b32 s10, s3, 0x60
	s_ashr_i32 s3, s2, 31
	s_and_b32 s9, s9, 0xffffff00
	s_or_b32 s8, s10, s8
	v_lshl_add_u64 v[18:19], s[2:3], 1, v[2:3]
	s_or_b32 s2, s8, s9
	v_or_b32_e32 v22, s2, v6
	v_or_b32_e32 v24, s2, v7
	v_or_b32_e32 v26, s2, v10
	v_ashrrev_i32_e32 v23, 31, v22
	v_ashrrev_i32_e32 v25, 31, v24
	v_ashrrev_i32_e32 v27, 31, v26
	v_lshlrev_b64 v[22:23], 11, v[22:23]
	v_lshlrev_b64 v[24:25], 11, v[24:25]
	v_lshlrev_b64 v[26:27], 11, v[26:27]
	s_waitcnt vmcnt(30)
	ds_write2_b32 v4, v82, v83 offset1:66
	s_waitcnt vmcnt(28)
	ds_write2_b32 v4, v84, v85 offset0:132 offset1:198
	s_waitcnt vmcnt(26)
	ds_write2_b32 v11, v86, v87 offset0:8 offset1:74
	s_waitcnt vmcnt(24)
	ds_write2_b32 v11, v88, v89 offset0:140 offset1:206
	s_waitcnt vmcnt(22)
	ds_write2_b32 v12, v90, v91 offset0:16 offset1:82
	s_waitcnt vmcnt(20)
	ds_write2_b32 v12, v92, v93 offset0:148 offset1:214
	s_waitcnt vmcnt(18)
	ds_write2_b32 v13, v94, v95 offset0:24 offset1:90
	s_waitcnt vmcnt(16)
	ds_write2_b32 v13, v96, v28 offset0:156 offset1:222
	s_waitcnt vmcnt(14)
	ds_write2_b32 v14, v29, v30 offset0:32 offset1:98
	s_waitcnt vmcnt(12)
	ds_write2_b32 v14, v31, v32 offset0:164 offset1:230
	s_waitcnt vmcnt(10)
	ds_write2_b32 v15, v33, v42 offset0:40 offset1:106
	s_waitcnt vmcnt(8)
	ds_write2_b32 v15, v43, v44 offset0:172 offset1:238
	s_waitcnt vmcnt(6)
	ds_write2_b32 v16, v45, v46 offset0:48 offset1:114
	s_waitcnt vmcnt(4)
	ds_write2_b32 v16, v47, v48 offset0:180 offset1:246
	s_waitcnt vmcnt(2)
	ds_write2_b32 v17, v49, v97 offset0:56 offset1:122
	s_waitcnt vmcnt(0)
	ds_write2_b32 v17, v50, v51 offset0:188 offset1:254
	s_waitcnt lgkmcnt(0)
	v_lshl_add_u64 v[36:37], v[18:19], 0, v[22:23]
	v_lshl_add_u64 v[38:39], v[18:19], 0, v[24:25]
	v_lshl_add_u64 v[40:41], v[18:19], 0, v[26:27]
	ds_read2_b32 v[22:23], v5 offset0:33 offset1:41
	ds_read2_b32 v[24:25], v5 offset1:8
	ds_read2_b32 v[26:27], v5 offset0:66 offset1:74
	ds_read2_b32 v[28:29], v5 offset0:99 offset1:107
	ds_read2_b32 v[30:31], v5 offset0:132 offset1:140
	ds_read2_b32 v[32:33], v5 offset0:165 offset1:173
	ds_read2_b32 v[42:43], v5 offset0:198 offset1:206
	ds_read2_b32 v[44:45], v5 offset0:231 offset1:239
	ds_read2_b32 v[46:47], v5 offset0:49 offset1:57
	ds_read2_b32 v[48:49], v5 offset0:16 offset1:24
	ds_read2_b32 v[50:51], v5 offset0:82 offset1:90
	ds_read2_b32 v[52:53], v5 offset0:115 offset1:123
	ds_read2_b32 v[54:55], v5 offset0:148 offset1:156
	ds_read2_b32 v[56:57], v5 offset0:181 offset1:189
	ds_read2_b32 v[58:59], v5 offset0:214 offset1:222
	ds_read2_b32 v[60:61], v5 offset0:247 offset1:255
	v_or_b32_e32 v20, s2, v9
	v_ashrrev_i32_e32 v21, 31, v20
	v_lshlrev_b64 v[20:21], 11, v[20:21]
	v_lshl_add_u64 v[34:35], v[18:19], 0, v[20:21]
	s_waitcnt lgkmcnt(14)
	v_cvt_pk_bf16_f32 v18, v24, v22
	s_waitcnt lgkmcnt(12)
	v_cvt_pk_bf16_f32 v19, v26, v28
	s_waitcnt lgkmcnt(10)
	v_cvt_pk_bf16_f32 v20, v30, v32
	s_waitcnt lgkmcnt(8)
	v_cvt_pk_bf16_f32 v21, v42, v44
	v_cvt_pk_bf16_f32 v22, v25, v23
	v_cvt_pk_bf16_f32 v23, v27, v29
	v_cvt_pk_bf16_f32 v24, v31, v33
	v_cvt_pk_bf16_f32 v25, v43, v45
	s_waitcnt lgkmcnt(6)
	v_cvt_pk_bf16_f32 v26, v48, v46
	s_waitcnt lgkmcnt(4)
	v_cvt_pk_bf16_f32 v27, v50, v52
	s_waitcnt lgkmcnt(2)
	v_cvt_pk_bf16_f32 v28, v54, v56
	s_waitcnt lgkmcnt(0)
	v_cvt_pk_bf16_f32 v29, v58, v60
	v_cvt_pk_bf16_f32 v30, v49, v47
	v_cvt_pk_bf16_f32 v31, v51, v53
	v_cvt_pk_bf16_f32 v32, v55, v57
	v_cvt_pk_bf16_f32 v33, v59, v61
	global_store_dwordx4 v[34:35], v[18:21], off
	global_store_dwordx4 v[36:37], v[22:25], off
	global_store_dwordx4 v[38:39], v[26:29], off
	global_store_dwordx4 v[40:41], v[30:33], off
	s_waitcnt lgkmcnt(0)
	s_add_i32 s6, s6, s12
	s_add_i32 s4, s4, s5
	s_cmpk_gt_i32 s6, 0xaff
	s_cbranch_scc0 .LBB0_308

.LBB0_889:
	s_cmpk_lg_i32 s38, 0x800
	s_cbranch_scc1 .LBB0_888
	v_mov_b32_e32 v128, v192
	s_nop 0
	v_and_b32_e32 v129, 15, v128
	v_ashrrev_i32_e32 v130, 2, v128
	v_lshrrev_b32_e32 v128, 1, v128
	v_and_or_b32 v129, v130, s58, v129
	v_and_b32_e32 v128, 0x78, v128
	v_add_u32_e32 v140, s27, v129
	v_or_b32_e32 v128, s66, v128
	v_ashrrev_i32_e32 v141, 31, v140
	v_ashrrev_i32_e32 v129, 31, v128
	v_lshlrev_b64 v[130:131], 12, v[140:141]
	v_lshl_add_u64 v[130:131], s[2:3], 0, v[130:131]
	v_lshlrev_b64 v[142:143], 1, v[128:129]
	v_lshl_add_u64 v[168:169], v[130:131], 0, v[142:143]
	global_load_dwordx4 v[132:135], v[168:169], off offset:2048 nt
	global_load_dwordx4 v[144:147], v[168:169], off nt
	global_load_dwordx4 v[172:175], v[168:169], off offset:2304 nt
	global_load_dwordx4 v[176:179], v[168:169], off offset:256 nt
	v_or_b32_e32 v128, 16, v140
	v_ashrrev_i32_e32 v129, 31, v128
	v_lshlrev_b64 v[128:129], 12, v[128:129]
	v_lshl_add_u64 v[128:129], s[2:3], 0, v[128:129]
	v_lshl_add_u64 v[128:129], v[128:129], 0, v[142:143]
	global_load_dwordx4 v[180:183], v[128:129], off offset:2048 nt
	global_load_dwordx4 v[136:139], v[128:129], off nt
	v_or_b32_e32 v130, 32, v140
	v_ashrrev_i32_e32 v131, 31, v130
	v_lshlrev_b64 v[130:131], 12, v[130:131]
	v_lshl_add_u64 v[130:131], s[2:3], 0, v[130:131]
	v_lshl_add_u64 v[194:195], v[130:131], 0, v[142:143]
	global_load_dwordx4 v[184:187], v[128:129], off offset:256 nt
	global_load_dwordx4 v[188:191], v[128:129], off offset:2304 nt
	s_nop 0
	global_load_dwordx4 v[128:131], v[194:195], off offset:2048 nt
	s_waitcnt vmcnt(0)
	v_and_b32_e32 v198, 0xffff0000, v132
	v_lshlrev_b32_e32 v199, 16, v133
	v_and_b32_e32 v200, 0xffff0000, v133
	v_lshlrev_b32_e32 v201, 16, v134
	v_and_b32_e32 v202, 0xffff0000, v134
	v_lshlrev_b32_e32 v203, 16, v135
	v_and_b32_e32 v204, 0xffff0000, v135
	v_lshlrev_b32_e32 v205, 16, v172
	v_and_b32_e32 v206, 0xffff0000, v172
	v_lshlrev_b32_e32 v209, 16, v174
	v_and_b32_e32 v210, 0xffff0000, v174
	v_lshlrev_b32_e32 v211, 16, v175
	v_and_b32_e32 v212, 0xffff0000, v175
	v_lshlrev_b32_e32 v174, 16, v179
	v_and_b32_e32 v175, 0xffff0000, v179
	v_rcp_f32_e32 v179, v198
	v_rcp_f32_e32 v198, v199
	v_rcp_f32_e32 v199, v200
	v_rcp_f32_e32 v200, v201
	v_rcp_f32_e32 v201, v202
	v_rcp_f32_e32 v202, v203
	v_rcp_f32_e32 v203, v204
	v_rcp_f32_e32 v204, v205
	v_rcp_f32_e32 v205, v206
	v_lshlrev_b32_e32 v141, 16, v132
	v_lshlrev_b32_e32 v196, 16, v144
	v_and_b32_e32 v197, 0xffff0000, v144
	v_lshlrev_b32_e32 v132, 16, v145
	v_and_b32_e32 v133, 0xffff0000, v145
	v_lshlrev_b32_e32 v144, 16, v146
	v_and_b32_e32 v145, 0xffff0000, v146
	v_lshlrev_b32_e32 v134, 16, v147
	v_and_b32_e32 v135, 0xffff0000, v147
	v_lshlrev_b32_e32 v146, 16, v176
	v_and_b32_e32 v147, 0xffff0000, v176
	v_lshlrev_b32_e32 v207, 16, v173
	v_and_b32_e32 v208, 0xffff0000, v173
	v_rcp_f32_e32 v206, v207
	v_rcp_f32_e32 v207, v208
	v_rcp_f32_e32 v208, v209
	v_rcp_f32_e32 v209, v210
	v_rcp_f32_e32 v210, v211
	v_rcp_f32_e32 v211, v212
	v_pk_mul_f32 v[132:133], v[198:199], v[132:133]
	v_pk_mul_f32 v[134:135], v[202:203], v[134:135]
	v_pk_mul_f32 v[146:147], v[204:205], v[146:147]
	v_lshlrev_b32_e32 v172, 16, v177
	v_and_b32_e32 v173, 0xffff0000, v177
	v_lshlrev_b32_e32 v176, 16, v178
	v_and_b32_e32 v177, 0xffff0000, v178
	v_rcp_f32_e32 v178, v141
	v_pk_mul_f32 v[126:127], v[126:127], v[132:133]
	v_pk_mul_f32 v[122:123], v[122:123], v[134:135]
	v_pk_mul_f32 v[116:117], v[116:117], v[146:147]
	global_load_dwordx4 v[132:135], v[194:195], off nt
	v_lshlrev_b32_e32 v141, 16, v180
	v_and_b32_e32 v147, 0xffff0000, v180
	v_rcp_f32_e32 v146, v141
	v_rcp_f32_e32 v147, v147
	v_pk_mul_f32 v[144:145], v[200:201], v[144:145]
	v_and_b32_e32 v141, 0xffff0000, v181
	v_pk_mul_f32 v[120:121], v[120:121], v[144:145]
	v_pk_mul_f32 v[144:145], v[210:211], v[174:175]
	v_pk_mul_f32 v[172:173], v[206:207], v[172:173]
	v_pk_mul_f32 v[114:115], v[114:115], v[144:145]
	v_lshlrev_b32_e32 v144, 16, v136
	v_and_b32_e32 v145, 0xffff0000, v136
	v_lshlrev_b32_e32 v136, 16, v181
	v_pk_mul_f32 v[144:145], v[146:147], v[144:145]
	v_rcp_f32_e32 v146, v136
	v_rcp_f32_e32 v147, v141
	v_pk_mul_f32 v[108:109], v[108:109], v[144:145]
	v_lshlrev_b32_e32 v141, 16, v182
	v_and_b32_e32 v145, 0xffff0000, v182
	v_rcp_f32_e32 v144, v141
	v_rcp_f32_e32 v145, v145
	v_lshlrev_b32_e32 v136, 16, v137
	v_and_b32_e32 v137, 0xffff0000, v137
	v_pk_mul_f32 v[136:137], v[146:147], v[136:137]
	v_pk_mul_f32 v[118:119], v[118:119], v[172:173]
	v_pk_mul_f32 v[110:111], v[110:111], v[136:137]
	v_lshlrev_b32_e32 v136, 16, v138
	v_and_b32_e32 v137, 0xffff0000, v138
	v_pk_mul_f32 v[136:137], v[144:145], v[136:137]
	global_load_dwordx4 v[144:147], v[194:195], off offset:2304 nt
	v_pk_mul_f32 v[104:105], v[104:105], v[136:137]
	v_lshlrev_b32_e32 v136, 16, v183
	v_and_b32_e32 v137, 0xffff0000, v183
	v_rcp_f32_e32 v136, v136
	v_rcp_f32_e32 v137, v137
	v_lshlrev_b32_e32 v138, 16, v139
	v_and_b32_e32 v139, 0xffff0000, v139
	global_load_dwordx4 v[172:175], v[194:195], off offset:256 nt
	v_pk_mul_f32 v[136:137], v[136:137], v[138:139]
	v_lshlrev_b32_e32 v138, 16, v188
	v_and_b32_e32 v139, 0xffff0000, v188
	v_rcp_f32_e32 v138, v138
	v_rcp_f32_e32 v139, v139
	v_pk_mul_f32 v[106:107], v[106:107], v[136:137]
	v_lshlrev_b32_e32 v136, 16, v184
	v_and_b32_e32 v137, 0xffff0000, v184
	v_pk_mul_f32 v[136:137], v[138:139], v[136:137]
	v_lshlrev_b32_e32 v138, 16, v189
	v_and_b32_e32 v139, 0xffff0000, v189
	v_rcp_f32_e32 v138, v138
	v_rcp_f32_e32 v139, v139
	v_pk_mul_f32 v[100:101], v[100:101], v[136:137]
	v_lshlrev_b32_e32 v136, 16, v185
	v_and_b32_e32 v137, 0xffff0000, v185
	v_pk_mul_f32 v[136:137], v[138:139], v[136:137]
	v_lshlrev_b32_e32 v138, 16, v190
	v_and_b32_e32 v139, 0xffff0000, v190
	v_rcp_f32_e32 v138, v138
	v_rcp_f32_e32 v139, v139
	v_pk_mul_f32 v[102:103], v[102:103], v[136:137]
	v_lshlrev_b32_e32 v136, 16, v186
	v_and_b32_e32 v137, 0xffff0000, v186
	v_pk_mul_f32 v[136:137], v[138:139], v[136:137]
	v_pk_mul_f32 v[176:177], v[208:209], v[176:177]
	v_pk_mul_f32 v[96:97], v[96:97], v[136:137]
	v_or_b32_e32 v136, 48, v140
	v_ashrrev_i32_e32 v137, 31, v136
	v_lshlrev_b64 v[136:137], 12, v[136:137]
	v_lshl_add_u64 v[136:137], s[2:3], 0, v[136:137]
	v_lshlrev_b32_e32 v138, 16, v191
	v_and_b32_e32 v139, 0xffff0000, v191
	v_lshl_add_u64 v[180:181], v[136:137], 0, v[142:143]
	v_pk_mul_f32 v[112:113], v[112:113], v[176:177]
	global_load_dwordx4 v[140:143], v[180:181], off offset:2048 nt
	v_rcp_f32_e32 v176, v138
	v_rcp_f32_e32 v177, v139
	global_load_dwordx4 v[136:139], v[180:181], off nt
	v_pk_mul_f32 v[178:179], v[178:179], v[196:197]
	s_nop 0
	v_pk_mul_f32 v[124:125], v[124:125], v[178:179]
	v_lshlrev_b32_e32 v178, 16, v187
	v_and_b32_e32 v179, 0xffff0000, v187
	v_pk_mul_f32 v[176:177], v[176:177], v[178:179]
	v_lshlrev_b32_e32 v178, 16, v128
	v_and_b32_e32 v128, 0xffff0000, v128
	v_rcp_f32_e32 v179, v128
	v_lshlrev_b32_e32 v128, 16, v129
	v_and_b32_e32 v129, 0xffff0000, v129
	v_rcp_f32_e32 v128, v128
	v_rcp_f32_e32 v129, v129
	v_pk_mul_f32 v[98:99], v[98:99], v[176:177]
	s_waitcnt vmcnt(0)
	v_lshlrev_b32_e32 v176, 16, v132
	v_and_b32_e32 v177, 0xffff0000, v132
	v_lshlrev_b32_e32 v132, 16, v133
	v_and_b32_e32 v133, 0xffff0000, v133
	v_pk_mul_f32 v[128:129], v[128:129], v[132:133]
	v_lshlrev_b32_e32 v132, 16, v130
	v_and_b32_e32 v130, 0xffff0000, v130
	v_rcp_f32_e32 v132, v132
	v_rcp_f32_e32 v133, v130
	v_rcp_f32_e32 v178, v178
	v_pk_mul_f32 v[94:95], v[94:95], v[128:129]
	v_lshlrev_b32_e32 v128, 16, v134
	v_and_b32_e32 v129, 0xffff0000, v134
	v_pk_mul_f32 v[128:129], v[132:133], v[128:129]
	v_pk_mul_f32 v[176:177], v[178:179], v[176:177]
	v_pk_mul_f32 v[88:89], v[88:89], v[128:129]
	v_lshlrev_b32_e32 v128, 16, v131
	v_and_b32_e32 v129, 0xffff0000, v131
	v_rcp_f32_e32 v128, v128
	v_rcp_f32_e32 v129, v129
	v_pk_mul_f32 v[92:93], v[92:93], v[176:177]
	global_load_dwordx4 v[176:179], v[180:181], off offset:2304 nt
	v_lshlrev_b32_e32 v130, 16, v135
	v_and_b32_e32 v131, 0xffff0000, v135
	v_pk_mul_f32 v[128:129], v[128:129], v[130:131]
	v_lshlrev_b32_e32 v130, 16, v144
	v_and_b32_e32 v131, 0xffff0000, v144
	global_load_dwordx4 v[132:135], v[180:181], off offset:256 nt
	v_rcp_f32_e32 v130, v130
	v_rcp_f32_e32 v131, v131
	v_pk_mul_f32 v[90:91], v[90:91], v[128:129]
	v_lshlrev_b32_e32 v128, 16, v172
	v_and_b32_e32 v129, 0xffff0000, v172
	v_pk_mul_f32 v[128:129], v[130:131], v[128:129]
	v_lshlrev_b32_e32 v130, 16, v145
	v_and_b32_e32 v131, 0xffff0000, v145
	v_rcp_f32_e32 v130, v130
	v_rcp_f32_e32 v131, v131
	v_pk_mul_f32 v[84:85], v[84:85], v[128:129]
	v_lshlrev_b32_e32 v128, 16, v173
	v_and_b32_e32 v129, 0xffff0000, v173
	v_pk_mul_f32 v[128:129], v[130:131], v[128:129]
	v_lshlrev_b32_e32 v130, 16, v146
	v_and_b32_e32 v131, 0xffff0000, v146
	v_rcp_f32_e32 v130, v130
	v_rcp_f32_e32 v131, v131
	v_pk_mul_f32 v[86:87], v[86:87], v[128:129]
	v_lshlrev_b32_e32 v128, 16, v174
	v_and_b32_e32 v129, 0xffff0000, v174
	v_pk_mul_f32 v[128:129], v[130:131], v[128:129]
	v_lshl_add_u64 v[180:181], v[168:169], 0, s[12:13]
	v_pk_mul_f32 v[80:81], v[80:81], v[128:129]
	v_lshlrev_b32_e32 v128, 16, v147
	v_and_b32_e32 v129, 0xffff0000, v147
	global_load_dwordx4 v[144:147], v[180:181], off offset:2048 nt
	v_rcp_f32_e32 v172, v128
	v_add_co_u32_e32 v128, vcc, s59, v168
	v_rcp_f32_e32 v173, v129
	s_nop 0
	v_addc_co_u32_e32 v129, vcc, 0, v169, vcc
	global_load_dwordx4 v[128:131], v[128:129], off nt
	v_lshlrev_b32_e32 v174, 16, v175
	v_and_b32_e32 v175, 0xffff0000, v175
	v_pk_mul_f32 v[172:173], v[172:173], v[174:175]
	v_lshlrev_b32_e32 v174, 16, v140
	v_and_b32_e32 v140, 0xffff0000, v140
	v_pk_mul_f32 v[82:83], v[82:83], v[172:173]
	v_lshlrev_b32_e32 v172, 16, v136
	v_and_b32_e32 v173, 0xffff0000, v136
	v_lshlrev_b32_e32 v136, 16, v141
	v_and_b32_e32 v141, 0xffff0000, v141
	v_rcp_f32_e32 v175, v140
	v_rcp_f32_e32 v140, v136
	v_rcp_f32_e32 v141, v141
	v_rcp_f32_e32 v174, v174
	v_lshlrev_b32_e32 v136, 16, v137
	v_and_b32_e32 v137, 0xffff0000, v137
	v_pk_mul_f32 v[136:137], v[140:141], v[136:137]
	v_lshlrev_b32_e32 v140, 16, v142
	v_and_b32_e32 v141, 0xffff0000, v142
	v_rcp_f32_e32 v140, v140
	v_rcp_f32_e32 v141, v141
	v_pk_mul_f32 v[172:173], v[174:175], v[172:173]
	v_pk_mul_f32 v[78:79], v[78:79], v[136:137]
	v_pk_mul_f32 v[76:77], v[76:77], v[172:173]
	global_load_dwordx4 v[172:175], v[180:181], off offset:2304 nt
	v_lshlrev_b32_e32 v136, 16, v138
	v_and_b32_e32 v137, 0xffff0000, v138
	v_pk_mul_f32 v[136:137], v[140:141], v[136:137]
	v_lshlrev_b32_e32 v142, 16, v139
	v_pk_mul_f32 v[72:73], v[72:73], v[136:137]
	v_lshlrev_b32_e32 v136, 16, v143
	v_and_b32_e32 v137, 0xffff0000, v143
	v_rcp_f32_e32 v140, v136
	v_rcp_f32_e32 v141, v137
	v_and_b32_e32 v143, 0xffff0000, v139
	global_load_dwordx4 v[136:139], v[180:181], off offset:256 nt
	v_lshl_add_u64 v[180:181], v[168:169], 0, s[20:21]
	v_pk_mul_f32 v[140:141], v[140:141], v[142:143]
	s_waitcnt vmcnt(0)
	v_lshlrev_b32_e32 v142, 16, v176
	v_and_b32_e32 v143, 0xffff0000, v176
	v_rcp_f32_e32 v142, v142
	v_rcp_f32_e32 v143, v143
	v_pk_mul_f32 v[74:75], v[74:75], v[140:141]
	v_lshlrev_b32_e32 v140, 16, v132
	v_and_b32_e32 v141, 0xffff0000, v132
	v_pk_mul_f32 v[140:141], v[142:143], v[140:141]
	v_lshlrev_b32_e32 v132, 16, v177
	v_and_b32_e32 v143, 0xffff0000, v177
	v_rcp_f32_e32 v142, v132
	v_rcp_f32_e32 v143, v143
	v_pk_mul_f32 v[68:69], v[68:69], v[140:141]
	v_lshlrev_b32_e32 v140, 16, v178
	v_and_b32_e32 v141, 0xffff0000, v178
	v_rcp_f32_e32 v140, v140
	v_rcp_f32_e32 v141, v141
	v_lshlrev_b32_e32 v132, 16, v133
	v_and_b32_e32 v133, 0xffff0000, v133
	v_pk_mul_f32 v[132:133], v[142:143], v[132:133]
	s_nop 0
	v_pk_mul_f32 v[70:71], v[70:71], v[132:133]
	v_lshlrev_b32_e32 v132, 16, v134
	v_and_b32_e32 v133, 0xffff0000, v134
	v_pk_mul_f32 v[132:133], v[140:141], v[132:133]
	v_add_co_u32_e32 v140, vcc, s60, v168
	v_pk_mul_f32 v[64:65], v[64:65], v[132:133]
	v_lshlrev_b32_e32 v132, 16, v179
	v_and_b32_e32 v133, 0xffff0000, v179
	global_load_dwordx4 v[176:179], v[180:181], off offset:2048 nt
	v_rcp_f32_e32 v132, v132
	v_rcp_f32_e32 v133, v133
	v_addc_co_u32_e32 v141, vcc, 0, v169, vcc
	global_load_dwordx4 v[140:143], v[140:141], off nt
	v_lshlrev_b32_e32 v134, 16, v135
	v_and_b32_e32 v135, 0xffff0000, v135
	v_pk_mul_f32 v[132:133], v[132:133], v[134:135]
	v_lshlrev_b32_e32 v134, 16, v144
	v_and_b32_e32 v135, 0xffff0000, v144
	v_rcp_f32_e32 v134, v134
	v_rcp_f32_e32 v135, v135
	v_pk_mul_f32 v[66:67], v[66:67], v[132:133]
	v_lshlrev_b32_e32 v132, 16, v128
	v_and_b32_e32 v133, 0xffff0000, v128
	v_pk_mul_f32 v[132:133], v[134:135], v[132:133]
	v_lshlrev_b32_e32 v128, 16, v145
	v_and_b32_e32 v135, 0xffff0000, v145
	v_rcp_f32_e32 v134, v128
	v_rcp_f32_e32 v135, v135
	v_pk_mul_f32 v[60:61], v[60:61], v[132:133]
	v_lshlrev_b32_e32 v132, 16, v146
	v_and_b32_e32 v133, 0xffff0000, v146
	v_rcp_f32_e32 v132, v132
	v_rcp_f32_e32 v133, v133
	v_lshlrev_b32_e32 v128, 16, v129
	v_and_b32_e32 v129, 0xffff0000, v129
	v_pk_mul_f32 v[128:129], v[134:135], v[128:129]
	v_lshlrev_b32_e32 v146, 16, v131
	v_pk_mul_f32 v[62:63], v[62:63], v[128:129]
	v_lshlrev_b32_e32 v128, 16, v130
	v_and_b32_e32 v129, 0xffff0000, v130
	v_pk_mul_f32 v[128:129], v[132:133], v[128:129]
	global_load_dwordx4 v[132:135], v[180:181], off offset:2304 nt
	v_pk_mul_f32 v[56:57], v[56:57], v[128:129]
	v_lshlrev_b32_e32 v128, 16, v147
	v_and_b32_e32 v129, 0xffff0000, v147
	v_rcp_f32_e32 v144, v128
	v_rcp_f32_e32 v145, v129
	v_and_b32_e32 v147, 0xffff0000, v131
	global_load_dwordx4 v[128:131], v[180:181], off offset:256 nt
	v_pk_mul_f32 v[144:145], v[144:145], v[146:147]
	v_lshlrev_b32_e32 v146, 16, v172
	v_and_b32_e32 v147, 0xffff0000, v172
	v_rcp_f32_e32 v146, v146
	v_rcp_f32_e32 v147, v147
	v_pk_mul_f32 v[58:59], v[58:59], v[144:145]
	v_lshlrev_b32_e32 v144, 16, v136
	v_and_b32_e32 v145, 0xffff0000, v136
	v_pk_mul_f32 v[144:145], v[146:147], v[144:145]
	v_lshlrev_b32_e32 v136, 16, v173
	v_and_b32_e32 v147, 0xffff0000, v173
	v_rcp_f32_e32 v146, v136
	v_rcp_f32_e32 v147, v147
	v_pk_mul_f32 v[52:53], v[52:53], v[144:145]
	v_lshlrev_b32_e32 v144, 16, v174
	v_and_b32_e32 v145, 0xffff0000, v174
	v_rcp_f32_e32 v144, v144
	v_rcp_f32_e32 v145, v145
	v_lshlrev_b32_e32 v136, 16, v137
	v_and_b32_e32 v137, 0xffff0000, v137
	v_pk_mul_f32 v[136:137], v[146:147], v[136:137]
	v_lshlrev_b32_e32 v174, 16, v139
	v_pk_mul_f32 v[54:55], v[54:55], v[136:137]
	v_lshlrev_b32_e32 v136, 16, v138
	v_and_b32_e32 v137, 0xffff0000, v138
	v_pk_mul_f32 v[136:137], v[144:145], v[136:137]
	s_nop 0
	v_pk_mul_f32 v[48:49], v[48:49], v[136:137]
	v_lshlrev_b32_e32 v136, 16, v175
	v_and_b32_e32 v137, 0xffff0000, v175
	v_rcp_f32_e32 v172, v136
	v_add_co_u32_e32 v136, vcc, s61, v168
	v_rcp_f32_e32 v173, v137
	s_nop 0
	v_addc_co_u32_e32 v137, vcc, 0, v169, vcc
	v_and_b32_e32 v175, 0xffff0000, v139
	global_load_dwordx4 v[136:139], v[136:137], off nt
	v_lshl_add_u64 v[180:181], v[168:169], 0, s[22:23]
	global_load_dwordx4 v[144:147], v[180:181], off offset:2048 nt
	v_pk_mul_f32 v[172:173], v[172:173], v[174:175]
	s_waitcnt vmcnt(0)
	v_lshlrev_b32_e32 v174, 16, v176
	v_and_b32_e32 v175, 0xffff0000, v176
	v_rcp_f32_e32 v174, v174
	v_rcp_f32_e32 v175, v175
	v_pk_mul_f32 v[50:51], v[50:51], v[172:173]
	v_lshlrev_b32_e32 v172, 16, v140
	v_and_b32_e32 v173, 0xffff0000, v140
	v_pk_mul_f32 v[172:173], v[174:175], v[172:173]
	v_lshlrev_b32_e32 v140, 16, v177
	v_and_b32_e32 v175, 0xffff0000, v177
	v_rcp_f32_e32 v174, v140
	v_rcp_f32_e32 v175, v175
	v_pk_mul_f32 v[44:45], v[44:45], v[172:173]
	v_lshlrev_b32_e32 v172, 16, v178
	v_and_b32_e32 v173, 0xffff0000, v178
	v_rcp_f32_e32 v172, v172
	v_rcp_f32_e32 v173, v173
	v_lshlrev_b32_e32 v140, 16, v141
	v_and_b32_e32 v141, 0xffff0000, v141
	v_pk_mul_f32 v[140:141], v[174:175], v[140:141]
	v_lshlrev_b32_e32 v178, 16, v143
	v_pk_mul_f32 v[46:47], v[46:47], v[140:141]
	v_lshlrev_b32_e32 v140, 16, v142
	v_and_b32_e32 v141, 0xffff0000, v142
	v_pk_mul_f32 v[140:141], v[172:173], v[140:141]
	global_load_dwordx4 v[172:175], v[180:181], off offset:2304 nt
	v_pk_mul_f32 v[40:41], v[40:41], v[140:141]
	v_lshlrev_b32_e32 v140, 16, v179
	v_and_b32_e32 v141, 0xffff0000, v179
	v_rcp_f32_e32 v176, v140
	v_rcp_f32_e32 v177, v141
	v_and_b32_e32 v179, 0xffff0000, v143
	global_load_dwordx4 v[140:143], v[180:181], off offset:256 nt
	v_pk_mul_f32 v[176:177], v[176:177], v[178:179]
	v_lshlrev_b32_e32 v178, 16, v132
	v_and_b32_e32 v132, 0xffff0000, v132
	v_pk_mul_f32 v[42:43], v[42:43], v[176:177]
	v_lshlrev_b32_e32 v176, 16, v128
	v_and_b32_e32 v177, 0xffff0000, v128
	v_lshlrev_b32_e32 v128, 16, v133
	v_and_b32_e32 v133, 0xffff0000, v133
	v_rcp_f32_e32 v179, v132
	v_rcp_f32_e32 v132, v128
	v_rcp_f32_e32 v133, v133
	v_lshlrev_b32_e32 v128, 16, v129
	v_and_b32_e32 v129, 0xffff0000, v129
	v_rcp_f32_e32 v178, v178
	v_pk_mul_f32 v[128:129], v[132:133], v[128:129]
	v_lshlrev_b32_e32 v132, 16, v134
	v_and_b32_e32 v133, 0xffff0000, v134
	v_rcp_f32_e32 v132, v132
	v_rcp_f32_e32 v133, v133
	v_pk_mul_f32 v[38:39], v[38:39], v[128:129]
	v_lshlrev_b32_e32 v128, 16, v130
	v_and_b32_e32 v129, 0xffff0000, v130
	v_pk_mul_f32 v[176:177], v[178:179], v[176:177]
	v_pk_mul_f32 v[128:129], v[132:133], v[128:129]
	v_lshl_add_u64 v[132:133], v[168:169], 0, s[24:25]
	v_pk_mul_f32 v[36:37], v[36:37], v[176:177]
	global_load_dwordx4 v[176:179], v[132:133], off offset:2048 nt
	v_add_co_u32_e32 v168, vcc, s62, v168
	v_lshlrev_b32_e32 v130, 16, v135
	s_nop 0
	v_addc_co_u32_e32 v169, vcc, 0, v169, vcc
	global_load_dwordx4 v[180:183], v[168:169], off nt
	v_and_b32_e32 v135, 0xffff0000, v135
	v_rcp_f32_e32 v134, v130
	v_rcp_f32_e32 v135, v135
	v_pk_mul_f32 v[32:33], v[32:33], v[128:129]
	v_lshlrev_b32_e32 v128, 16, v131
	v_and_b32_e32 v129, 0xffff0000, v131
	v_pk_mul_f32 v[128:129], v[134:135], v[128:129]
	v_lshlrev_b32_e32 v130, 16, v144
	v_and_b32_e32 v131, 0xffff0000, v144
	v_rcp_f32_e32 v130, v130
	v_rcp_f32_e32 v131, v131
	v_pk_mul_f32 v[34:35], v[34:35], v[128:129]
	v_lshlrev_b32_e32 v128, 16, v136
	v_and_b32_e32 v129, 0xffff0000, v136
	v_pk_mul_f32 v[128:129], v[130:131], v[128:129]
	v_lshlrev_b32_e32 v130, 16, v145
	v_and_b32_e32 v131, 0xffff0000, v145
	v_rcp_f32_e32 v130, v130
	v_rcp_f32_e32 v131, v131
	v_pk_mul_f32 v[28:29], v[28:29], v[128:129]
	v_lshlrev_b32_e32 v128, 16, v137
	v_and_b32_e32 v129, 0xffff0000, v137
	v_pk_mul_f32 v[128:129], v[130:131], v[128:129]
	v_lshlrev_b32_e32 v134, 16, v146
	v_pk_mul_f32 v[30:31], v[30:31], v[128:129]
	global_load_dwordx4 v[128:131], v[132:133], off offset:2304 nt
	v_and_b32_e32 v135, 0xffff0000, v146
	v_rcp_f32_e32 v136, v134
	v_rcp_f32_e32 v137, v135
	global_load_dwordx4 v[132:135], v[132:133], off offset:256 nt
	v_lshlrev_b32_e32 v144, 16, v138
	v_and_b32_e32 v145, 0xffff0000, v138
	v_pk_mul_f32 v[136:137], v[136:137], v[144:145]
	v_lshlrev_b32_e32 v138, 16, v147
	v_and_b32_e32 v145, 0xffff0000, v147
	v_rcp_f32_e32 v144, v138
	v_rcp_f32_e32 v145, v145
	v_pk_mul_f32 v[24:25], v[24:25], v[136:137]
	v_lshlrev_b32_e32 v136, 16, v139
	v_and_b32_e32 v137, 0xffff0000, v139
	s_waitcnt vmcnt(0)
	v_lshlrev_b32_e32 v138, 16, v172
	v_and_b32_e32 v139, 0xffff0000, v172
	v_rcp_f32_e32 v138, v138
	v_rcp_f32_e32 v139, v139
	v_pk_mul_f32 v[136:137], v[144:145], v[136:137]
	s_nop 0
	v_pk_mul_f32 v[26:27], v[26:27], v[136:137]
	v_lshlrev_b32_e32 v136, 16, v140
	v_and_b32_e32 v137, 0xffff0000, v140
	v_pk_mul_f32 v[136:137], v[138:139], v[136:137]
	v_lshlrev_b32_e32 v138, 16, v173
	v_and_b32_e32 v139, 0xffff0000, v173
	v_rcp_f32_e32 v138, v138
	v_rcp_f32_e32 v139, v139
	v_pk_mul_f32 v[20:21], v[20:21], v[136:137]
	v_lshlrev_b32_e32 v136, 16, v141
	v_and_b32_e32 v137, 0xffff0000, v141
	v_pk_mul_f32 v[136:137], v[138:139], v[136:137]
	v_lshlrev_b32_e32 v138, 16, v174
	v_and_b32_e32 v139, 0xffff0000, v174
	v_rcp_f32_e32 v138, v138
	v_rcp_f32_e32 v139, v139
	v_pk_mul_f32 v[22:23], v[22:23], v[136:137]
	v_lshlrev_b32_e32 v136, 16, v142
	v_and_b32_e32 v137, 0xffff0000, v142
	v_pk_mul_f32 v[136:137], v[138:139], v[136:137]
	v_lshlrev_b32_e32 v138, 16, v175
	v_and_b32_e32 v139, 0xffff0000, v175
	v_rcp_f32_e32 v138, v138
	v_rcp_f32_e32 v139, v139
	v_pk_mul_f32 v[16:17], v[16:17], v[136:137]
	v_lshlrev_b32_e32 v136, 16, v143
	v_and_b32_e32 v137, 0xffff0000, v143
	v_pk_mul_f32 v[136:137], v[138:139], v[136:137]
	v_lshlrev_b32_e32 v138, 16, v176
	v_and_b32_e32 v139, 0xffff0000, v176
	v_rcp_f32_e32 v138, v138
	v_rcp_f32_e32 v139, v139
	v_pk_mul_f32 v[18:19], v[18:19], v[136:137]
	v_lshlrev_b32_e32 v136, 16, v180
	v_and_b32_e32 v137, 0xffff0000, v180
	v_pk_mul_f32 v[136:137], v[138:139], v[136:137]
	v_lshlrev_b32_e32 v138, 16, v177
	v_and_b32_e32 v139, 0xffff0000, v177
	v_rcp_f32_e32 v138, v138
	v_rcp_f32_e32 v139, v139
	v_pk_mul_f32 v[12:13], v[12:13], v[136:137]
	v_lshlrev_b32_e32 v136, 16, v181
	v_and_b32_e32 v137, 0xffff0000, v181
	v_pk_mul_f32 v[136:137], v[138:139], v[136:137]
	v_lshlrev_b32_e32 v138, 16, v178
	v_and_b32_e32 v139, 0xffff0000, v178
	v_rcp_f32_e32 v138, v138
	v_rcp_f32_e32 v139, v139
	v_pk_mul_f32 v[14:15], v[14:15], v[136:137]
	v_lshlrev_b32_e32 v136, 16, v182
	v_and_b32_e32 v137, 0xffff0000, v182
	v_pk_mul_f32 v[136:137], v[138:139], v[136:137]
	v_lshlrev_b32_e32 v138, 16, v179
	v_and_b32_e32 v139, 0xffff0000, v179
	v_rcp_f32_e32 v138, v138
	v_rcp_f32_e32 v139, v139
	v_pk_mul_f32 v[8:9], v[8:9], v[136:137]
	v_lshlrev_b32_e32 v136, 16, v183
	v_and_b32_e32 v137, 0xffff0000, v183
	v_pk_mul_f32 v[136:137], v[138:139], v[136:137]
	v_lshlrev_b32_e32 v138, 16, v128
	v_and_b32_e32 v128, 0xffff0000, v128
	v_rcp_f32_e32 v139, v128
	v_lshlrev_b32_e32 v128, 16, v129
	v_and_b32_e32 v129, 0xffff0000, v129
	v_rcp_f32_e32 v128, v128
	v_rcp_f32_e32 v129, v129
	v_pk_mul_f32 v[10:11], v[10:11], v[136:137]
	v_lshlrev_b32_e32 v136, 16, v132
	v_and_b32_e32 v137, 0xffff0000, v132
	v_lshlrev_b32_e32 v132, 16, v133
	v_and_b32_e32 v133, 0xffff0000, v133
	v_pk_mul_f32 v[128:129], v[128:129], v[132:133]
	v_lshlrev_b32_e32 v132, 16, v130
	v_and_b32_e32 v130, 0xffff0000, v130
	v_rcp_f32_e32 v132, v132
	v_rcp_f32_e32 v133, v130
	v_lshlrev_b32_e32 v130, 16, v131
	v_and_b32_e32 v131, 0xffff0000, v131
	v_rcp_f32_e32 v138, v138
	v_rcp_f32_e32 v130, v130
	v_rcp_f32_e32 v131, v131
	v_pk_mul_f32 v[6:7], v[6:7], v[128:129]
	v_lshlrev_b32_e32 v128, 16, v134
	v_and_b32_e32 v129, 0xffff0000, v134
	v_pk_mul_f32 v[128:129], v[132:133], v[128:129]
	v_pk_mul_f32 v[136:137], v[138:139], v[136:137]
	v_pk_mul_f32 v[0:1], v[0:1], v[128:129]
	v_lshlrev_b32_e32 v128, 16, v135
	v_and_b32_e32 v129, 0xffff0000, v135
	v_pk_mul_f32 v[128:129], v[130:131], v[128:129]
	v_pk_mul_f32 v[4:5], v[4:5], v[136:137]
	v_pk_mul_f32 v[2:3], v[2:3], v[128:129]
	s_branch .LBB0_888

.LBB0_893:
	v_mov_b32_e32 v129, v192
	s_andn2_b64 vcc, exec, s[8:9]
	v_ashrrev_i32_e32 v128, 2, v129
	v_and_b32_e32 v130, 0xffffffc0, v128
	v_lshrrev_b32_e32 v128, 1, v129
	v_and_or_b32 v129, v129, 15, s27
	v_and_b32_e32 v128, 0x78, v128
	v_add_u32_e32 v130, v129, v130
	v_or_b32_e32 v128, s66, v128
	v_ashrrev_i32_e32 v131, 31, v130
	v_ashrrev_i32_e32 v129, 31, v128
	v_lshlrev_b64 v[132:133], 12, v[130:131]
	v_lshl_add_u64 v[132:133], s[2:3], 0, v[132:133]
	v_lshlrev_b64 v[128:129], 1, v[128:129]
	v_lshl_add_u64 v[136:137], v[132:133], 0, v[128:129]
	global_load_dwordx4 v[132:135], v[136:137], off offset:2048 nt
	s_nop 0
	global_load_dwordx4 v[136:139], v[136:137], off offset:2304 nt
	v_or_b32_e32 v140, 16, v130
	v_lshlrev_b64 v[142:143], 11, v[130:131]
	v_ashrrev_i32_e32 v141, 31, v140
	v_lshl_add_u64 v[142:143], s[4:5], 0, v[142:143]
	v_lshlrev_b64 v[144:145], 12, v[140:141]
	v_lshl_add_u64 v[142:143], v[142:143], 0, v[128:129]
	v_lshl_add_u64 v[144:145], s[2:3], 0, v[144:145]
	v_lshl_add_u64 v[144:145], v[144:145], 0, v[128:129]
	s_mov_b64 s[8:9], -1
	s_waitcnt vmcnt(0)
	v_lshlrev_b32_e32 v146, 16, v132
	v_and_b32_e32 v147, 0xffff0000, v132
	v_lshlrev_b32_e32 v132, 16, v133
	v_and_b32_e32 v133, 0xffff0000, v133
	v_lshlrev_b32_e32 v164, 16, v134
	v_and_b32_e32 v165, 0xffff0000, v134
	v_lshlrev_b32_e32 v134, 16, v135
	v_and_b32_e32 v135, 0xffff0000, v135
	v_lshlrev_b32_e32 v166, 16, v136
	v_and_b32_e32 v167, 0xffff0000, v136
	v_lshlrev_b32_e32 v136, 16, v137
	v_and_b32_e32 v137, 0xffff0000, v137
	v_lshlrev_b32_e32 v168, 16, v138
	v_and_b32_e32 v169, 0xffff0000, v138
	v_lshlrev_b32_e32 v138, 16, v139
	v_and_b32_e32 v139, 0xffff0000, v139
	v_pk_mul_f32 v[124:125], v[124:125], v[146:147]
	v_pk_mul_f32 v[126:127], v[126:127], v[132:133]
	v_pk_mul_f32 v[120:121], v[120:121], v[164:165]
	v_pk_mul_f32 v[122:123], v[122:123], v[134:135]
	v_pk_mul_f32 v[132:133], v[116:117], v[166:167]
	v_pk_mul_f32 v[134:135], v[118:119], v[136:137]
	v_cvt_pk_bf16_f32 v116, v124, v125
	v_cvt_pk_bf16_f32 v117, v126, v127
	v_cvt_pk_bf16_f32 v118, v120, v121
	v_cvt_pk_bf16_f32 v119, v122, v123
	v_pk_mul_f32 v[120:121], v[112:113], v[168:169]
	v_pk_mul_f32 v[122:123], v[114:115], v[138:139]
	global_store_dwordx4 v[142:143], v[116:119], off
	v_cvt_pk_bf16_f32 v112, v132, v133
	v_cvt_pk_bf16_f32 v113, v134, v135
	v_cvt_pk_bf16_f32 v114, v120, v121
	v_cvt_pk_bf16_f32 v115, v122, v123
	global_load_dwordx4 v[116:119], v[144:145], off offset:2048 nt
	v_or_b32_e32 v120, 32, v130
	global_store_dwordx4 v[142:143], v[112:115], off offset:256
	global_load_dwordx4 v[112:115], v[144:145], off offset:2304 nt
	v_ashrrev_i32_e32 v121, 31, v120
	v_lshlrev_b64 v[122:123], 11, v[140:141]
	v_lshlrev_b64 v[124:125], 12, v[120:121]
	v_lshl_add_u64 v[122:123], s[4:5], 0, v[122:123]
	v_lshl_add_u64 v[124:125], s[2:3], 0, v[124:125]
	v_lshl_add_u64 v[122:123], v[122:123], 0, v[128:129]
	v_lshl_add_u64 v[124:125], v[124:125], 0, v[128:129]
	s_waitcnt vmcnt(2)
	v_lshlrev_b32_e32 v126, 16, v116
	v_and_b32_e32 v127, 0xffff0000, v116
	v_lshlrev_b32_e32 v116, 16, v117
	v_and_b32_e32 v117, 0xffff0000, v117
	v_lshlrev_b32_e32 v132, 16, v118
	v_and_b32_e32 v133, 0xffff0000, v118
	v_lshlrev_b32_e32 v118, 16, v119
	v_and_b32_e32 v119, 0xffff0000, v119
	s_waitcnt vmcnt(0)
	v_lshlrev_b32_e32 v134, 16, v112
	v_and_b32_e32 v135, 0xffff0000, v112
	v_lshlrev_b32_e32 v112, 16, v113
	v_and_b32_e32 v113, 0xffff0000, v113
	v_lshlrev_b32_e32 v136, 16, v114
	v_and_b32_e32 v137, 0xffff0000, v114
	v_lshlrev_b32_e32 v114, 16, v115
	v_and_b32_e32 v115, 0xffff0000, v115
	v_pk_mul_f32 v[108:109], v[108:109], v[126:127]
	v_pk_mul_f32 v[110:111], v[110:111], v[116:117]
	v_pk_mul_f32 v[104:105], v[104:105], v[132:133]
	v_pk_mul_f32 v[106:107], v[106:107], v[118:119]
	v_pk_mul_f32 v[116:117], v[100:101], v[134:135]
	v_pk_mul_f32 v[112:113], v[102:103], v[112:113]
	v_cvt_pk_bf16_f32 v100, v108, v109
	v_cvt_pk_bf16_f32 v101, v110, v111
	v_cvt_pk_bf16_f32 v102, v104, v105
	v_cvt_pk_bf16_f32 v103, v106, v107
	v_pk_mul_f32 v[104:105], v[96:97], v[136:137]
	v_pk_mul_f32 v[106:107], v[98:99], v[114:115]
	global_store_dwordx4 v[122:123], v[100:103], off
	v_cvt_pk_bf16_f32 v96, v116, v117
	v_cvt_pk_bf16_f32 v97, v112, v113
	v_cvt_pk_bf16_f32 v98, v104, v105
	v_cvt_pk_bf16_f32 v99, v106, v107
	global_load_dwordx4 v[100:103], v[124:125], off offset:2048 nt
	v_or_b32_e32 v104, 48, v130
	global_store_dwordx4 v[122:123], v[96:99], off offset:256
	global_load_dwordx4 v[96:99], v[124:125], off offset:2304 nt
	v_ashrrev_i32_e32 v105, 31, v104
	v_lshlrev_b64 v[106:107], 11, v[120:121]
	v_lshlrev_b64 v[108:109], 12, v[104:105]
	v_lshl_add_u64 v[106:107], s[4:5], 0, v[106:107]
	v_lshl_add_u64 v[108:109], s[2:3], 0, v[108:109]
	v_lshl_add_u64 v[106:107], v[106:107], 0, v[128:129]
	v_lshl_add_u64 v[108:109], v[108:109], 0, v[128:129]
	s_waitcnt vmcnt(2)
	v_lshlrev_b32_e32 v110, 16, v100
	v_and_b32_e32 v111, 0xffff0000, v100
	v_lshlrev_b32_e32 v100, 16, v101
	v_and_b32_e32 v101, 0xffff0000, v101
	v_lshlrev_b32_e32 v112, 16, v102
	v_and_b32_e32 v113, 0xffff0000, v102
	v_lshlrev_b32_e32 v102, 16, v103
	v_and_b32_e32 v103, 0xffff0000, v103
	s_waitcnt vmcnt(0)
	v_lshlrev_b32_e32 v114, 16, v96
	v_and_b32_e32 v115, 0xffff0000, v96
	v_lshlrev_b32_e32 v96, 16, v97
	v_and_b32_e32 v97, 0xffff0000, v97
	v_lshlrev_b32_e32 v116, 16, v98
	v_and_b32_e32 v117, 0xffff0000, v98
	v_lshlrev_b32_e32 v98, 16, v99
	v_and_b32_e32 v99, 0xffff0000, v99
	v_pk_mul_f32 v[92:93], v[92:93], v[110:111]
	v_pk_mul_f32 v[94:95], v[94:95], v[100:101]
	v_pk_mul_f32 v[88:89], v[88:89], v[112:113]
	v_pk_mul_f32 v[90:91], v[90:91], v[102:103]
	v_pk_mul_f32 v[100:101], v[84:85], v[114:115]
	v_pk_mul_f32 v[96:97], v[86:87], v[96:97]
	v_cvt_pk_bf16_f32 v84, v92, v93
	v_cvt_pk_bf16_f32 v85, v94, v95
	v_cvt_pk_bf16_f32 v86, v88, v89
	v_cvt_pk_bf16_f32 v87, v90, v91
	v_pk_mul_f32 v[88:89], v[80:81], v[116:117]
	v_pk_mul_f32 v[90:91], v[82:83], v[98:99]
	global_store_dwordx4 v[106:107], v[84:87], off
	v_cvt_pk_bf16_f32 v80, v100, v101
	v_cvt_pk_bf16_f32 v81, v96, v97
	v_cvt_pk_bf16_f32 v82, v88, v89
	v_cvt_pk_bf16_f32 v83, v90, v91
	global_load_dwordx4 v[84:87], v[108:109], off offset:2048 nt
	v_add_u32_e32 v88, 0x80, v130
	global_store_dwordx4 v[106:107], v[80:83], off offset:256
	global_load_dwordx4 v[80:83], v[108:109], off offset:2304 nt
	v_ashrrev_i32_e32 v89, 31, v88
	v_lshlrev_b64 v[90:91], 11, v[104:105]
	v_lshlrev_b64 v[92:93], 12, v[88:89]
	v_lshl_add_u64 v[90:91], s[4:5], 0, v[90:91]
	v_lshl_add_u64 v[92:93], s[2:3], 0, v[92:93]
	v_lshl_add_u64 v[90:91], v[90:91], 0, v[128:129]
	v_lshl_add_u64 v[92:93], v[92:93], 0, v[128:129]
	s_waitcnt vmcnt(2)
	v_lshlrev_b32_e32 v94, 16, v84
	v_and_b32_e32 v95, 0xffff0000, v84
	v_lshlrev_b32_e32 v84, 16, v85
	v_and_b32_e32 v85, 0xffff0000, v85
	v_lshlrev_b32_e32 v96, 16, v86
	v_and_b32_e32 v97, 0xffff0000, v86
	v_lshlrev_b32_e32 v86, 16, v87
	v_and_b32_e32 v87, 0xffff0000, v87
	s_waitcnt vmcnt(0)
	v_lshlrev_b32_e32 v98, 16, v80
	v_and_b32_e32 v99, 0xffff0000, v80
	v_lshlrev_b32_e32 v80, 16, v81
	v_and_b32_e32 v81, 0xffff0000, v81
	v_lshlrev_b32_e32 v100, 16, v82
	v_and_b32_e32 v101, 0xffff0000, v82
	v_lshlrev_b32_e32 v82, 16, v83
	v_and_b32_e32 v83, 0xffff0000, v83
	v_pk_mul_f32 v[76:77], v[76:77], v[94:95]
	v_pk_mul_f32 v[78:79], v[78:79], v[84:85]
	v_pk_mul_f32 v[72:73], v[72:73], v[96:97]
	v_pk_mul_f32 v[74:75], v[74:75], v[86:87]
	v_pk_mul_f32 v[84:85], v[68:69], v[98:99]
	v_pk_mul_f32 v[80:81], v[70:71], v[80:81]
	v_cvt_pk_bf16_f32 v68, v76, v77
	v_cvt_pk_bf16_f32 v69, v78, v79
	v_cvt_pk_bf16_f32 v70, v72, v73
	v_cvt_pk_bf16_f32 v71, v74, v75
	v_pk_mul_f32 v[72:73], v[64:65], v[100:101]
	v_pk_mul_f32 v[74:75], v[66:67], v[82:83]
	global_store_dwordx4 v[90:91], v[68:71], off
	v_cvt_pk_bf16_f32 v64, v84, v85
	v_cvt_pk_bf16_f32 v65, v80, v81
	v_cvt_pk_bf16_f32 v66, v72, v73
	v_cvt_pk_bf16_f32 v67, v74, v75
	global_load_dwordx4 v[68:71], v[92:93], off offset:2048 nt
	v_add_u32_e32 v72, 0x90, v130
	global_store_dwordx4 v[90:91], v[64:67], off offset:256
	global_load_dwordx4 v[64:67], v[92:93], off offset:2304 nt
	v_ashrrev_i32_e32 v73, 31, v72
	v_lshlrev_b64 v[74:75], 11, v[88:89]
	v_lshlrev_b64 v[76:77], 12, v[72:73]
	v_lshl_add_u64 v[74:75], s[4:5], 0, v[74:75]
	v_lshl_add_u64 v[76:77], s[2:3], 0, v[76:77]
	v_lshl_add_u64 v[74:75], v[74:75], 0, v[128:129]
	v_lshl_add_u64 v[76:77], v[76:77], 0, v[128:129]
	s_waitcnt vmcnt(2)
	v_lshlrev_b32_e32 v78, 16, v68
	v_and_b32_e32 v79, 0xffff0000, v68
	v_lshlrev_b32_e32 v68, 16, v69
	v_and_b32_e32 v69, 0xffff0000, v69
	v_lshlrev_b32_e32 v80, 16, v70
	v_and_b32_e32 v81, 0xffff0000, v70
	v_lshlrev_b32_e32 v70, 16, v71
	v_and_b32_e32 v71, 0xffff0000, v71
	s_waitcnt vmcnt(0)
	v_lshlrev_b32_e32 v82, 16, v64
	v_and_b32_e32 v83, 0xffff0000, v64
	v_lshlrev_b32_e32 v64, 16, v65
	v_and_b32_e32 v65, 0xffff0000, v65
	v_lshlrev_b32_e32 v84, 16, v66
	v_and_b32_e32 v85, 0xffff0000, v66
	v_lshlrev_b32_e32 v66, 16, v67
	v_and_b32_e32 v67, 0xffff0000, v67
	v_pk_mul_f32 v[60:61], v[60:61], v[78:79]
	v_pk_mul_f32 v[62:63], v[62:63], v[68:69]
	v_pk_mul_f32 v[56:57], v[56:57], v[80:81]
	v_pk_mul_f32 v[58:59], v[58:59], v[70:71]
	v_pk_mul_f32 v[68:69], v[52:53], v[82:83]
	v_pk_mul_f32 v[64:65], v[54:55], v[64:65]
	v_cvt_pk_bf16_f32 v52, v60, v61
	v_cvt_pk_bf16_f32 v53, v62, v63
	v_cvt_pk_bf16_f32 v54, v56, v57
	v_cvt_pk_bf16_f32 v55, v58, v59
	v_pk_mul_f32 v[56:57], v[48:49], v[84:85]
	v_pk_mul_f32 v[58:59], v[50:51], v[66:67]
	global_store_dwordx4 v[74:75], v[52:55], off
	v_cvt_pk_bf16_f32 v48, v68, v69
	v_cvt_pk_bf16_f32 v49, v64, v65
	v_cvt_pk_bf16_f32 v50, v56, v57
	v_cvt_pk_bf16_f32 v51, v58, v59
	global_load_dwordx4 v[52:55], v[76:77], off offset:2048 nt
	v_add_u32_e32 v56, 0xa0, v130
	global_store_dwordx4 v[74:75], v[48:51], off offset:256
	global_load_dwordx4 v[48:51], v[76:77], off offset:2304 nt
	v_ashrrev_i32_e32 v57, 31, v56
	v_lshlrev_b64 v[58:59], 11, v[72:73]
	v_lshlrev_b64 v[60:61], 12, v[56:57]
	v_lshl_add_u64 v[58:59], s[4:5], 0, v[58:59]
	v_lshl_add_u64 v[60:61], s[2:3], 0, v[60:61]
	v_lshl_add_u64 v[58:59], v[58:59], 0, v[128:129]
	v_lshl_add_u64 v[60:61], v[60:61], 0, v[128:129]
	s_waitcnt vmcnt(2)
	v_lshlrev_b32_e32 v62, 16, v52
	v_and_b32_e32 v63, 0xffff0000, v52
	v_lshlrev_b32_e32 v52, 16, v53
	v_and_b32_e32 v53, 0xffff0000, v53
	v_lshlrev_b32_e32 v64, 16, v54
	v_and_b32_e32 v65, 0xffff0000, v54
	v_lshlrev_b32_e32 v54, 16, v55
	v_and_b32_e32 v55, 0xffff0000, v55
	s_waitcnt vmcnt(0)
	v_lshlrev_b32_e32 v66, 16, v48
	v_and_b32_e32 v67, 0xffff0000, v48
	v_lshlrev_b32_e32 v48, 16, v49
	v_and_b32_e32 v49, 0xffff0000, v49
	v_lshlrev_b32_e32 v68, 16, v50
	v_and_b32_e32 v69, 0xffff0000, v50
	v_lshlrev_b32_e32 v50, 16, v51
	v_and_b32_e32 v51, 0xffff0000, v51
	v_pk_mul_f32 v[44:45], v[44:45], v[62:63]
	v_pk_mul_f32 v[46:47], v[46:47], v[52:53]
	v_pk_mul_f32 v[40:41], v[40:41], v[64:65]
	v_pk_mul_f32 v[42:43], v[42:43], v[54:55]
	v_pk_mul_f32 v[52:53], v[36:37], v[66:67]
	v_pk_mul_f32 v[48:49], v[38:39], v[48:49]
	v_cvt_pk_bf16_f32 v36, v44, v45
	v_cvt_pk_bf16_f32 v37, v46, v47
	v_cvt_pk_bf16_f32 v38, v40, v41
	v_cvt_pk_bf16_f32 v39, v42, v43
	v_pk_mul_f32 v[40:41], v[32:33], v[68:69]
	v_pk_mul_f32 v[42:43], v[34:35], v[50:51]
	global_store_dwordx4 v[58:59], v[36:39], off
	v_cvt_pk_bf16_f32 v32, v52, v53
	v_cvt_pk_bf16_f32 v33, v48, v49
	v_cvt_pk_bf16_f32 v34, v40, v41
	v_cvt_pk_bf16_f32 v35, v42, v43
	global_load_dwordx4 v[36:39], v[60:61], off offset:2048 nt
	v_add_u32_e32 v40, 0xb0, v130
	global_store_dwordx4 v[58:59], v[32:35], off offset:256
	global_load_dwordx4 v[32:35], v[60:61], off offset:2304 nt
	v_ashrrev_i32_e32 v41, 31, v40
	v_lshlrev_b64 v[42:43], 11, v[56:57]
	v_lshlrev_b64 v[44:45], 12, v[40:41]
	v_lshl_add_u64 v[42:43], s[4:5], 0, v[42:43]
	v_lshl_add_u64 v[44:45], s[2:3], 0, v[44:45]
	v_lshl_add_u64 v[42:43], v[42:43], 0, v[128:129]
	v_lshl_add_u64 v[44:45], v[44:45], 0, v[128:129]
	s_waitcnt vmcnt(2)
	v_lshlrev_b32_e32 v46, 16, v36
	v_and_b32_e32 v47, 0xffff0000, v36
	v_lshlrev_b32_e32 v36, 16, v37
	v_and_b32_e32 v37, 0xffff0000, v37
	v_lshlrev_b32_e32 v48, 16, v38
	v_and_b32_e32 v49, 0xffff0000, v38
	v_lshlrev_b32_e32 v38, 16, v39
	v_and_b32_e32 v39, 0xffff0000, v39
	s_waitcnt vmcnt(0)
	v_lshlrev_b32_e32 v50, 16, v32
	v_and_b32_e32 v51, 0xffff0000, v32
	v_lshlrev_b32_e32 v32, 16, v33
	v_and_b32_e32 v33, 0xffff0000, v33
	v_lshlrev_b32_e32 v52, 16, v34
	v_and_b32_e32 v53, 0xffff0000, v34
	v_lshlrev_b32_e32 v34, 16, v35
	v_and_b32_e32 v35, 0xffff0000, v35
	v_pk_mul_f32 v[28:29], v[28:29], v[46:47]
	v_pk_mul_f32 v[30:31], v[30:31], v[36:37]
	v_pk_mul_f32 v[24:25], v[24:25], v[48:49]
	v_pk_mul_f32 v[26:27], v[26:27], v[38:39]
	v_pk_mul_f32 v[36:37], v[20:21], v[50:51]
	v_pk_mul_f32 v[32:33], v[22:23], v[32:33]
	v_cvt_pk_bf16_f32 v20, v28, v29
	v_cvt_pk_bf16_f32 v21, v30, v31
	v_cvt_pk_bf16_f32 v22, v24, v25
	v_cvt_pk_bf16_f32 v23, v26, v27
	v_pk_mul_f32 v[24:25], v[16:17], v[52:53]
	v_pk_mul_f32 v[26:27], v[18:19], v[34:35]
	global_store_dwordx4 v[42:43], v[20:23], off
	v_cvt_pk_bf16_f32 v16, v36, v37
	v_cvt_pk_bf16_f32 v17, v32, v33
	v_cvt_pk_bf16_f32 v18, v24, v25
	v_cvt_pk_bf16_f32 v19, v26, v27
	global_load_dwordx4 v[20:23], v[44:45], off offset:2048 nt
	v_lshlrev_b64 v[24:25], 11, v[40:41]
	global_store_dwordx4 v[42:43], v[16:19], off offset:256
	global_load_dwordx4 v[16:19], v[44:45], off offset:2304 nt
	v_lshl_add_u64 v[24:25], s[4:5], 0, v[24:25]
	v_lshl_add_u64 v[24:25], v[24:25], 0, v[128:129]
	s_waitcnt vmcnt(2)
	v_lshlrev_b32_e32 v26, 16, v20
	v_and_b32_e32 v27, 0xffff0000, v20
	v_lshlrev_b32_e32 v20, 16, v21
	v_and_b32_e32 v21, 0xffff0000, v21
	v_lshlrev_b32_e32 v28, 16, v22
	v_and_b32_e32 v29, 0xffff0000, v22
	v_lshlrev_b32_e32 v22, 16, v23
	v_and_b32_e32 v23, 0xffff0000, v23
	s_waitcnt vmcnt(0)
	v_lshlrev_b32_e32 v30, 16, v16
	v_and_b32_e32 v31, 0xffff0000, v16
	v_lshlrev_b32_e32 v16, 16, v17
	v_and_b32_e32 v17, 0xffff0000, v17
	v_lshlrev_b32_e32 v32, 16, v18
	v_and_b32_e32 v33, 0xffff0000, v18
	v_lshlrev_b32_e32 v18, 16, v19
	v_and_b32_e32 v19, 0xffff0000, v19
	v_pk_mul_f32 v[12:13], v[12:13], v[26:27]
	v_pk_mul_f32 v[14:15], v[14:15], v[20:21]
	v_pk_mul_f32 v[8:9], v[8:9], v[28:29]
	v_pk_mul_f32 v[10:11], v[10:11], v[22:23]
	v_pk_mul_f32 v[4:5], v[4:5], v[30:31]
	v_pk_mul_f32 v[6:7], v[6:7], v[16:17]
	v_pk_mul_f32 v[16:17], v[0:1], v[32:33]
	v_pk_mul_f32 v[18:19], v[2:3], v[18:19]
	v_cvt_pk_bf16_f32 v0, v12, v13
	v_cvt_pk_bf16_f32 v1, v14, v15
	v_cvt_pk_bf16_f32 v2, v8, v9
	v_cvt_pk_bf16_f32 v3, v10, v11
	v_cvt_pk_bf16_f32 v4, v4, v5
	v_cvt_pk_bf16_f32 v5, v6, v7
	v_cvt_pk_bf16_f32 v6, v16, v17
	v_cvt_pk_bf16_f32 v7, v18, v19
	global_store_dwordx4 v[24:25], v[0:3], off
	global_store_dwordx4 v[24:25], v[4:7], off offset:256
	s_cbranch_vccnz .LBB0_880
	s_andn2_b64 vcc, exec, s[14:15]
	s_cbranch_vccnz .LBB0_879
	s_barrier
	s_branch .LBB0_879

.Lhb7_done:
.LBB0_1071:
	s_or_b64 exec, exec, s[2:3]
	v_mov_b32_e32 v32, v192
	s_waitcnt lgkmcnt(0)
	s_barrier
	s_nop 0
	v_readfirstlane_b32 s2, v32
	s_ashr_i32 s10, s2, 6
	s_mul_i32 s15, s10, s92
	s_add_i32 s2, s15, s96
	s_cmpk_gt_i32 s2, 0x41ff
	s_cbranch_scc1 .LBB0_1079
	s_load_dwordx2 s[8:9], s[0:1], 0xf0
	s_load_dwordx4 s[20:23], s[0:1], 0x98
	v_lshlrev_b32_e32 v0, 2, v32
	v_and_b32_e32 v34, 0xfc, v0
	v_mov_b32_e32 v65, 0
	s_waitcnt lgkmcnt(0)
	s_add_u32 s16, s8, 0x2380000
	s_addc_u32 s17, s9, 0
	s_ashr_i32 s3, s2, 31
	s_lshl_b64 s[2:3], s[2:3], 11
	s_add_u32 s2, s8, s2
	v_lshlrev_b32_e32 v64, 1, v34
	s_addc_u32 s3, s9, s3
	v_lshl_add_u64 v[36:37], s[2:3], 0, v[64:65]
	s_mov_b64 s[4:5], 0x4900000
	v_lshlrev_b32_e32 v33, 2, v34
	v_lshl_add_u64 v[38:39], v[36:37], 0, s[4:5]
	s_mov_b32 s4, 0x4900000
	global_load_dwordx4 v[0:3], v33, s[20:21] offset:3072
	global_load_dwordx4 v[4:7], v33, s[22:23] offset:3072
	global_load_dwordx4 v[8:11], v33, s[22:23] offset:2048
	global_load_dwordx4 v[12:15], v33, s[20:21] offset:2048
	global_load_dwordx4 v[16:19], v33, s[22:23] offset:1024
	global_load_dwordx4 v[20:23], v33, s[20:21] offset:1024
	global_load_dwordx4 v[24:27], v33, s[22:23]
	global_load_dwordx4 v[28:31], v33, s[20:21]
	v_add_co_u32_e32 v36, vcc, s4, v36
	v_mbcnt_hi_u32_b32 v33, -1, v193
	s_nop 0
	v_addc_co_u32_e32 v37, vcc, 0, v37, vcc
	global_load_dwordx2 v[82:83], v[36:37], off nt
	global_load_dwordx2 v[80:81], v[38:39], off offset:512 nt
	global_load_dwordx2 v[78:79], v[38:39], off offset:1024 nt
	global_load_dwordx2 v[76:77], v[38:39], off offset:1536 nt
	v_and_b32_e32 v35, 64, v33
	v_add_u32_e32 v35, 64, v35
	v_xor_b32_e32 v36, 1, v33
	v_cmp_lt_i32_e32 vcc, v36, v35
	s_add_i32 s10, s10, 8
	v_readlane_b32 s4, v248, 9
	v_cndmask_b32_e32 v36, v33, v36, vcc
	v_lshlrev_b32_e32 v84, 2, v36
	v_xor_b32_e32 v36, 2, v33
	v_cmp_lt_i32_e32 vcc, v36, v35
	s_mul_i32 s18, s92, s10
	v_readlane_b32 s5, v248, 10
	v_cndmask_b32_e32 v36, v33, v36, vcc
	v_lshlrev_b32_e32 v85, 2, v36
	v_xor_b32_e32 v36, 4, v33
	v_cmp_lt_i32_e32 vcc, v36, v35
	s_add_i32 s10, s96, s18
	s_mov_b32 s12, s4
	v_cndmask_b32_e32 v36, v33, v36, vcc
	v_lshlrev_b32_e32 v86, 2, v36
	v_xor_b32_e32 v36, 8, v33
	v_cmp_lt_i32_e32 vcc, v36, v35
	s_ashr_i32 s13, s4, 31
	v_writelane_b32 v248, s4, 9
	v_cndmask_b32_e32 v36, v33, v36, vcc
	v_lshlrev_b32_e32 v87, 2, v36
	v_xor_b32_e32 v36, 16, v33
	v_cmp_lt_i32_e32 vcc, v36, v35
	s_ashr_i32 s11, s10, 31
	v_writelane_b32 v248, s5, 10
	v_cndmask_b32_e32 v36, v33, v36, vcc
	v_lshlrev_b32_e32 v88, 2, v36
	v_xor_b32_e32 v36, 32, v33
	v_cmp_lt_i32_e32 vcc, v36, v35
	s_lshl_b64 s[4:5], s[12:13], 11
	s_lshl_b64 s[10:11], s[10:11], 11
	v_cndmask_b32_e32 v33, v33, v36, vcc
	v_and_b32_e32 v32, 63, v32
	s_add_u32 s8, s8, s10
	s_mov_b32 s24, -1
	v_lshlrev_b32_e32 v89, 2, v33
	v_lshlrev_b32_e32 v66, 3, v32
	v_mov_b32_e32 v67, v65
	s_addc_u32 s9, s9, s11
	s_movk_i32 s19, 0x4000
	v_lshlrev_b32_e32 v64, 2, v34
	s_mov_b64 s[10:11], 0x3000
	s_mov_b64 s[12:13], 0x4000
	s_mov_b32 s14, 0x3a800000
	s_mov_b32 s20, 0x800000
	s_mov_b32 s21, 0xc800000
	s_mov_b32 s22, 0x2800000
	s_mov_b32 s23, s96
	s_branch .LBB0_1075
.LBB0_1073:
	v_lshl_add_u64 v[68:69], s[8:9], 0, v[66:67]
	v_add_co_u32_e32 v90, vcc, 0x4900000, v68
	s_nop 1
	v_addc_co_u32_e32 v91, vcc, 0, v69, vcc
	global_load_dwordx2 v[68:69], v[90:91], off nt
	global_load_dwordx2 v[70:71], v[90:91], off offset:512 nt
	global_load_dwordx2 v[72:73], v[90:91], off offset:1024 nt
	global_load_dwordx2 v[74:75], v[90:91], off offset:1536 nt

.LBB0_1207:
	s_ashr_i32 s4, s10, 31
	s_lshr_b32 s4, s4, 27
	s_add_i32 s4, s10, s4
	s_ashr_i32 s5, s4, 5
	s_lshl_b32 s4, s5, 6
	s_lshl_b32 s8, s5, 10
	s_waitcnt vmcnt(0)
	v_or_b32_e32 v16, s4, v4
	s_sub_i32 s8, s13, s8
	v_or_b32_e32 v26, 10, v16
	v_or_b32_e32 v28, 12, v16
	v_or_b32_e32 v30, 14, v16
	v_or_b32_e32 v40, 24, v16
	v_or_b32_e32 v42, 26, v16
	v_or_b32_e32 v44, 28, v16
	v_or_b32_e32 v46, 30, v16
	s_ashr_i32 s9, s8, 31
	v_ashrrev_i32_e32 v17, 31, v16
	v_or_b32_e32 v18, 2, v16
	v_or_b32_e32 v20, 4, v16
	v_or_b32_e32 v22, 6, v16
	v_or_b32_e32 v24, 8, v16
	v_or_b32_e32 v32, 16, v16
	v_or_b32_e32 v34, 18, v16
	v_or_b32_e32 v36, 20, v16
	v_or_b32_e32 v38, 22, v16
	v_or_b32_e32 v48, 32, v16
	v_or_b32_e32 v50, 34, v16
	v_or_b32_e32 v52, 36, v16
	v_or_b32_e32 v54, 38, v16
	v_or_b32_e32 v56, 40, v16
	v_or_b32_e32 v58, 42, v16
	v_or_b32_e32 v60, 44, v16
	v_or_b32_e32 v62, 46, v16
	v_or_b32_e32 v64, 48, v16
	v_or_b32_e32 v66, 50, v16
	v_or_b32_e32 v68, 52, v16
	v_or_b32_e32 v70, 54, v16
	v_or_b32_e32 v72, 56, v16
	v_or_b32_e32 v74, 58, v16
	v_or_b32_e32 v76, 60, v16
	v_or_b32_e32 v78, 62, v16
	v_ashrrev_i32_e32 v27, 31, v26
	v_ashrrev_i32_e32 v29, 31, v28
	v_ashrrev_i32_e32 v31, 31, v30
	v_ashrrev_i32_e32 v41, 31, v40
	v_ashrrev_i32_e32 v43, 31, v42
	v_ashrrev_i32_e32 v45, 31, v44
	v_ashrrev_i32_e32 v47, 31, v46
	v_lshl_add_u64 v[80:81], s[8:9], 2, v[0:1]
	v_lshlrev_b64 v[16:17], 12, v[16:17]
	v_ashrrev_i32_e32 v19, 31, v18
	v_ashrrev_i32_e32 v21, 31, v20
	v_ashrrev_i32_e32 v23, 31, v22
	v_ashrrev_i32_e32 v25, 31, v24
	v_ashrrev_i32_e32 v33, 31, v32
	v_ashrrev_i32_e32 v35, 31, v34
	v_ashrrev_i32_e32 v37, 31, v36
	v_ashrrev_i32_e32 v39, 31, v38
	v_ashrrev_i32_e32 v49, 31, v48
	v_ashrrev_i32_e32 v51, 31, v50
	v_ashrrev_i32_e32 v53, 31, v52
	v_ashrrev_i32_e32 v55, 31, v54
	v_ashrrev_i32_e32 v57, 31, v56
	v_ashrrev_i32_e32 v59, 31, v58
	v_ashrrev_i32_e32 v61, 31, v60
	v_ashrrev_i32_e32 v63, 31, v62
	v_ashrrev_i32_e32 v65, 31, v64
	v_ashrrev_i32_e32 v67, 31, v66
	v_ashrrev_i32_e32 v69, 31, v68
	v_ashrrev_i32_e32 v71, 31, v70
	v_ashrrev_i32_e32 v73, 31, v72
	v_ashrrev_i32_e32 v75, 31, v74
	v_ashrrev_i32_e32 v77, 31, v76
	v_ashrrev_i32_e32 v79, 31, v78
	v_lshlrev_b64 v[26:27], 12, v[26:27]
	v_lshlrev_b64 v[28:29], 12, v[28:29]
	v_lshlrev_b64 v[30:31], 12, v[30:31]
	v_lshlrev_b64 v[40:41], 12, v[40:41]
	v_lshlrev_b64 v[42:43], 12, v[42:43]
	v_lshlrev_b64 v[44:45], 12, v[44:45]
	v_lshlrev_b64 v[46:47], 12, v[46:47]
	v_lshl_add_u64 v[16:17], v[80:81], 0, v[16:17]
	v_lshlrev_b64 v[18:19], 12, v[18:19]
	v_lshlrev_b64 v[20:21], 12, v[20:21]
	v_lshlrev_b64 v[22:23], 12, v[22:23]
	v_lshlrev_b64 v[24:25], 12, v[24:25]
	v_lshlrev_b64 v[32:33], 12, v[32:33]
	v_lshlrev_b64 v[34:35], 12, v[34:35]
	v_lshlrev_b64 v[36:37], 12, v[36:37]
	v_lshlrev_b64 v[38:39], 12, v[38:39]
	v_lshlrev_b64 v[48:49], 12, v[48:49]
	v_lshlrev_b64 v[50:51], 12, v[50:51]
	v_lshlrev_b64 v[52:53], 12, v[52:53]
	v_lshlrev_b64 v[54:55], 12, v[54:55]
	v_lshlrev_b64 v[56:57], 12, v[56:57]
	v_lshlrev_b64 v[58:59], 12, v[58:59]
	v_lshlrev_b64 v[60:61], 12, v[60:61]
	v_lshlrev_b64 v[62:63], 12, v[62:63]
	v_lshlrev_b64 v[64:65], 12, v[64:65]
	v_lshlrev_b64 v[66:67], 12, v[66:67]
	v_lshlrev_b64 v[68:69], 12, v[68:69]
	v_lshlrev_b64 v[70:71], 12, v[70:71]
	v_lshlrev_b64 v[72:73], 12, v[72:73]
	v_lshlrev_b64 v[74:75], 12, v[74:75]
	v_lshlrev_b64 v[76:77], 12, v[76:77]
	v_lshlrev_b64 v[78:79], 12, v[78:79]
	v_lshl_add_u64 v[26:27], v[80:81], 0, v[26:27]
	v_lshl_add_u64 v[28:29], v[80:81], 0, v[28:29]
	v_lshl_add_u64 v[30:31], v[80:81], 0, v[30:31]
	v_lshl_add_u64 v[40:41], v[80:81], 0, v[40:41]
	v_lshl_add_u64 v[42:43], v[80:81], 0, v[42:43]
	v_lshl_add_u64 v[44:45], v[80:81], 0, v[44:45]
	v_lshl_add_u64 v[46:47], v[80:81], 0, v[46:47]
	v_lshl_add_u64 v[18:19], v[80:81], 0, v[18:19]
	v_lshl_add_u64 v[20:21], v[80:81], 0, v[20:21]
	v_lshl_add_u64 v[22:23], v[80:81], 0, v[22:23]
	v_lshl_add_u64 v[24:25], v[80:81], 0, v[24:25]
	v_lshl_add_u64 v[32:33], v[80:81], 0, v[32:33]
	v_lshl_add_u64 v[34:35], v[80:81], 0, v[34:35]
	v_lshl_add_u64 v[36:37], v[80:81], 0, v[36:37]
	v_lshl_add_u64 v[38:39], v[80:81], 0, v[38:39]
	v_lshl_add_u64 v[48:49], v[80:81], 0, v[48:49]
	v_lshl_add_u64 v[50:51], v[80:81], 0, v[50:51]
	v_lshl_add_u64 v[52:53], v[80:81], 0, v[52:53]
	v_lshl_add_u64 v[54:55], v[80:81], 0, v[54:55]
	v_lshl_add_u64 v[56:57], v[80:81], 0, v[56:57]
	v_lshl_add_u64 v[58:59], v[80:81], 0, v[58:59]
	v_lshl_add_u64 v[60:61], v[80:81], 0, v[60:61]
	v_lshl_add_u64 v[62:63], v[80:81], 0, v[62:63]
	v_lshl_add_u64 v[64:65], v[80:81], 0, v[64:65]
	v_lshl_add_u64 v[66:67], v[80:81], 0, v[66:67]
	v_lshl_add_u64 v[68:69], v[80:81], 0, v[68:69]
	v_lshl_add_u64 v[70:71], v[80:81], 0, v[70:71]
	v_lshl_add_u64 v[72:73], v[80:81], 0, v[72:73]
	v_lshl_add_u64 v[74:75], v[80:81], 0, v[74:75]
	v_lshl_add_u64 v[76:77], v[80:81], 0, v[76:77]
	v_lshl_add_u64 v[78:79], v[80:81], 0, v[78:79]
	global_load_dword v15, v[16:17], off nt
	global_load_dword v80, v[18:19], off nt
	global_load_dword v81, v[20:21], off nt
	global_load_dword v82, v[22:23], off nt
	global_load_dword v83, v[24:25], off nt
	global_load_dword v84, v[26:27], off nt
	global_load_dword v85, v[28:29], off nt
	global_load_dword v86, v[30:31], off nt
	global_load_dword v87, v[32:33], off nt
	global_load_dword v88, v[34:35], off nt
	global_load_dword v89, v[36:37], off nt
	global_load_dword v90, v[38:39], off nt
	global_load_dword v91, v[40:41], off nt
	global_load_dword v92, v[42:43], off nt
	global_load_dword v93, v[44:45], off nt
	global_load_dword v26, v[46:47], off nt
	global_load_dword v27, v[48:49], off nt
	global_load_dword v28, v[50:51], off nt
	global_load_dword v29, v[52:53], off nt
	global_load_dword v30, v[54:55], off nt
	global_load_dword v31, v[56:57], off nt
	global_load_dword v40, v[58:59], off nt
	global_load_dword v41, v[60:61], off nt
	global_load_dword v42, v[62:63], off nt
	global_load_dword v43, v[64:65], off nt
	global_load_dword v44, v[66:67], off nt
	global_load_dword v45, v[68:69], off nt
	global_load_dword v94, v[70:71], off nt
	global_load_dword v95, v[72:73], off nt
	global_load_dword v96, v[74:75], off nt
	global_load_dword v46, v[76:77], off nt
	global_load_dword v47, v[78:79], off nt
	s_mul_i32 s8, s5, 0xffa80000
	v_add_u32_e32 v16, s8, v7
	s_ashr_i32 s5, s4, 31
	v_add_u32_e32 v20, 0xb000, v16
	v_add_u32_e32 v22, 0x16000, v16
	v_add_u32_e32 v24, 0x21000, v16
	v_lshl_add_u64 v[18:19], s[4:5], 1, v[2:3]
	v_ashrrev_i32_e32 v21, 31, v20
	v_ashrrev_i32_e32 v23, 31, v22
	v_ashrrev_i32_e32 v25, 31, v24
	s_waitcnt vmcnt(30)
	ds_write2_b32 v5, v15, v80 offset1:66
	s_waitcnt vmcnt(28)
	ds_write2_b32 v5, v81, v82 offset0:132 offset1:198
	s_waitcnt vmcnt(26)
	ds_write2_b32 v8, v83, v84 offset0:8 offset1:74
	s_waitcnt vmcnt(24)
	ds_write2_b32 v8, v85, v86 offset0:140 offset1:206
	s_waitcnt vmcnt(22)
	ds_write2_b32 v9, v87, v88 offset0:16 offset1:82
	s_waitcnt vmcnt(20)
	ds_write2_b32 v9, v89, v90 offset0:148 offset1:214
	s_waitcnt vmcnt(18)
	ds_write2_b32 v10, v91, v92 offset0:24 offset1:90
	s_waitcnt vmcnt(16)
	ds_write2_b32 v10, v93, v26 offset0:156 offset1:222
	s_waitcnt vmcnt(14)
	ds_write2_b32 v11, v27, v28 offset0:32 offset1:98
	s_waitcnt vmcnt(12)
	ds_write2_b32 v11, v29, v30 offset0:164 offset1:230
	s_waitcnt vmcnt(10)
	ds_write2_b32 v12, v31, v40 offset0:40 offset1:106
	s_waitcnt vmcnt(8)
	ds_write2_b32 v12, v41, v42 offset0:172 offset1:238
	s_waitcnt vmcnt(6)
	ds_write2_b32 v13, v43, v44 offset0:48 offset1:114
	s_waitcnt vmcnt(4)
	ds_write2_b32 v13, v45, v94 offset0:180 offset1:246
	s_waitcnt vmcnt(2)
	ds_write2_b32 v14, v95, v96 offset0:56 offset1:122
	s_waitcnt vmcnt(0)
	ds_write2_b32 v14, v46, v47 offset0:188 offset1:254
	s_waitcnt lgkmcnt(0)
	v_lshl_add_u64 v[34:35], v[18:19], 0, v[20:21]
	v_lshl_add_u64 v[36:37], v[18:19], 0, v[22:23]
	v_lshl_add_u64 v[38:39], v[18:19], 0, v[24:25]
	ds_read2_b32 v[20:21], v6 offset0:33 offset1:41
	ds_read2_b32 v[22:23], v6 offset1:8
	ds_read2_b32 v[24:25], v6 offset0:66 offset1:74
	ds_read2_b32 v[26:27], v6 offset0:99 offset1:107
	ds_read2_b32 v[28:29], v6 offset0:132 offset1:140
	ds_read2_b32 v[30:31], v6 offset0:165 offset1:173
	ds_read2_b32 v[40:41], v6 offset0:198 offset1:206
	ds_read2_b32 v[42:43], v6 offset0:231 offset1:239
	ds_read2_b32 v[44:45], v6 offset0:49 offset1:57
	ds_read2_b32 v[46:47], v6 offset0:16 offset1:24
	ds_read2_b32 v[48:49], v6 offset0:82 offset1:90
	ds_read2_b32 v[50:51], v6 offset0:115 offset1:123
	ds_read2_b32 v[52:53], v6 offset0:148 offset1:156
	ds_read2_b32 v[54:55], v6 offset0:181 offset1:189
	ds_read2_b32 v[56:57], v6 offset0:214 offset1:222
	ds_read2_b32 v[58:59], v6 offset0:247 offset1:255
	v_ashrrev_i32_e32 v17, 31, v16
	v_lshl_add_u64 v[32:33], v[18:19], 0, v[16:17]
	s_waitcnt lgkmcnt(14)
	v_cvt_pk_bf16_f32 v16, v22, v20
	s_waitcnt lgkmcnt(12)
	v_cvt_pk_bf16_f32 v17, v24, v26
	s_waitcnt lgkmcnt(10)
	v_cvt_pk_bf16_f32 v18, v28, v30
	s_waitcnt lgkmcnt(8)
	v_cvt_pk_bf16_f32 v19, v40, v42
	v_cvt_pk_bf16_f32 v20, v23, v21
	v_cvt_pk_bf16_f32 v21, v25, v27
	v_cvt_pk_bf16_f32 v22, v29, v31
	v_cvt_pk_bf16_f32 v23, v41, v43
	s_waitcnt lgkmcnt(6)
	v_cvt_pk_bf16_f32 v24, v46, v44
	s_waitcnt lgkmcnt(4)
	v_cvt_pk_bf16_f32 v25, v48, v50
	s_waitcnt lgkmcnt(2)
	v_cvt_pk_bf16_f32 v26, v52, v54
	s_waitcnt lgkmcnt(0)
	v_cvt_pk_bf16_f32 v27, v56, v58
	v_cvt_pk_bf16_f32 v28, v47, v45
	v_cvt_pk_bf16_f32 v29, v49, v51
	v_cvt_pk_bf16_f32 v30, v53, v55
	v_cvt_pk_bf16_f32 v31, v57, v59
	global_store_dwordx4 v[32:33], v[16:19], off
	global_store_dwordx4 v[34:35], v[20:23], off
	global_store_dwordx4 v[36:37], v[24:27], off
	global_store_dwordx4 v[38:39], v[28:31], off
	s_waitcnt lgkmcnt(0)
	s_add_i32 s10, s10, s11
	s_add_i32 s13, s13, s16
	s_cmpk_gt_i32 s10, 0x57f
	v_add_u32_e32 v7, s12, v7
	s_cbranch_scc0 .LBB0_1207

.LBB0_1213:
	s_ashr_i32 s2, s8, 31
	s_lshr_b32 s2, s2, 27
	s_add_i32 s2, s8, s2
	s_ashr_i32 s3, s2, 5
	s_lshl_b32 s2, s3, 6
	s_lshl_b32 s4, s3, 10
	s_waitcnt vmcnt(0)
	v_or_b32_e32 v16, s2, v4
	s_sub_i32 s4, s10, s4
	v_or_b32_e32 v26, 10, v16
	v_or_b32_e32 v28, 12, v16
	v_or_b32_e32 v30, 14, v16
	v_or_b32_e32 v40, 24, v16
	v_or_b32_e32 v42, 26, v16
	v_or_b32_e32 v44, 28, v16
	v_or_b32_e32 v46, 30, v16
	s_ashr_i32 s5, s4, 31
	v_ashrrev_i32_e32 v17, 31, v16
	v_or_b32_e32 v18, 2, v16
	v_or_b32_e32 v20, 4, v16
	v_or_b32_e32 v22, 6, v16
	v_or_b32_e32 v24, 8, v16
	v_or_b32_e32 v32, 16, v16
	v_or_b32_e32 v34, 18, v16
	v_or_b32_e32 v36, 20, v16
	v_or_b32_e32 v38, 22, v16
	v_or_b32_e32 v48, 32, v16
	v_or_b32_e32 v50, 34, v16
	v_or_b32_e32 v52, 36, v16
	v_or_b32_e32 v54, 38, v16
	v_or_b32_e32 v56, 40, v16
	v_or_b32_e32 v58, 42, v16
	v_or_b32_e32 v60, 44, v16
	v_or_b32_e32 v62, 46, v16
	v_or_b32_e32 v64, 48, v16
	v_or_b32_e32 v66, 50, v16
	v_or_b32_e32 v68, 52, v16
	v_or_b32_e32 v70, 54, v16
	v_or_b32_e32 v72, 56, v16
	v_or_b32_e32 v74, 58, v16
	v_or_b32_e32 v76, 60, v16
	v_or_b32_e32 v78, 62, v16
	v_ashrrev_i32_e32 v27, 31, v26
	v_ashrrev_i32_e32 v29, 31, v28
	v_ashrrev_i32_e32 v31, 31, v30
	v_ashrrev_i32_e32 v41, 31, v40
	v_ashrrev_i32_e32 v43, 31, v42
	v_ashrrev_i32_e32 v45, 31, v44
	v_ashrrev_i32_e32 v47, 31, v46
	v_lshl_add_u64 v[80:81], s[4:5], 2, v[0:1]
	v_lshlrev_b64 v[16:17], 12, v[16:17]
	v_ashrrev_i32_e32 v19, 31, v18
	v_ashrrev_i32_e32 v21, 31, v20
	v_ashrrev_i32_e32 v23, 31, v22
	v_ashrrev_i32_e32 v25, 31, v24
	v_ashrrev_i32_e32 v33, 31, v32
	v_ashrrev_i32_e32 v35, 31, v34
	v_ashrrev_i32_e32 v37, 31, v36
	v_ashrrev_i32_e32 v39, 31, v38
	v_ashrrev_i32_e32 v49, 31, v48
	v_ashrrev_i32_e32 v51, 31, v50
	v_ashrrev_i32_e32 v53, 31, v52
	v_ashrrev_i32_e32 v55, 31, v54
	v_ashrrev_i32_e32 v57, 31, v56
	v_ashrrev_i32_e32 v59, 31, v58
	v_ashrrev_i32_e32 v61, 31, v60
	v_ashrrev_i32_e32 v63, 31, v62
	v_ashrrev_i32_e32 v65, 31, v64
	v_ashrrev_i32_e32 v67, 31, v66
	v_ashrrev_i32_e32 v69, 31, v68
	v_ashrrev_i32_e32 v71, 31, v70
	v_ashrrev_i32_e32 v73, 31, v72
	v_ashrrev_i32_e32 v75, 31, v74
	v_ashrrev_i32_e32 v77, 31, v76
	v_ashrrev_i32_e32 v79, 31, v78
	v_lshlrev_b64 v[26:27], 12, v[26:27]
	v_lshlrev_b64 v[28:29], 12, v[28:29]
	v_lshlrev_b64 v[30:31], 12, v[30:31]
	v_lshlrev_b64 v[40:41], 12, v[40:41]
	v_lshlrev_b64 v[42:43], 12, v[42:43]
	v_lshlrev_b64 v[44:45], 12, v[44:45]
	v_lshlrev_b64 v[46:47], 12, v[46:47]
	v_lshl_add_u64 v[16:17], v[80:81], 0, v[16:17]
	v_lshlrev_b64 v[18:19], 12, v[18:19]
	v_lshlrev_b64 v[20:21], 12, v[20:21]
	v_lshlrev_b64 v[22:23], 12, v[22:23]
	v_lshlrev_b64 v[24:25], 12, v[24:25]
	v_lshlrev_b64 v[32:33], 12, v[32:33]
	v_lshlrev_b64 v[34:35], 12, v[34:35]
	v_lshlrev_b64 v[36:37], 12, v[36:37]
	v_lshlrev_b64 v[38:39], 12, v[38:39]
	v_lshlrev_b64 v[48:49], 12, v[48:49]
	v_lshlrev_b64 v[50:51], 12, v[50:51]
	v_lshlrev_b64 v[52:53], 12, v[52:53]
	v_lshlrev_b64 v[54:55], 12, v[54:55]
	v_lshlrev_b64 v[56:57], 12, v[56:57]
	v_lshlrev_b64 v[58:59], 12, v[58:59]
	v_lshlrev_b64 v[60:61], 12, v[60:61]
	v_lshlrev_b64 v[62:63], 12, v[62:63]
	v_lshlrev_b64 v[64:65], 12, v[64:65]
	v_lshlrev_b64 v[66:67], 12, v[66:67]
	v_lshlrev_b64 v[68:69], 12, v[68:69]
	v_lshlrev_b64 v[70:71], 12, v[70:71]
	v_lshlrev_b64 v[72:73], 12, v[72:73]
	v_lshlrev_b64 v[74:75], 12, v[74:75]
	v_lshlrev_b64 v[76:77], 12, v[76:77]
	v_lshlrev_b64 v[78:79], 12, v[78:79]
	v_lshl_add_u64 v[26:27], v[80:81], 0, v[26:27]
	v_lshl_add_u64 v[28:29], v[80:81], 0, v[28:29]
	v_lshl_add_u64 v[30:31], v[80:81], 0, v[30:31]
	v_lshl_add_u64 v[40:41], v[80:81], 0, v[40:41]
	v_lshl_add_u64 v[42:43], v[80:81], 0, v[42:43]
	v_lshl_add_u64 v[44:45], v[80:81], 0, v[44:45]
	v_lshl_add_u64 v[46:47], v[80:81], 0, v[46:47]
	v_lshl_add_u64 v[18:19], v[80:81], 0, v[18:19]
	v_lshl_add_u64 v[20:21], v[80:81], 0, v[20:21]
	v_lshl_add_u64 v[22:23], v[80:81], 0, v[22:23]
	v_lshl_add_u64 v[24:25], v[80:81], 0, v[24:25]
	v_lshl_add_u64 v[32:33], v[80:81], 0, v[32:33]
	v_lshl_add_u64 v[34:35], v[80:81], 0, v[34:35]
	v_lshl_add_u64 v[36:37], v[80:81], 0, v[36:37]
	v_lshl_add_u64 v[38:39], v[80:81], 0, v[38:39]
	v_lshl_add_u64 v[48:49], v[80:81], 0, v[48:49]
	v_lshl_add_u64 v[50:51], v[80:81], 0, v[50:51]
	v_lshl_add_u64 v[52:53], v[80:81], 0, v[52:53]
	v_lshl_add_u64 v[54:55], v[80:81], 0, v[54:55]
	v_lshl_add_u64 v[56:57], v[80:81], 0, v[56:57]
	v_lshl_add_u64 v[58:59], v[80:81], 0, v[58:59]
	v_lshl_add_u64 v[60:61], v[80:81], 0, v[60:61]
	v_lshl_add_u64 v[62:63], v[80:81], 0, v[62:63]
	v_lshl_add_u64 v[64:65], v[80:81], 0, v[64:65]
	v_lshl_add_u64 v[66:67], v[80:81], 0, v[66:67]
	v_lshl_add_u64 v[68:69], v[80:81], 0, v[68:69]
	v_lshl_add_u64 v[70:71], v[80:81], 0, v[70:71]
	v_lshl_add_u64 v[72:73], v[80:81], 0, v[72:73]
	v_lshl_add_u64 v[74:75], v[80:81], 0, v[74:75]
	v_lshl_add_u64 v[76:77], v[80:81], 0, v[76:77]
	v_lshl_add_u64 v[78:79], v[80:81], 0, v[78:79]
	global_load_dword v15, v[16:17], off nt
	global_load_dword v80, v[18:19], off nt
	global_load_dword v81, v[20:21], off nt
	global_load_dword v82, v[22:23], off nt
	global_load_dword v83, v[24:25], off nt
	global_load_dword v84, v[26:27], off nt
	global_load_dword v85, v[28:29], off nt
	global_load_dword v86, v[30:31], off nt
	global_load_dword v87, v[32:33], off nt
	global_load_dword v88, v[34:35], off nt
	global_load_dword v89, v[36:37], off nt
	global_load_dword v90, v[38:39], off nt
	global_load_dword v91, v[40:41], off nt
	global_load_dword v92, v[42:43], off nt
	global_load_dword v93, v[44:45], off nt
	global_load_dword v26, v[46:47], off nt
	global_load_dword v27, v[48:49], off nt
	global_load_dword v28, v[50:51], off nt
	global_load_dword v29, v[52:53], off nt
	global_load_dword v30, v[54:55], off nt
	global_load_dword v31, v[56:57], off nt
	global_load_dword v40, v[58:59], off nt
	global_load_dword v41, v[60:61], off nt
	global_load_dword v42, v[62:63], off nt
	global_load_dword v43, v[64:65], off nt
	global_load_dword v44, v[66:67], off nt
	global_load_dword v45, v[68:69], off nt
	global_load_dword v94, v[70:71], off nt
	global_load_dword v95, v[72:73], off nt
	global_load_dword v96, v[74:75], off nt
	global_load_dword v46, v[76:77], off nt
	global_load_dword v47, v[78:79], off nt
	s_mul_i32 s4, s3, 0xffa80000
	v_add_u32_e32 v16, s4, v7
	s_ashr_i32 s3, s2, 31
	v_add_u32_e32 v20, 0xb000, v16
	v_add_u32_e32 v22, 0x16000, v16
	v_add_u32_e32 v24, 0x21000, v16
	v_lshl_add_u64 v[18:19], s[2:3], 1, v[2:3]
	v_ashrrev_i32_e32 v21, 31, v20
	v_ashrrev_i32_e32 v23, 31, v22
	v_ashrrev_i32_e32 v25, 31, v24
	s_waitcnt vmcnt(30)
	ds_write2_b32 v5, v15, v80 offset1:66
	s_waitcnt vmcnt(28)
	ds_write2_b32 v5, v81, v82 offset0:132 offset1:198
	s_waitcnt vmcnt(26)
	ds_write2_b32 v8, v83, v84 offset0:8 offset1:74
	s_waitcnt vmcnt(24)
	ds_write2_b32 v8, v85, v86 offset0:140 offset1:206
	s_waitcnt vmcnt(22)
	ds_write2_b32 v9, v87, v88 offset0:16 offset1:82
	s_waitcnt vmcnt(20)
	ds_write2_b32 v9, v89, v90 offset0:148 offset1:214
	s_waitcnt vmcnt(18)
	ds_write2_b32 v10, v91, v92 offset0:24 offset1:90
	s_waitcnt vmcnt(16)
	ds_write2_b32 v10, v93, v26 offset0:156 offset1:222
	s_waitcnt vmcnt(14)
	ds_write2_b32 v11, v27, v28 offset0:32 offset1:98
	s_waitcnt vmcnt(12)
	ds_write2_b32 v11, v29, v30 offset0:164 offset1:230
	s_waitcnt vmcnt(10)
	ds_write2_b32 v12, v31, v40 offset0:40 offset1:106
	s_waitcnt vmcnt(8)
	ds_write2_b32 v12, v41, v42 offset0:172 offset1:238
	s_waitcnt vmcnt(6)
	ds_write2_b32 v13, v43, v44 offset0:48 offset1:114
	s_waitcnt vmcnt(4)
	ds_write2_b32 v13, v45, v94 offset0:180 offset1:246
	s_waitcnt vmcnt(2)
	ds_write2_b32 v14, v95, v96 offset0:56 offset1:122
	s_waitcnt vmcnt(0)
	ds_write2_b32 v14, v46, v47 offset0:188 offset1:254
	s_waitcnt lgkmcnt(0)
	v_lshl_add_u64 v[34:35], v[18:19], 0, v[20:21]
	v_lshl_add_u64 v[36:37], v[18:19], 0, v[22:23]
	v_lshl_add_u64 v[38:39], v[18:19], 0, v[24:25]
	ds_read2_b32 v[20:21], v6 offset0:33 offset1:41
	ds_read2_b32 v[22:23], v6 offset1:8
	ds_read2_b32 v[24:25], v6 offset0:66 offset1:74
	ds_read2_b32 v[26:27], v6 offset0:99 offset1:107
	ds_read2_b32 v[28:29], v6 offset0:132 offset1:140
	ds_read2_b32 v[30:31], v6 offset0:165 offset1:173
	ds_read2_b32 v[40:41], v6 offset0:198 offset1:206
	ds_read2_b32 v[42:43], v6 offset0:231 offset1:239
	ds_read2_b32 v[44:45], v6 offset0:49 offset1:57
	ds_read2_b32 v[46:47], v6 offset0:16 offset1:24
	ds_read2_b32 v[48:49], v6 offset0:82 offset1:90
	ds_read2_b32 v[50:51], v6 offset0:115 offset1:123
	ds_read2_b32 v[52:53], v6 offset0:148 offset1:156
	ds_read2_b32 v[54:55], v6 offset0:181 offset1:189
	ds_read2_b32 v[56:57], v6 offset0:214 offset1:222
	ds_read2_b32 v[58:59], v6 offset0:247 offset1:255
	v_ashrrev_i32_e32 v17, 31, v16
	v_lshl_add_u64 v[32:33], v[18:19], 0, v[16:17]
	s_waitcnt lgkmcnt(14)
	v_cvt_pk_bf16_f32 v16, v22, v20
	s_waitcnt lgkmcnt(12)
	v_cvt_pk_bf16_f32 v17, v24, v26
	s_waitcnt lgkmcnt(10)
	v_cvt_pk_bf16_f32 v18, v28, v30
	s_waitcnt lgkmcnt(8)
	v_cvt_pk_bf16_f32 v19, v40, v42
	v_cvt_pk_bf16_f32 v20, v23, v21
	v_cvt_pk_bf16_f32 v21, v25, v27
	v_cvt_pk_bf16_f32 v22, v29, v31
	v_cvt_pk_bf16_f32 v23, v41, v43
	s_waitcnt lgkmcnt(6)
	v_cvt_pk_bf16_f32 v24, v46, v44
	s_waitcnt lgkmcnt(4)
	v_cvt_pk_bf16_f32 v25, v48, v50
	s_waitcnt lgkmcnt(2)
	v_cvt_pk_bf16_f32 v26, v52, v54
	s_waitcnt lgkmcnt(0)
	v_cvt_pk_bf16_f32 v27, v56, v58
	v_cvt_pk_bf16_f32 v28, v47, v45
	v_cvt_pk_bf16_f32 v29, v49, v51
	v_cvt_pk_bf16_f32 v30, v53, v55
	v_cvt_pk_bf16_f32 v31, v57, v59
	global_store_dwordx4 v[32:33], v[16:19], off
	global_store_dwordx4 v[34:35], v[20:23], off
	global_store_dwordx4 v[36:37], v[24:27], off
	global_store_dwordx4 v[38:39], v[28:31], off
	s_waitcnt lgkmcnt(0)
	s_add_i32 s8, s8, s12
	s_add_i32 s10, s10, s11
	s_cmpk_gt_i32 s8, 0x57f
	v_add_u32_e32 v7, s9, v7
	s_cbranch_scc0 .LBB0_1213

.LBB0_1307:
	v_mov_b32_e32 v169, v192
	s_waitcnt vmcnt(0)
	s_barrier
	s_lshl_b32 s8, s14, 8
	v_readfirstlane_b32 s24, v169
	s_ashr_i32 s12, s24, 6
	s_and_b32 s11, s12, 3
	s_lshl_b32 s9, s11, 5
	s_or_b32 s8, s9, s8
	v_lshrrev_b32_e32 v128, 2, v169
	v_and_or_b32 v156, v128, 12, s8
	s_ashr_i32 s8, s45, 5
	s_mul_hi_i32 s9, s8, 0x6000
	s_mulk_i32 s8, 0x6000
	s_add_u32 s8, s2, s8
	s_addc_u32 s9, s3, s9
	s_add_u32 s8, s8, 0x2385000
	s_addc_u32 s9, s9, 0
	v_and_b32_e32 v168, 15, v169
	s_ashr_i32 s10, s24, 8
	s_lshl_b32 s25, s45, 8
	s_lshl_b32 s26, s10, 6
	v_or_b32_e32 v144, s25, v168
	v_add_u32_e32 v164, s26, v144
	v_ashrrev_i32_e32 v165, 31, v164
	v_ashrrev_i32_e32 v157, 31, v156
	v_lshlrev_b64 v[144:145], 11, v[164:165]
	v_lshlrev_b64 v[160:161], 2, v[156:157]
	v_lshl_add_u64 v[144:145], s[4:5], 0, v[144:145]
	v_lshlrev_b64 v[166:167], 1, v[156:157]
	v_lshl_add_u64 v[140:141], s[16:17], 0, v[160:161]
	v_lshl_add_u64 v[144:145], v[144:145], 0, v[166:167]
	v_or_b32_e32 v148, 16, v156
	v_or_b32_e32 v150, 0x80, v156
	v_or_b32_e32 v156, 0x90, v156
	global_load_dwordx4 v[128:131], v[140:141], off
	global_load_dwordx4 v[136:139], v[140:141], off offset:64
	global_load_dwordx4 v[132:135], v[140:141], off offset:512
	s_nop 0
	global_load_dwordx4 v[140:143], v[140:141], off offset:576
	s_nop 0
	global_load_dwordx2 v[162:163], v[144:145], off nt
	global_load_dwordx2 v[170:171], v[144:145], off offset:32 nt
	global_load_dwordx2 v[172:173], v[144:145], off offset:256 nt
	global_load_dwordx2 v[174:175], v[144:145], off offset:288 nt
	v_ashrrev_i32_e32 v149, 31, v148
	v_ashrrev_i32_e32 v151, 31, v150
	v_ashrrev_i32_e32 v157, 31, v156
	v_lshl_add_u64 v[144:145], s[8:9], 0, v[160:161]
	v_lshl_add_u64 v[148:149], v[148:149], 2, s[8:9]
	v_lshl_add_u64 v[150:151], v[150:151], 2, s[8:9]
	v_lshl_add_u64 v[156:157], v[156:157], 2, s[8:9]
	global_load_dwordx4 v[144:147], v[144:145], off
	s_nop 0
	global_load_dwordx4 v[152:155], v[148:149], off
	s_nop 0
	global_load_dwordx4 v[148:151], v[150:151], off
	v_or_b32_e32 v176, 16, v164
	global_load_dwordx4 v[156:159], v[156:157], off
	v_ashrrev_i32_e32 v177, 31, v176
	s_mov_b32 s8, 0x3f9837f0
	v_lshlrev_b64 v[176:177], 11, v[176:177]
	v_lshl_add_u64 v[176:177], s[4:5], 0, v[176:177]
	s_waitcnt vmcnt(0)
	v_pk_add_f32 v[122:123], v[122:123], v[130:131]
	v_lshlrev_b32_e32 v178, 16, v162
	v_and_b32_e32 v179, 0xffff0000, v162
	v_lshlrev_b32_e32 v162, 16, v163
	v_and_b32_e32 v163, 0xffff0000, v163
	v_lshlrev_b32_e32 v180, 16, v170
	v_and_b32_e32 v181, 0xffff0000, v170
	v_lshlrev_b32_e32 v170, 16, v171
	v_and_b32_e32 v171, 0xffff0000, v171
	v_lshlrev_b32_e32 v182, 16, v172
	v_and_b32_e32 v183, 0xffff0000, v172
	v_lshlrev_b32_e32 v172, 16, v173
	v_and_b32_e32 v173, 0xffff0000, v173
	v_lshlrev_b32_e32 v184, 16, v174
	v_and_b32_e32 v185, 0xffff0000, v174
	v_lshlrev_b32_e32 v174, 16, v175
	v_and_b32_e32 v175, 0xffff0000, v175
	v_pk_add_f32 v[120:121], v[120:121], v[128:129]
	v_pk_add_f32 v[102:103], v[102:103], v[138:139]
	v_pk_add_f32 v[100:101], v[100:101], v[136:137]
	v_pk_add_f32 v[74:75], v[74:75], v[134:135]
	v_pk_add_f32 v[72:73], v[72:73], v[132:133]
	v_pk_add_f32 v[50:51], v[50:51], v[142:143]
	v_pk_add_f32 v[48:49], v[48:49], v[140:141]
	v_pk_mul_f32 v[178:179], v[178:179], s[8:9] op_sel_hi:[1,0]
	v_pk_mul_f32 v[162:163], v[162:163], s[8:9] op_sel_hi:[1,0]
	v_pk_mul_f32 v[180:181], v[180:181], s[8:9] op_sel_hi:[1,0]
	v_pk_mul_f32 v[170:171], v[170:171], s[8:9] op_sel_hi:[1,0]
	v_pk_mul_f32 v[182:183], v[182:183], s[8:9] op_sel_hi:[1,0]
	v_pk_mul_f32 v[172:173], v[172:173], s[8:9] op_sel_hi:[1,0]
	v_pk_mul_f32 v[184:185], v[184:185], s[8:9] op_sel_hi:[1,0]
	v_pk_mul_f32 v[174:175], v[174:175], s[8:9] op_sel_hi:[1,0]
	v_pk_fma_f32 v[122:123], v[146:147], v[122:123], v[162:163]
	v_pk_fma_f32 v[120:121], v[144:145], v[120:121], v[178:179]
	v_pk_fma_f32 v[102:103], v[154:155], v[102:103], v[170:171]
	v_pk_fma_f32 v[100:101], v[152:153], v[100:101], v[180:181]
	v_pk_fma_f32 v[74:75], v[150:151], v[74:75], v[172:173]
	v_pk_fma_f32 v[72:73], v[148:149], v[72:73], v[182:183]
	v_pk_fma_f32 v[50:51], v[158:159], v[50:51], v[174:175]
	v_pk_fma_f32 v[48:49], v[156:157], v[48:49], v[184:185]
	v_lshl_add_u64 v[162:163], v[176:177], 0, v[166:167]
	global_load_dwordx2 v[170:171], v[162:163], off nt
	global_load_dwordx2 v[172:173], v[162:163], off offset:32 nt
	global_load_dwordx2 v[174:175], v[162:163], off offset:256 nt
	s_nop 0
	global_load_dwordx2 v[162:163], v[162:163], off offset:288 nt
	v_or_b32_e32 v176, 32, v164
	v_ashrrev_i32_e32 v177, 31, v176
	v_lshlrev_b64 v[176:177], 11, v[176:177]
	v_pk_add_f32 v[126:127], v[126:127], v[130:131]
	v_pk_add_f32 v[124:125], v[124:125], v[128:129]
	v_pk_add_f32 v[110:111], v[110:111], v[138:139]
	v_pk_add_f32 v[108:109], v[108:109], v[136:137]
	v_pk_add_f32 v[90:91], v[90:91], v[134:135]
	v_pk_add_f32 v[88:89], v[88:89], v[132:133]
	v_pk_add_f32 v[70:71], v[70:71], v[142:143]
	v_pk_add_f32 v[68:69], v[68:69], v[140:141]
	v_lshl_add_u64 v[176:177], s[4:5], 0, v[176:177]
	v_lshl_add_u64 v[176:177], v[176:177], 0, v[166:167]
	v_pk_add_f32 v[118:119], v[118:119], v[130:131]
	v_pk_add_f32 v[116:117], v[116:117], v[128:129]
	v_pk_add_f32 v[114:115], v[114:115], v[138:139]
	v_pk_add_f32 v[112:113], v[112:113], v[136:137]
	v_pk_add_f32 v[106:107], v[106:107], v[134:135]
	v_pk_add_f32 v[104:105], v[104:105], v[132:133]
	v_pk_add_f32 v[78:79], v[78:79], v[142:143]
	v_pk_add_f32 v[76:77], v[76:77], v[140:141]
	v_pk_add_f32 v[98:99], v[98:99], v[130:131]
	v_pk_add_f32 v[96:97], v[96:97], v[128:129]
	v_pk_add_f32 v[94:95], v[94:95], v[138:139]
	v_pk_add_f32 v[92:93], v[92:93], v[136:137]
	v_pk_add_f32 v[86:87], v[86:87], v[134:135]
	v_pk_add_f32 v[84:85], v[84:85], v[132:133]
	v_pk_add_f32 v[82:83], v[82:83], v[142:143]
	v_pk_add_f32 v[80:81], v[80:81], v[140:141]
	v_pk_add_f32 v[66:67], v[66:67], v[130:131]
	v_pk_add_f32 v[64:65], v[64:65], v[128:129]
	v_pk_add_f32 v[62:63], v[62:63], v[138:139]
	v_pk_add_f32 v[60:61], v[60:61], v[136:137]
	v_pk_add_f32 v[58:59], v[58:59], v[134:135]
	v_pk_add_f32 v[56:57], v[56:57], v[132:133]
	v_pk_add_f32 v[54:55], v[54:55], v[142:143]
	v_pk_add_f32 v[52:53], v[52:53], v[140:141]
	v_pk_add_f32 v[46:47], v[46:47], v[130:131]
	v_pk_add_f32 v[44:45], v[44:45], v[128:129]
	v_pk_add_f32 v[42:43], v[42:43], v[138:139]
	v_pk_add_f32 v[40:41], v[40:41], v[136:137]
	v_pk_add_f32 v[38:39], v[38:39], v[134:135]
	v_pk_add_f32 v[36:37], v[36:37], v[132:133]
	v_pk_add_f32 v[34:35], v[34:35], v[142:143]
	v_pk_add_f32 v[32:33], v[32:33], v[140:141]
	v_pk_add_f32 v[30:31], v[30:31], v[130:131]
	v_pk_add_f32 v[28:29], v[28:29], v[128:129]
	v_pk_add_f32 v[26:27], v[26:27], v[138:139]
	v_pk_add_f32 v[24:25], v[24:25], v[136:137]
	v_pk_add_f32 v[22:23], v[22:23], v[134:135]
	v_pk_add_f32 v[20:21], v[20:21], v[132:133]
	v_pk_add_f32 v[18:19], v[18:19], v[142:143]
	v_pk_add_f32 v[16:17], v[16:17], v[140:141]
	v_pk_add_f32 v[12:13], v[12:13], v[128:129]
	v_pk_add_f32 v[14:15], v[14:15], v[130:131]
	v_pk_add_f32 v[10:11], v[10:11], v[138:139]
	v_pk_add_f32 v[8:9], v[8:9], v[136:137]
	v_pk_add_f32 v[6:7], v[6:7], v[134:135]
	v_pk_add_f32 v[4:5], v[4:5], v[132:133]
	v_pk_add_f32 v[2:3], v[2:3], v[142:143]
	v_pk_add_f32 v[0:1], v[0:1], v[140:141]
	s_waitcnt vmcnt(3)
	v_lshlrev_b32_e32 v178, 16, v170
	v_and_b32_e32 v179, 0xffff0000, v170
	v_lshlrev_b32_e32 v170, 16, v171
	v_and_b32_e32 v171, 0xffff0000, v171
	s_waitcnt vmcnt(2)
	v_lshlrev_b32_e32 v180, 16, v172
	v_and_b32_e32 v181, 0xffff0000, v172
	v_lshlrev_b32_e32 v172, 16, v173
	v_and_b32_e32 v173, 0xffff0000, v173
	s_waitcnt vmcnt(1)
	v_lshlrev_b32_e32 v182, 16, v174
	v_and_b32_e32 v183, 0xffff0000, v174
	v_lshlrev_b32_e32 v174, 16, v175
	v_and_b32_e32 v175, 0xffff0000, v175
	s_waitcnt vmcnt(0)
	v_lshlrev_b32_e32 v184, 16, v162
	v_and_b32_e32 v185, 0xffff0000, v162
	v_lshlrev_b32_e32 v162, 16, v163
	v_and_b32_e32 v163, 0xffff0000, v163
	v_pk_mul_f32 v[178:179], v[178:179], s[8:9] op_sel_hi:[1,0]
	v_pk_mul_f32 v[170:171], v[170:171], s[8:9] op_sel_hi:[1,0]
	v_pk_mul_f32 v[180:181], v[180:181], s[8:9] op_sel_hi:[1,0]
	v_pk_mul_f32 v[172:173], v[172:173], s[8:9] op_sel_hi:[1,0]
	v_pk_mul_f32 v[182:183], v[182:183], s[8:9] op_sel_hi:[1,0]
	v_pk_mul_f32 v[174:175], v[174:175], s[8:9] op_sel_hi:[1,0]
	v_pk_mul_f32 v[184:185], v[184:185], s[8:9] op_sel_hi:[1,0]
	v_pk_mul_f32 v[162:163], v[162:163], s[8:9] op_sel_hi:[1,0]
	v_pk_fma_f32 v[126:127], v[146:147], v[126:127], v[170:171]
	v_pk_fma_f32 v[124:125], v[144:145], v[124:125], v[178:179]
	v_pk_fma_f32 v[110:111], v[154:155], v[110:111], v[172:173]
	v_pk_fma_f32 v[108:109], v[152:153], v[108:109], v[180:181]
	v_pk_fma_f32 v[90:91], v[150:151], v[90:91], v[174:175]
	v_pk_fma_f32 v[88:89], v[148:149], v[88:89], v[182:183]
	v_pk_fma_f32 v[70:71], v[158:159], v[70:71], v[162:163]
	v_pk_fma_f32 v[68:69], v[156:157], v[68:69], v[184:185]
	s_nop 0
	global_load_dwordx2 v[162:163], v[176:177], off nt
	global_load_dwordx2 v[170:171], v[176:177], off offset:32 nt
	global_load_dwordx2 v[172:173], v[176:177], off offset:256 nt
	global_load_dwordx2 v[174:175], v[176:177], off offset:288 nt
	v_or_b32_e32 v176, 48, v164
	v_ashrrev_i32_e32 v177, 31, v176
	v_lshlrev_b64 v[176:177], 11, v[176:177]
	v_lshl_add_u64 v[176:177], s[4:5], 0, v[176:177]
	v_lshl_add_u64 v[176:177], v[176:177], 0, v[166:167]
	s_waitcnt vmcnt(3)
	v_lshlrev_b32_e32 v178, 16, v162
	v_and_b32_e32 v179, 0xffff0000, v162
	v_lshlrev_b32_e32 v162, 16, v163
	v_and_b32_e32 v163, 0xffff0000, v163
	s_waitcnt vmcnt(2)
	v_lshlrev_b32_e32 v180, 16, v170
	v_and_b32_e32 v181, 0xffff0000, v170
	v_lshlrev_b32_e32 v170, 16, v171
	v_and_b32_e32 v171, 0xffff0000, v171
	s_waitcnt vmcnt(1)
	v_lshlrev_b32_e32 v182, 16, v172
	v_and_b32_e32 v183, 0xffff0000, v172
	v_lshlrev_b32_e32 v172, 16, v173
	v_and_b32_e32 v173, 0xffff0000, v173
	s_waitcnt vmcnt(0)
	v_lshlrev_b32_e32 v184, 16, v174
	v_and_b32_e32 v185, 0xffff0000, v174
	v_lshlrev_b32_e32 v174, 16, v175
	v_and_b32_e32 v175, 0xffff0000, v175
	v_pk_mul_f32 v[178:179], v[178:179], s[8:9] op_sel_hi:[1,0]
	v_pk_mul_f32 v[162:163], v[162:163], s[8:9] op_sel_hi:[1,0]
	v_pk_mul_f32 v[180:181], v[180:181], s[8:9] op_sel_hi:[1,0]
	v_pk_mul_f32 v[170:171], v[170:171], s[8:9] op_sel_hi:[1,0]
	v_pk_mul_f32 v[182:183], v[182:183], s[8:9] op_sel_hi:[1,0]
	v_pk_mul_f32 v[172:173], v[172:173], s[8:9] op_sel_hi:[1,0]
	v_pk_mul_f32 v[184:185], v[184:185], s[8:9] op_sel_hi:[1,0]
	v_pk_mul_f32 v[174:175], v[174:175], s[8:9] op_sel_hi:[1,0]
	v_pk_fma_f32 v[118:119], v[146:147], v[118:119], v[162:163]
	v_pk_fma_f32 v[116:117], v[144:145], v[116:117], v[178:179]
	v_pk_fma_f32 v[114:115], v[154:155], v[114:115], v[170:171]
	v_pk_fma_f32 v[112:113], v[152:153], v[112:113], v[180:181]
	v_pk_fma_f32 v[106:107], v[150:151], v[106:107], v[172:173]
	v_pk_fma_f32 v[104:105], v[148:149], v[104:105], v[182:183]
	v_pk_fma_f32 v[78:79], v[158:159], v[78:79], v[174:175]
	v_pk_fma_f32 v[76:77], v[156:157], v[76:77], v[184:185]
	s_nop 0
	global_load_dwordx2 v[162:163], v[176:177], off nt
	global_load_dwordx2 v[170:171], v[176:177], off offset:32 nt
	global_load_dwordx2 v[172:173], v[176:177], off offset:256 nt
	global_load_dwordx2 v[174:175], v[176:177], off offset:288 nt
	v_add_u32_e32 v176, 0x80, v164
	v_ashrrev_i32_e32 v177, 31, v176
	v_lshlrev_b64 v[176:177], 11, v[176:177]
	v_lshl_add_u64 v[176:177], s[4:5], 0, v[176:177]
	v_lshl_add_u64 v[176:177], v[176:177], 0, v[166:167]
	s_waitcnt vmcnt(3)
	v_lshlrev_b32_e32 v178, 16, v162
	v_and_b32_e32 v179, 0xffff0000, v162
	v_lshlrev_b32_e32 v162, 16, v163
	v_and_b32_e32 v163, 0xffff0000, v163
	s_waitcnt vmcnt(2)
	v_lshlrev_b32_e32 v180, 16, v170
	v_and_b32_e32 v181, 0xffff0000, v170
	v_lshlrev_b32_e32 v170, 16, v171
	v_and_b32_e32 v171, 0xffff0000, v171
	s_waitcnt vmcnt(1)
	v_lshlrev_b32_e32 v182, 16, v172
	v_and_b32_e32 v183, 0xffff0000, v172
	v_lshlrev_b32_e32 v172, 16, v173
	v_and_b32_e32 v173, 0xffff0000, v173
	s_waitcnt vmcnt(0)
	v_lshlrev_b32_e32 v184, 16, v174
	v_and_b32_e32 v185, 0xffff0000, v174
	v_lshlrev_b32_e32 v174, 16, v175
	v_and_b32_e32 v175, 0xffff0000, v175
	v_pk_mul_f32 v[178:179], v[178:179], s[8:9] op_sel_hi:[1,0]
	v_pk_mul_f32 v[162:163], v[162:163], s[8:9] op_sel_hi:[1,0]
	v_pk_mul_f32 v[180:181], v[180:181], s[8:9] op_sel_hi:[1,0]
	v_pk_mul_f32 v[170:171], v[170:171], s[8:9] op_sel_hi:[1,0]
	v_pk_mul_f32 v[182:183], v[182:183], s[8:9] op_sel_hi:[1,0]
	v_pk_mul_f32 v[172:173], v[172:173], s[8:9] op_sel_hi:[1,0]
	v_pk_mul_f32 v[184:185], v[184:185], s[8:9] op_sel_hi:[1,0]
	v_pk_mul_f32 v[174:175], v[174:175], s[8:9] op_sel_hi:[1,0]
	v_pk_fma_f32 v[98:99], v[146:147], v[98:99], v[162:163]
	v_pk_fma_f32 v[96:97], v[144:145], v[96:97], v[178:179]
	v_pk_fma_f32 v[94:95], v[154:155], v[94:95], v[170:171]
	v_pk_fma_f32 v[92:93], v[152:153], v[92:93], v[180:181]
	v_pk_fma_f32 v[86:87], v[150:151], v[86:87], v[172:173]
	v_pk_fma_f32 v[84:85], v[148:149], v[84:85], v[182:183]
	v_pk_fma_f32 v[82:83], v[158:159], v[82:83], v[174:175]
	v_pk_fma_f32 v[80:81], v[156:157], v[80:81], v[184:185]
	v_add_u32_e32 v162, 0x90, v164
	global_load_dwordx2 v[170:171], v[176:177], off nt
	global_load_dwordx2 v[172:173], v[176:177], off offset:32 nt
	global_load_dwordx2 v[174:175], v[176:177], off offset:256 nt
	s_nop 0
	global_load_dwordx2 v[176:177], v[176:177], off offset:288 nt
	v_ashrrev_i32_e32 v163, 31, v162
	v_lshlrev_b64 v[178:179], 11, v[162:163]
	v_lshl_add_u64 v[178:179], s[4:5], 0, v[178:179]
	v_lshl_add_u64 v[178:179], v[178:179], 0, v[166:167]
	s_waitcnt vmcnt(3)
	v_lshlrev_b32_e32 v180, 16, v170
	v_and_b32_e32 v181, 0xffff0000, v170
	v_lshlrev_b32_e32 v170, 16, v171
	v_and_b32_e32 v171, 0xffff0000, v171
	s_waitcnt vmcnt(2)
	v_lshlrev_b32_e32 v182, 16, v172
	v_and_b32_e32 v183, 0xffff0000, v172
	v_lshlrev_b32_e32 v172, 16, v173
	v_and_b32_e32 v173, 0xffff0000, v173
	s_waitcnt vmcnt(1)
	v_lshlrev_b32_e32 v184, 16, v174
	v_and_b32_e32 v185, 0xffff0000, v174
	v_lshlrev_b32_e32 v174, 16, v175
	v_and_b32_e32 v175, 0xffff0000, v175
	s_waitcnt vmcnt(0)
	v_lshlrev_b32_e32 v186, 16, v176
	v_and_b32_e32 v187, 0xffff0000, v176
	v_lshlrev_b32_e32 v176, 16, v177
	v_and_b32_e32 v177, 0xffff0000, v177
	v_pk_mul_f32 v[180:181], v[180:181], s[8:9] op_sel_hi:[1,0]
	v_pk_mul_f32 v[170:171], v[170:171], s[8:9] op_sel_hi:[1,0]
	v_pk_mul_f32 v[182:183], v[182:183], s[8:9] op_sel_hi:[1,0]
	v_pk_mul_f32 v[172:173], v[172:173], s[8:9] op_sel_hi:[1,0]
	v_pk_mul_f32 v[184:185], v[184:185], s[8:9] op_sel_hi:[1,0]
	v_pk_mul_f32 v[174:175], v[174:175], s[8:9] op_sel_hi:[1,0]
	v_pk_mul_f32 v[186:187], v[186:187], s[8:9] op_sel_hi:[1,0]
	v_pk_mul_f32 v[176:177], v[176:177], s[8:9] op_sel_hi:[1,0]
	v_pk_fma_f32 v[66:67], v[146:147], v[66:67], v[170:171]
	v_pk_fma_f32 v[64:65], v[144:145], v[64:65], v[180:181]
	v_pk_fma_f32 v[62:63], v[154:155], v[62:63], v[172:173]
	v_pk_fma_f32 v[60:61], v[152:153], v[60:61], v[182:183]
	v_pk_fma_f32 v[58:59], v[150:151], v[58:59], v[174:175]
	v_pk_fma_f32 v[56:57], v[148:149], v[56:57], v[184:185]
	v_pk_fma_f32 v[54:55], v[158:159], v[54:55], v[176:177]
	v_pk_fma_f32 v[52:53], v[156:157], v[52:53], v[186:187]
	s_nop 0
	global_load_dwordx2 v[170:171], v[178:179], off nt
	global_load_dwordx2 v[172:173], v[178:179], off offset:32 nt
	global_load_dwordx2 v[174:175], v[178:179], off offset:256 nt
	global_load_dwordx2 v[176:177], v[178:179], off offset:288 nt
	v_add_u32_e32 v178, 0xa0, v164
	v_ashrrev_i32_e32 v179, 31, v178
	v_lshlrev_b64 v[178:179], 11, v[178:179]
	v_lshl_add_u64 v[178:179], s[4:5], 0, v[178:179]
	v_lshl_add_u64 v[178:179], v[178:179], 0, v[166:167]
	v_add_u32_e32 v164, 0xb0, v164
	s_waitcnt vmcnt(3)
	v_lshlrev_b32_e32 v180, 16, v170
	v_and_b32_e32 v181, 0xffff0000, v170
	v_lshlrev_b32_e32 v170, 16, v171
	v_and_b32_e32 v171, 0xffff0000, v171
	s_waitcnt vmcnt(2)
	v_lshlrev_b32_e32 v182, 16, v172
	v_and_b32_e32 v183, 0xffff0000, v172
	v_lshlrev_b32_e32 v172, 16, v173
	v_and_b32_e32 v173, 0xffff0000, v173
	s_waitcnt vmcnt(1)
	v_lshlrev_b32_e32 v184, 16, v174
	v_and_b32_e32 v185, 0xffff0000, v174
	v_lshlrev_b32_e32 v174, 16, v175
	v_and_b32_e32 v175, 0xffff0000, v175
	s_waitcnt vmcnt(0)
	v_lshlrev_b32_e32 v186, 16, v176
	v_and_b32_e32 v187, 0xffff0000, v176
	v_lshlrev_b32_e32 v176, 16, v177
	v_and_b32_e32 v177, 0xffff0000, v177
	v_pk_mul_f32 v[180:181], v[180:181], s[8:9] op_sel_hi:[1,0]
	v_pk_mul_f32 v[170:171], v[170:171], s[8:9] op_sel_hi:[1,0]
	v_pk_mul_f32 v[182:183], v[182:183], s[8:9] op_sel_hi:[1,0]
	v_pk_mul_f32 v[172:173], v[172:173], s[8:9] op_sel_hi:[1,0]
	v_pk_mul_f32 v[184:185], v[184:185], s[8:9] op_sel_hi:[1,0]
	v_pk_mul_f32 v[174:175], v[174:175], s[8:9] op_sel_hi:[1,0]
	v_pk_mul_f32 v[186:187], v[186:187], s[8:9] op_sel_hi:[1,0]
	v_pk_mul_f32 v[176:177], v[176:177], s[8:9] op_sel_hi:[1,0]
	v_pk_fma_f32 v[46:47], v[146:147], v[46:47], v[170:171]
	v_pk_fma_f32 v[44:45], v[144:145], v[44:45], v[180:181]
	v_pk_fma_f32 v[42:43], v[154:155], v[42:43], v[172:173]
	v_pk_fma_f32 v[40:41], v[152:153], v[40:41], v[182:183]
	v_pk_fma_f32 v[38:39], v[150:151], v[38:39], v[174:175]
	v_pk_fma_f32 v[36:37], v[148:149], v[36:37], v[184:185]
	v_pk_fma_f32 v[34:35], v[158:159], v[34:35], v[176:177]
	v_pk_fma_f32 v[32:33], v[156:157], v[32:33], v[186:187]
	v_mbcnt_hi_u32_b32 v171, -1, v193
	global_load_dwordx2 v[172:173], v[178:179], off nt
	global_load_dwordx2 v[174:175], v[178:179], off offset:32 nt
	global_load_dwordx2 v[176:177], v[178:179], off offset:256 nt
	s_nop 0
	global_load_dwordx2 v[178:179], v[178:179], off offset:288 nt
	v_and_b32_e32 v170, 64, v171
	v_xor_b32_e32 v165, 16, v171
	v_add_u32_e32 v196, 64, v170
	v_cmp_lt_i32_e32 vcc, v165, v196
	v_mov_b32_e32 v182, v120
	v_mov_b32_e32 v183, v123
	v_cndmask_b32_e32 v165, v171, v165, vcc
	v_lshlrev_b32_e32 v170, 2, v165
	v_ashrrev_i32_e32 v165, 31, v164
	v_lshlrev_b64 v[180:181], 11, v[164:165]
	v_lshl_add_u64 v[180:181], s[4:5], 0, v[180:181]
	v_lshl_add_u64 v[166:167], v[180:181], 0, v[166:167]
	v_mov_b32_e32 v180, v121
	v_mov_b32_e32 v181, v122
	v_pk_add_f32 v[180:181], v[180:181], v[182:183]
	v_mov_b32_e32 v184, v101
	v_mov_b32_e32 v185, v102
	s_waitcnt vmcnt(3)
	v_lshlrev_b32_e32 v186, 16, v172
	v_and_b32_e32 v187, 0xffff0000, v172
	v_lshlrev_b32_e32 v172, 16, v173
	v_and_b32_e32 v173, 0xffff0000, v173
	s_waitcnt vmcnt(2)
	v_lshlrev_b32_e32 v188, 16, v174
	v_and_b32_e32 v189, 0xffff0000, v174
	v_lshlrev_b32_e32 v174, 16, v175
	v_and_b32_e32 v175, 0xffff0000, v175
	s_waitcnt vmcnt(1)
	v_lshlrev_b32_e32 v190, 16, v176
	v_and_b32_e32 v191, 0xffff0000, v176
	v_lshlrev_b32_e32 v176, 16, v177
	v_and_b32_e32 v177, 0xffff0000, v177
	s_waitcnt vmcnt(0)
	v_lshlrev_b32_e32 v194, 16, v178
	v_and_b32_e32 v195, 0xffff0000, v178
	v_lshlrev_b32_e32 v178, 16, v179
	v_and_b32_e32 v179, 0xffff0000, v179
	v_pk_mul_f32 v[186:187], v[186:187], s[8:9] op_sel_hi:[1,0]
	v_pk_mul_f32 v[172:173], v[172:173], s[8:9] op_sel_hi:[1,0]
	v_pk_mul_f32 v[188:189], v[188:189], s[8:9] op_sel_hi:[1,0]
	v_pk_mul_f32 v[174:175], v[174:175], s[8:9] op_sel_hi:[1,0]
	v_pk_mul_f32 v[190:191], v[190:191], s[8:9] op_sel_hi:[1,0]
	v_pk_mul_f32 v[176:177], v[176:177], s[8:9] op_sel_hi:[1,0]
	v_pk_mul_f32 v[194:195], v[194:195], s[8:9] op_sel_hi:[1,0]
	v_pk_mul_f32 v[178:179], v[178:179], s[8:9] op_sel_hi:[1,0]
	v_pk_fma_f32 v[30:31], v[146:147], v[30:31], v[172:173]
	v_pk_fma_f32 v[28:29], v[144:145], v[28:29], v[186:187]
	v_pk_fma_f32 v[26:27], v[154:155], v[26:27], v[174:175]
	v_pk_fma_f32 v[24:25], v[152:153], v[24:25], v[188:189]
	v_pk_fma_f32 v[22:23], v[150:151], v[22:23], v[176:177]
	v_pk_fma_f32 v[20:21], v[148:149], v[20:21], v[190:191]
	v_pk_fma_f32 v[18:19], v[158:159], v[18:19], v[178:179]
	v_pk_fma_f32 v[16:17], v[156:157], v[16:17], v[194:195]
	v_mov_b32_e32 v174, v100
	global_load_dwordx2 v[172:173], v[166:167], off nt
	global_load_dwordx2 v[176:177], v[166:167], off offset:32 nt
	global_load_dwordx2 v[188:189], v[166:167], off offset:256 nt
	global_load_dwordx2 v[182:183], v[166:167], off offset:288 nt
	v_mov_b32_e32 v175, v103
	v_add_f32_e32 v179, v72, v73
	v_add_f32_e32 v187, v74, v75
	v_mov_b32_e32 v178, v48
	v_mov_b32_e32 v186, v49
	v_pk_add_f32 v[166:167], v[184:185], v[174:175]
	v_pk_add_f32 v[174:175], v[178:179], v[186:187]
	v_add_f32_e32 v178, v180, v181
	v_pk_add_f32 v[166:167], v[166:167], v[166:167] op_sel_hi:[0,1]
	v_mov_b32_e32 v190, v51
	v_add_f32_e32 v191, 0, v178
	v_mov_b32_e32 v166, v50
	v_pk_add_f32 v[166:167], v[166:167], v[190:191]
	s_waitcnt vmcnt(3)
	v_lshlrev_b32_e32 v132, 16, v172
	v_pk_add_f32 v[166:167], v[174:175], v[166:167]
	v_and_b32_e32 v133, 0xffff0000, v172
	v_add_f32_e32 v167, v166, v167
	ds_bpermute_b32 v174, v170, v167
	v_xor_b32_e32 v166, 32, v171
	v_cmp_lt_i32_e32 vcc, v166, v196
	v_lshlrev_b32_e32 v134, 16, v173
	v_and_b32_e32 v135, 0xffff0000, v173
	v_cndmask_b32_e32 v166, v171, v166, vcc
	v_lshlrev_b32_e32 v166, 2, v166
	s_waitcnt lgkmcnt(0)
	v_add_f32_e32 v167, v167, v174
	ds_bpermute_b32 v171, v166, v167
	s_waitcnt vmcnt(1)
	v_lshlrev_b32_e32 v140, 16, v188
	v_and_b32_e32 v141, 0xffff0000, v188
	v_lshlrev_b32_e32 v142, 16, v189
	v_and_b32_e32 v143, 0xffff0000, v189
	s_waitcnt lgkmcnt(0)
	v_add_f32_e32 v128, v167, v171
	v_fmamk_f32 v130, v128, 0xbc800000, v123
	v_fmamk_f32 v136, v128, 0xbc800000, v121
	v_fmamk_f32 v138, v128, 0xbc800000, v103
	v_fmamk_f32 v167, v128, 0xbc800000, v101
	v_fmamk_f32 v129, v128, 0xbc800000, v122
	v_fmamk_f32 v131, v128, 0xbc800000, v120
	v_fmamk_f32 v137, v128, 0xbc800000, v102
	v_fmamk_f32 v139, v128, 0xbc800000, v100
	v_fmamk_f32 v174, v128, 0xbc800000, v75
	v_fmamk_f32 v178, v128, 0xbc800000, v73
	v_mul_f32_e32 v136, v136, v136
	v_mul_f32_e32 v130, v130, v130
	v_mul_f32_e32 v167, v167, v167
	v_mul_f32_e32 v138, v138, v138
	v_fmamk_f32 v171, v128, 0xbc800000, v74
	v_fmamk_f32 v175, v128, 0xbc800000, v72
	v_fmamk_f32 v180, v128, 0xbc800000, v51
	v_fmamk_f32 v184, v128, 0xbc800000, v49
	v_mul_f32_e32 v178, v178, v178
	v_mul_f32_e32 v174, v174, v174
	v_fmac_f32_e32 v136, v131, v131
	v_fmac_f32_e32 v130, v129, v129
	v_fmac_f32_e32 v167, v139, v139
	v_fmac_f32_e32 v138, v137, v137
	v_fmamk_f32 v179, v128, 0xbc800000, v50
	v_fmamk_f32 v181, v128, 0xbc800000, v48
	v_mul_f32_e32 v184, v184, v184
	v_mul_f32_e32 v180, v180, v180
	v_fmac_f32_e32 v178, v175, v175
	v_fmac_f32_e32 v174, v171, v171
	v_add_f32_e32 v129, v136, v130
	v_add_f32_e32 v130, v167, v138
	v_fmac_f32_e32 v184, v181, v181
	v_fmac_f32_e32 v180, v179, v179
	v_add_f32_e32 v131, v178, v174
	v_add_f32_e32 v129, v129, v130
	v_add_f32_e32 v136, v184, v180
	v_add_f32_e32 v129, v131, v129
	v_add_f32_e32 v129, v136, v129
	ds_bpermute_b32 v130, v170, v129
	v_lshlrev_b32_e32 v136, 16, v176
	v_and_b32_e32 v137, 0xffff0000, v176
	v_lshlrev_b32_e32 v138, 16, v177
	v_and_b32_e32 v139, 0xffff0000, v177
	s_waitcnt lgkmcnt(0)
	v_add_f32_e32 v129, v129, v130
	s_waitcnt vmcnt(0)
	v_lshlrev_b32_e32 v172, 16, v182
	v_and_b32_e32 v173, 0xffff0000, v182
	v_lshlrev_b32_e32 v174, 16, v183
	v_and_b32_e32 v175, 0xffff0000, v183
	ds_bpermute_b32 v131, v166, v129
	v_pk_mul_f32 v[132:133], v[132:133], s[8:9] op_sel_hi:[1,0]
	v_pk_mul_f32 v[134:135], v[134:135], s[8:9] op_sel_hi:[1,0]
	v_pk_mul_f32 v[136:137], v[136:137], s[8:9] op_sel_hi:[1,0]
	v_pk_mul_f32 v[138:139], v[138:139], s[8:9] op_sel_hi:[1,0]
	v_pk_mul_f32 v[140:141], v[140:141], s[8:9] op_sel_hi:[1,0]
	v_pk_mul_f32 v[142:143], v[142:143], s[8:9] op_sel_hi:[1,0]
	v_pk_mul_f32 v[172:173], v[172:173], s[8:9] op_sel_hi:[1,0]
	v_pk_mul_f32 v[174:175], v[174:175], s[8:9] op_sel_hi:[1,0]
	v_pk_fma_f32 v[14:15], v[146:147], v[14:15], v[134:135]
	v_pk_fma_f32 v[12:13], v[144:145], v[12:13], v[132:133]
	v_pk_fma_f32 v[10:11], v[154:155], v[10:11], v[138:139]
	v_pk_fma_f32 v[8:9], v[152:153], v[8:9], v[136:137]
	v_pk_fma_f32 v[6:7], v[150:151], v[6:7], v[142:143]
	v_pk_fma_f32 v[4:5], v[148:149], v[4:5], v[140:141]
	v_pk_fma_f32 v[2:3], v[158:159], v[2:3], v[174:175]
	v_pk_fma_f32 v[0:1], v[156:157], v[0:1], v[172:173]
	v_and_b32_e32 v130, 63, v169
	s_lshl_b32 s8, s11, 3
	v_cmp_gt_u32_e32 vcc, 16, v130
	s_add_i32 s11, s8, 0
	s_and_saveexec_b64 s[8:9], vcc
	s_cbranch_execz .LBB0_1309
	s_lshl_b32 s13, s10, 11
	s_add_i32 s13, s11, s13
	v_mul_f32_e32 v128, 0x3c800000, v128
	s_waitcnt lgkmcnt(0)
	v_add_f32_e32 v129, v129, v131
	v_lshl_add_u32 v131, v168, 5, s13
	ds_write_b64 v131, v[128:129]
